# hoisted per-row ssq/residual loads out of serial load-wait chains in GEMM epilogues (P_H, P_D, P_G, P_E, P_F1, P_F2)
# speedup vs baseline: 1.0249x; 1.0249x over previous
; DI unsigned pk2(float lo, float hi) { f32x2 v = {lo, hi}; bf16x2_t b = __builtin_convertvector(v, bf16x2_t); return __builtin_bit_cast(unsigned, b); }
; DI void acc_add(acc_t* p, float v, float scale) { atomicAdd(p, (acc_t)(v * scale)); }
;     DI void operator()(const f32x4 (&acc)[2][2][4][2], const Unit& u, int wr, int wc, int fr, int fq) const {
;         const int colb = u.pn * BM + wc * 32 + 8 * fq;
;         EPI_ROWS_BEGIN
;             float ss = 0.f;
; #pragma unroll
;             for (int bj = 0; bj < 2; ++bj) { const int col = colb + bj * HALF; bf16_t* xp = XB + (size_t)row * DM + col;
;                 float xv[8]; unpack8(*(const u32x4*)xp, xv);
;                 const f32x4 x0 = (f32x4){xv[0], xv[1], xv[2], xv[3]} + acc[ai][bj][m][0], x1 = (f32x4){xv[4], xv[5], xv[6], xv[7]} + acc[ai][bj][m][1];
;                 if (Y != nullptr) { float* yp = Y + (size_t)row * DM + col; *(f32x4*)yp = x0; *(f32x4*)(yp + 4) = x1; }
;                 u32x4 w; w.x = pk2(x0[0], x0[1]); w.y = pk2(x0[2], x0[3]); w.z = pk2(x1[0], x1[1]); w.w = pk2(x1[2], x1[3]); *(u32x4*)xp = w;
;                 ss += (x0[0] * x0[0] + x0[1] * x0[1]) + (x0[2] * x0[2] + x0[3] * x0[3]) + (x1[0] * x1[0] + x1[1] * x1[1]) + (x1[2] * x1[2] + x1[3] * x1[3]); }
;             ss += __shfl_xor(ss, 16); ss += __shfl_xor(ss, 32);
;             if (ssq_next != nullptr && fq == 0) acc_add(ssq_next + row, ss, SSQ_SCALE);
;         EPI_ROWS_END
.LBB0_2336:
	v_lshl_add_u32 v142, s14, 8, v144
	v_ashrrev_i32_e32 v143, 31, v142
	v_lshl_or_b32 v140, s0, 8, v146
	v_lshlrev_b64 v[148:149], 11, v[142:143]
	v_lshl_add_u64 v[148:149], s[4:5], 0, v[148:149]
	v_ashrrev_i32_e32 v141, 31, v140
	v_lshl_add_u64 v[152:153], v[140:141], 1, v[148:149]
	v_mov_b32_e32 v218, 0x8000
	v_mov_b32_e32 v219, 0
	global_load_dwordx4 v[174:177], v[152:153], off
	global_load_dwordx4 v[178:181], v[152:153], off offset:256
	v_lshl_add_u64 v[220:221], v[218:219], 0, v[152:153]
	global_load_dwordx4 v[182:185], v[220:221], off
	global_load_dwordx4 v[186:189], v[220:221], off offset:256
	v_lshl_add_u64 v[220:221], v[218:219], 1, v[152:153]
	global_load_dwordx4 v[190:193], v[220:221], off
	global_load_dwordx4 v[194:197], v[220:221], off offset:256
	v_lshl_add_u64 v[220:221], v[218:219], 0, v[220:221]
	global_load_dwordx4 v[198:201], v[220:221], off
	global_load_dwordx4 v[202:205], v[220:221], off offset:256
	v_lshl_add_u64 v[210:211], v[218:219], 3, v[152:153]
	v_lshl_add_u64 v[212:213], v[218:219], 0, v[210:211]
	v_lshl_add_u64 v[214:215], v[218:219], 1, v[210:211]
	v_lshl_add_u64 v[216:217], v[218:219], 0, v[214:215]
	s_waitcnt vmcnt(7)
	v_mov_b64_e32 v[148:149], v[174:175]
	v_mov_b64_e32 v[150:151], v[176:177]
	global_load_dwordx4 v[174:177], v[210:211], off
	v_lshlrev_b32_e32 v162, 16, v148
	v_and_b32_e32 v163, 0xffff0000, v148
	v_lshlrev_b32_e32 v148, 16, v149
	v_and_b32_e32 v149, 0xffff0000, v149
	v_lshlrev_b32_e32 v164, 16, v150
	v_and_b32_e32 v165, 0xffff0000, v150
	v_lshlrev_b32_e32 v150, 16, v151
	v_and_b32_e32 v151, 0xffff0000, v151
	v_pk_add_f32 v[128:129], v[128:129], v[148:149]
	v_pk_add_f32 v[126:127], v[126:127], v[162:163]
	v_pk_add_f32 v[148:149], v[124:125], v[150:151]
	v_pk_add_f32 v[150:151], v[122:123], v[164:165]
	v_cvt_pk_bf16_f32 v122, v126, v127
	v_cvt_pk_bf16_f32 v123, v128, v129
	v_cvt_pk_bf16_f32 v124, v150, v151
	v_cvt_pk_bf16_f32 v125, v148, v149
	global_store_dwordx4 v[152:153], v[122:125], off
	s_nop 1
	v_mul_f32_e32 v122, v127, v127
	v_mul_f32_e32 v123, v129, v129
	v_fmac_f32_e32 v122, v126, v126
	v_fmac_f32_e32 v123, v128, v128
	v_add_f32_e32 v122, v122, v123
	v_mul_f32_e32 v123, v151, v151
	v_fmac_f32_e32 v123, v150, v150
	v_add_f32_e32 v122, v123, v122
	v_mul_f32_e32 v123, v149, v149
	v_fmac_f32_e32 v123, v148, v148
	v_add_f32_e32 v148, v123, v122
	s_waitcnt vmcnt(8)
	v_mov_b64_e32 v[122:123], v[178:179]
	v_mov_b64_e32 v[124:125], v[180:181]
	global_load_dwordx4 v[178:181], v[210:211], off offset:256
	v_lshlrev_b32_e32 v126, 16, v122
	v_and_b32_e32 v127, 0xffff0000, v122
	v_lshlrev_b32_e32 v122, 16, v123
	v_and_b32_e32 v123, 0xffff0000, v123
	v_lshlrev_b32_e32 v128, 16, v124
	v_and_b32_e32 v129, 0xffff0000, v124
	v_lshlrev_b32_e32 v124, 16, v125
	v_and_b32_e32 v125, 0xffff0000, v125
	v_pk_add_f32 v[120:121], v[120:121], v[122:123]
	v_pk_add_f32 v[118:119], v[118:119], v[126:127]
	v_pk_add_f32 v[122:123], v[116:117], v[124:125]
	v_pk_add_f32 v[124:125], v[114:115], v[128:129]
	v_cvt_pk_bf16_f32 v114, v118, v119
	v_cvt_pk_bf16_f32 v115, v120, v121
	v_cvt_pk_bf16_f32 v116, v124, v125
	v_cvt_pk_bf16_f32 v117, v122, v123
	global_store_dwordx4 v[152:153], v[114:117], off offset:256
	s_nop 1
	v_mul_f32_e32 v114, v119, v119
	v_mul_f32_e32 v115, v121, v121
	v_fmac_f32_e32 v114, v118, v118
	v_fmac_f32_e32 v115, v120, v120
	v_add_f32_e32 v114, v114, v115
	v_mul_f32_e32 v115, v125, v125
	v_fmac_f32_e32 v115, v124, v124
	v_add_f32_e32 v114, v115, v114
	v_mul_f32_e32 v115, v123, v123
	v_fmac_f32_e32 v115, v122, v122
	v_add_f32_e32 v114, v115, v114
	v_add_f32_e32 v114, v148, v114
	ds_bpermute_b32 v115, v207, v114
	s_waitcnt lgkmcnt(0)
	v_add_f32_e32 v116, v114, v115
	ds_bpermute_b32 v117, v208, v116
	v_lshl_add_u64 v[114:115], v[142:143], 3, s[8:9]
	s_and_saveexec_b64 s[0:1], s[38:39]
	s_cbranch_execz .LBB0_2338
	s_waitcnt lgkmcnt(0)
	v_add_f32_e32 v116, v116, v117
	v_mul_f32_e32 v116, 0x49800000, v116
	v_trunc_f32_e32 v116, v116
	v_mul_f32_e32 v117, 0x2f800000, v116
	v_floor_f32_e32 v117, v117
	v_fmac_f32_e32 v116, 0xcf800000, v117
	v_cvt_u32_f32_e32 v116, v116
	v_cvt_u32_f32_e32 v117, v117
	global_atomic_add_x2 v[114:115], v[116:117], off
.LBB0_2338:
	s_or_b64 exec, exec, s[0:1]
	v_or_b32_e32 v116, 16, v142
	s_waitcnt lgkmcnt(0)
	v_ashrrev_i32_e32 v117, 31, v116
	v_lshlrev_b64 v[116:117], 11, v[116:117]
	v_lshl_add_u64 v[116:117], s[4:5], 0, v[116:117]
	v_lshl_add_u64 v[120:121], v[140:141], 1, v[116:117]
	s_waitcnt vmcnt(9)
	v_mov_b64_e32 v[116:117], v[182:183]
	v_mov_b64_e32 v[118:119], v[184:185]
	global_load_dwordx4 v[182:185], v[212:213], off
	v_lshlrev_b32_e32 v122, 16, v116
	v_and_b32_e32 v123, 0xffff0000, v116
	v_lshlrev_b32_e32 v116, 16, v117
	v_and_b32_e32 v117, 0xffff0000, v117
	v_lshlrev_b32_e32 v124, 16, v118
	v_and_b32_e32 v125, 0xffff0000, v118
	v_lshlrev_b32_e32 v118, 16, v119
	v_and_b32_e32 v119, 0xffff0000, v119
	v_pk_add_f32 v[112:113], v[112:113], v[116:117]
	v_pk_add_f32 v[110:111], v[110:111], v[122:123]
	v_pk_add_f32 v[116:117], v[108:109], v[118:119]
	v_pk_add_f32 v[118:119], v[106:107], v[124:125]
	v_cvt_pk_bf16_f32 v106, v110, v111
	v_cvt_pk_bf16_f32 v107, v112, v113
	v_cvt_pk_bf16_f32 v108, v118, v119
	v_cvt_pk_bf16_f32 v109, v116, v117
	global_store_dwordx4 v[120:121], v[106:109], off
	s_nop 1
	v_mul_f32_e32 v106, v111, v111
	v_mul_f32_e32 v107, v113, v113
	v_fmac_f32_e32 v106, v110, v110
	v_fmac_f32_e32 v107, v112, v112
	v_add_f32_e32 v106, v106, v107
	v_mul_f32_e32 v107, v119, v119
	v_fmac_f32_e32 v107, v118, v118
	v_add_f32_e32 v106, v107, v106
	v_mul_f32_e32 v107, v117, v117
	v_fmac_f32_e32 v107, v116, v116
	v_add_f32_e32 v116, v107, v106
	s_waitcnt vmcnt(10)
	v_mov_b64_e32 v[106:107], v[186:187]
	v_mov_b64_e32 v[108:109], v[188:189]
	global_load_dwordx4 v[186:189], v[212:213], off offset:256
	v_lshlrev_b32_e32 v110, 16, v106
	v_and_b32_e32 v111, 0xffff0000, v106
	v_lshlrev_b32_e32 v106, 16, v107
	v_and_b32_e32 v107, 0xffff0000, v107
	v_lshlrev_b32_e32 v112, 16, v108
	v_and_b32_e32 v113, 0xffff0000, v108
	v_lshlrev_b32_e32 v108, 16, v109
	v_and_b32_e32 v109, 0xffff0000, v109
	v_pk_add_f32 v[104:105], v[104:105], v[106:107]
	v_pk_add_f32 v[102:103], v[102:103], v[110:111]
	v_pk_add_f32 v[106:107], v[100:101], v[108:109]
	v_pk_add_f32 v[108:109], v[98:99], v[112:113]
	v_cvt_pk_bf16_f32 v98, v102, v103
	v_cvt_pk_bf16_f32 v99, v104, v105
	v_cvt_pk_bf16_f32 v100, v108, v109
	v_cvt_pk_bf16_f32 v101, v106, v107
	global_store_dwordx4 v[120:121], v[98:101], off offset:256
	s_nop 1
	v_mul_f32_e32 v98, v103, v103
	v_mul_f32_e32 v99, v105, v105
	v_fmac_f32_e32 v98, v102, v102
	v_fmac_f32_e32 v99, v104, v104
	v_add_f32_e32 v98, v98, v99
	v_mul_f32_e32 v99, v109, v109
	v_fmac_f32_e32 v99, v108, v108
	v_add_f32_e32 v98, v99, v98
	v_mul_f32_e32 v99, v107, v107
	v_fmac_f32_e32 v99, v106, v106
	v_add_f32_e32 v98, v99, v98
	v_add_f32_e32 v98, v116, v98
	ds_bpermute_b32 v99, v207, v98
	s_waitcnt lgkmcnt(0)
	v_add_f32_e32 v98, v98, v99
	ds_bpermute_b32 v99, v208, v98
	s_and_saveexec_b64 s[0:1], s[38:39]
	s_cbranch_execz .LBB0_2340
; DI unsigned pk2(float lo, float hi) { f32x2 v = {lo, hi}; bf16x2_t b = __builtin_convertvector(v, bf16x2_t); return __builtin_bit_cast(unsigned, b); }
; DI void acc_add(acc_t* p, float v, float scale) { atomicAdd(p, (acc_t)(v * scale)); }
;     DI void operator()(const f32x4 (&acc)[2][2][4][2], const Unit& u, int wr, int wc, int fr, int fq) const {
;         const int colb = u.pn * BM + wc * 32 + 8 * fq;
;         EPI_ROWS_BEGIN
;             float ss = 0.f;
; #pragma unroll
;             for (int bj = 0; bj < 2; ++bj) { const int col = colb + bj * HALF; bf16_t* xp = XB + (size_t)row * DM + col;
;                 float xv[8]; unpack8(*(const u32x4*)xp, xv);
;                 const f32x4 x0 = (f32x4){xv[0], xv[1], xv[2], xv[3]} + acc[ai][bj][m][0], x1 = (f32x4){xv[4], xv[5], xv[6], xv[7]} + acc[ai][bj][m][1];
;                 if (Y != nullptr) { float* yp = Y + (size_t)row * DM + col; *(f32x4*)yp = x0; *(f32x4*)(yp + 4) = x1; }
;                 u32x4 w; w.x = pk2(x0[0], x0[1]); w.y = pk2(x0[2], x0[3]); w.z = pk2(x1[0], x1[1]); w.w = pk2(x1[2], x1[3]); *(u32x4*)xp = w;
;                 ss += (x0[0] * x0[0] + x0[1] * x0[1]) + (x0[2] * x0[2] + x0[3] * x0[3]) + (x1[0] * x1[0] + x1[1] * x1[1]) + (x1[2] * x1[2] + x1[3] * x1[3]); }
;             ss += __shfl_xor(ss, 16); ss += __shfl_xor(ss, 32);
;             if (ssq_next != nullptr && fq == 0) acc_add(ssq_next + row, ss, SSQ_SCALE);
;         EPI_ROWS_END
	s_waitcnt lgkmcnt(0)
	v_add_f32_e32 v98, v98, v99
	v_mul_f32_e32 v98, 0x49800000, v98
	v_trunc_f32_e32 v98, v98
	v_mul_f32_e32 v99, 0x2f800000, v98
	v_floor_f32_e32 v99, v99
	v_fmac_f32_e32 v98, 0xcf800000, v99
	v_cvt_u32_f32_e32 v98, v98
	v_cvt_u32_f32_e32 v99, v99
	global_atomic_add_x2 v[114:115], v[98:99], off offset:128
.LBB0_2340:
	s_or_b64 exec, exec, s[0:1]
	v_or_b32_e32 v98, 32, v142
	s_waitcnt lgkmcnt(0)
	v_ashrrev_i32_e32 v99, 31, v98
	v_lshlrev_b64 v[98:99], 11, v[98:99]
	v_lshl_add_u64 v[98:99], s[4:5], 0, v[98:99]
	v_lshl_add_u64 v[102:103], v[140:141], 1, v[98:99]
	s_waitcnt vmcnt(11)
	v_mov_b64_e32 v[98:99], v[190:191]
	v_mov_b64_e32 v[100:101], v[192:193]
	global_load_dwordx4 v[190:193], v[214:215], off
	v_lshlrev_b32_e32 v104, 16, v98
	v_and_b32_e32 v105, 0xffff0000, v98
	v_lshlrev_b32_e32 v98, 16, v99
	v_and_b32_e32 v99, 0xffff0000, v99
	v_lshlrev_b32_e32 v106, 16, v100
	v_and_b32_e32 v107, 0xffff0000, v100
	v_lshlrev_b32_e32 v100, 16, v101
	v_and_b32_e32 v101, 0xffff0000, v101
	v_pk_add_f32 v[94:95], v[94:95], v[98:99]
	v_pk_add_f32 v[92:93], v[92:93], v[104:105]
	v_pk_add_f32 v[98:99], v[90:91], v[100:101]
	v_pk_add_f32 v[100:101], v[88:89], v[106:107]
	v_cvt_pk_bf16_f32 v88, v92, v93
	v_cvt_pk_bf16_f32 v89, v94, v95
	v_cvt_pk_bf16_f32 v90, v100, v101
	v_cvt_pk_bf16_f32 v91, v98, v99
	global_store_dwordx4 v[102:103], v[88:91], off
	s_nop 1
	v_mul_f32_e32 v88, v93, v93
	v_mul_f32_e32 v89, v95, v95
	v_fmac_f32_e32 v88, v92, v92
	v_fmac_f32_e32 v89, v94, v94
	v_add_f32_e32 v88, v88, v89
	v_mul_f32_e32 v89, v101, v101
	v_fmac_f32_e32 v89, v100, v100
	v_add_f32_e32 v88, v89, v88
	v_mul_f32_e32 v89, v99, v99
	v_fmac_f32_e32 v89, v98, v98
	v_add_f32_e32 v98, v89, v88
	s_waitcnt vmcnt(12)
	v_mov_b64_e32 v[88:89], v[194:195]
	v_mov_b64_e32 v[90:91], v[196:197]
	global_load_dwordx4 v[194:197], v[214:215], off offset:256
	v_lshlrev_b32_e32 v92, 16, v88
	v_and_b32_e32 v93, 0xffff0000, v88
	v_lshlrev_b32_e32 v88, 16, v89
	v_and_b32_e32 v89, 0xffff0000, v89
	v_lshlrev_b32_e32 v94, 16, v90
	v_and_b32_e32 v95, 0xffff0000, v90
	v_lshlrev_b32_e32 v90, 16, v91
	v_and_b32_e32 v91, 0xffff0000, v91
	v_pk_add_f32 v[86:87], v[86:87], v[88:89]
	v_pk_add_f32 v[84:85], v[84:85], v[92:93]
	v_pk_add_f32 v[88:89], v[82:83], v[90:91]
	v_pk_add_f32 v[90:91], v[80:81], v[94:95]
	v_cvt_pk_bf16_f32 v80, v84, v85
	v_cvt_pk_bf16_f32 v81, v86, v87
	v_cvt_pk_bf16_f32 v82, v90, v91
	v_cvt_pk_bf16_f32 v83, v88, v89
	global_store_dwordx4 v[102:103], v[80:83], off offset:256
	s_nop 1
	v_mul_f32_e32 v80, v85, v85
	v_mul_f32_e32 v81, v87, v87
	v_fmac_f32_e32 v80, v84, v84
	v_fmac_f32_e32 v81, v86, v86
	v_add_f32_e32 v80, v80, v81
	v_mul_f32_e32 v81, v91, v91
	v_fmac_f32_e32 v81, v90, v90
	v_add_f32_e32 v80, v81, v80
	v_mul_f32_e32 v81, v89, v89
	v_fmac_f32_e32 v81, v88, v88
	v_add_f32_e32 v80, v81, v80
	v_add_f32_e32 v80, v98, v80
	ds_bpermute_b32 v81, v207, v80
	s_waitcnt lgkmcnt(0)
	v_add_f32_e32 v80, v80, v81
	ds_bpermute_b32 v81, v208, v80
	s_and_saveexec_b64 s[0:1], s[38:39]
	s_cbranch_execz .LBB0_2342
	s_waitcnt lgkmcnt(0)
	v_add_f32_e32 v80, v80, v81
	v_mul_f32_e32 v80, 0x49800000, v80
	v_trunc_f32_e32 v80, v80
	v_mul_f32_e32 v81, 0x2f800000, v80
	v_floor_f32_e32 v81, v81
	v_fmac_f32_e32 v80, 0xcf800000, v81
	v_cvt_u32_f32_e32 v80, v80
	v_cvt_u32_f32_e32 v81, v81
	global_atomic_add_x2 v[114:115], v[80:81], off offset:256
.LBB0_2342:
	s_or_b64 exec, exec, s[0:1]
	v_or_b32_e32 v80, 48, v142
	s_waitcnt lgkmcnt(0)
	v_ashrrev_i32_e32 v81, 31, v80
	v_lshlrev_b64 v[80:81], 11, v[80:81]
	v_lshl_add_u64 v[80:81], s[4:5], 0, v[80:81]
	v_lshl_add_u64 v[84:85], v[140:141], 1, v[80:81]
	s_waitcnt vmcnt(13)
	v_mov_b64_e32 v[80:81], v[198:199]
	v_mov_b64_e32 v[82:83], v[200:201]
	global_load_dwordx4 v[198:201], v[216:217], off
	v_lshlrev_b32_e32 v86, 16, v80
	v_and_b32_e32 v87, 0xffff0000, v80
	v_lshlrev_b32_e32 v80, 16, v81
	v_and_b32_e32 v81, 0xffff0000, v81
	v_lshlrev_b32_e32 v88, 16, v82
	v_and_b32_e32 v89, 0xffff0000, v82
	v_lshlrev_b32_e32 v82, 16, v83
	v_and_b32_e32 v83, 0xffff0000, v83
	v_pk_add_f32 v[78:79], v[78:79], v[80:81]
	v_pk_add_f32 v[76:77], v[76:77], v[86:87]
	v_pk_add_f32 v[80:81], v[74:75], v[82:83]
	v_pk_add_f32 v[82:83], v[72:73], v[88:89]
	v_cvt_pk_bf16_f32 v72, v76, v77
	v_cvt_pk_bf16_f32 v73, v78, v79
	v_cvt_pk_bf16_f32 v74, v82, v83
	v_cvt_pk_bf16_f32 v75, v80, v81
	global_store_dwordx4 v[84:85], v[72:75], off
	s_nop 1
	v_mul_f32_e32 v72, v77, v77
	v_mul_f32_e32 v73, v79, v79
	v_fmac_f32_e32 v72, v76, v76
	v_fmac_f32_e32 v73, v78, v78
	v_add_f32_e32 v72, v72, v73
	v_mul_f32_e32 v73, v83, v83
	v_fmac_f32_e32 v73, v82, v82
	v_add_f32_e32 v72, v73, v72
	v_mul_f32_e32 v73, v81, v81
	v_fmac_f32_e32 v73, v80, v80
	v_add_f32_e32 v80, v73, v72
	s_waitcnt vmcnt(14)
	v_mov_b64_e32 v[72:73], v[202:203]
	v_mov_b64_e32 v[74:75], v[204:205]
	global_load_dwordx4 v[202:205], v[216:217], off offset:256
	v_lshlrev_b32_e32 v76, 16, v72
	v_and_b32_e32 v77, 0xffff0000, v72
	v_lshlrev_b32_e32 v72, 16, v73
	v_and_b32_e32 v73, 0xffff0000, v73
	v_lshlrev_b32_e32 v78, 16, v74
	v_and_b32_e32 v79, 0xffff0000, v74
	v_lshlrev_b32_e32 v74, 16, v75
	v_and_b32_e32 v75, 0xffff0000, v75
	v_pk_add_f32 v[70:71], v[70:71], v[72:73]
	v_pk_add_f32 v[68:69], v[68:69], v[76:77]
	v_pk_add_f32 v[72:73], v[66:67], v[74:75]
	v_pk_add_f32 v[74:75], v[64:65], v[78:79]
	v_cvt_pk_bf16_f32 v64, v68, v69
	v_cvt_pk_bf16_f32 v65, v70, v71
	v_cvt_pk_bf16_f32 v66, v74, v75
	v_cvt_pk_bf16_f32 v67, v72, v73
	global_store_dwordx4 v[84:85], v[64:67], off offset:256
	s_nop 1
	v_mul_f32_e32 v64, v69, v69
	v_mul_f32_e32 v65, v71, v71
	v_fmac_f32_e32 v64, v68, v68
	v_fmac_f32_e32 v65, v70, v70
	v_add_f32_e32 v64, v64, v65
	v_mul_f32_e32 v65, v75, v75
	v_fmac_f32_e32 v65, v74, v74
	v_add_f32_e32 v64, v65, v64
	v_mul_f32_e32 v65, v73, v73
	v_fmac_f32_e32 v65, v72, v72
	v_add_f32_e32 v64, v65, v64
	v_add_f32_e32 v64, v80, v64
	ds_bpermute_b32 v65, v207, v64
	s_waitcnt lgkmcnt(0)
	v_add_f32_e32 v64, v64, v65
	ds_bpermute_b32 v65, v208, v64
	s_and_saveexec_b64 s[0:1], s[38:39]
	s_cbranch_execz .LBB0_2344
	s_waitcnt lgkmcnt(0)
	v_add_f32_e32 v64, v64, v65
	v_mul_f32_e32 v64, 0x49800000, v64
	v_trunc_f32_e32 v64, v64
	v_mul_f32_e32 v65, 0x2f800000, v64
	v_floor_f32_e32 v65, v65
	v_fmac_f32_e32 v64, 0xcf800000, v65
	v_cvt_u32_f32_e32 v64, v64
	v_cvt_u32_f32_e32 v65, v65
	global_atomic_add_x2 v[114:115], v[64:65], off offset:384
; DI unsigned pk2(float lo, float hi) { f32x2 v = {lo, hi}; bf16x2_t b = __builtin_convertvector(v, bf16x2_t); return __builtin_bit_cast(unsigned, b); }
; DI void acc_add(acc_t* p, float v, float scale) { atomicAdd(p, (acc_t)(v * scale)); }
;     DI void operator()(const f32x4 (&acc)[2][2][4][2], const Unit& u, int wr, int wc, int fr, int fq) const {
;         const int colb = u.pn * BM + wc * 32 + 8 * fq;
;         EPI_ROWS_BEGIN
;             float ss = 0.f;
; #pragma unroll
;             for (int bj = 0; bj < 2; ++bj) { const int col = colb + bj * HALF; bf16_t* xp = XB + (size_t)row * DM + col;
;                 float xv[8]; unpack8(*(const u32x4*)xp, xv);
;                 const f32x4 x0 = (f32x4){xv[0], xv[1], xv[2], xv[3]} + acc[ai][bj][m][0], x1 = (f32x4){xv[4], xv[5], xv[6], xv[7]} + acc[ai][bj][m][1];
;                 if (Y != nullptr) { float* yp = Y + (size_t)row * DM + col; *(f32x4*)yp = x0; *(f32x4*)(yp + 4) = x1; }
;                 u32x4 w; w.x = pk2(x0[0], x0[1]); w.y = pk2(x0[2], x0[3]); w.z = pk2(x1[0], x1[1]); w.w = pk2(x1[2], x1[3]); *(u32x4*)xp = w;
;                 ss += (x0[0] * x0[0] + x0[1] * x0[1]) + (x0[2] * x0[2] + x0[3] * x0[3]) + (x1[0] * x1[0] + x1[1] * x1[1]) + (x1[2] * x1[2] + x1[3] * x1[3]); }
;             ss += __shfl_xor(ss, 16); ss += __shfl_xor(ss, 32);
;             if (ssq_next != nullptr && fq == 0) acc_add(ssq_next + row, ss, SSQ_SCALE);
;         EPI_ROWS_END
.LBB0_2344:
	s_or_b64 exec, exec, s[0:1]
	v_add_u32_e32 v64, 0x80, v142
	s_waitcnt lgkmcnt(0)
	v_ashrrev_i32_e32 v65, 31, v64
	v_lshlrev_b64 v[64:65], 11, v[64:65]
	v_lshl_add_u64 v[64:65], s[4:5], 0, v[64:65]
	v_lshl_add_u64 v[68:69], v[140:141], 1, v[64:65]
	s_waitcnt vmcnt(15)
	v_mov_b64_e32 v[64:65], v[174:175]
	v_mov_b64_e32 v[66:67], v[176:177]
	v_lshlrev_b32_e32 v70, 16, v64
	v_and_b32_e32 v71, 0xffff0000, v64
	v_lshlrev_b32_e32 v64, 16, v65
	v_and_b32_e32 v65, 0xffff0000, v65
	v_lshlrev_b32_e32 v72, 16, v66
	v_and_b32_e32 v73, 0xffff0000, v66
	v_lshlrev_b32_e32 v66, 16, v67
	v_and_b32_e32 v67, 0xffff0000, v67
	v_pk_add_f32 v[62:63], v[62:63], v[64:65]
	v_pk_add_f32 v[60:61], v[60:61], v[70:71]
	v_pk_add_f32 v[64:65], v[58:59], v[66:67]
	v_pk_add_f32 v[66:67], v[56:57], v[72:73]
	v_cvt_pk_bf16_f32 v56, v60, v61
	v_cvt_pk_bf16_f32 v57, v62, v63
	v_cvt_pk_bf16_f32 v58, v66, v67
	v_cvt_pk_bf16_f32 v59, v64, v65
	global_store_dwordx4 v[68:69], v[56:59], off
	s_nop 1
	v_mul_f32_e32 v56, v61, v61
	v_mul_f32_e32 v57, v63, v63
	v_fmac_f32_e32 v56, v60, v60
	v_fmac_f32_e32 v57, v62, v62
	v_add_f32_e32 v56, v56, v57
	v_mul_f32_e32 v57, v67, v67
	v_fmac_f32_e32 v57, v66, v66
	v_add_f32_e32 v56, v57, v56
	v_mul_f32_e32 v57, v65, v65
	v_fmac_f32_e32 v57, v64, v64
	v_add_f32_e32 v64, v57, v56
	s_waitcnt vmcnt(14)
	v_mov_b64_e32 v[56:57], v[178:179]
	v_mov_b64_e32 v[58:59], v[180:181]
	v_lshlrev_b32_e32 v60, 16, v56
	v_and_b32_e32 v61, 0xffff0000, v56
	v_lshlrev_b32_e32 v56, 16, v57
	v_and_b32_e32 v57, 0xffff0000, v57
	v_lshlrev_b32_e32 v62, 16, v58
	v_and_b32_e32 v63, 0xffff0000, v58
	v_lshlrev_b32_e32 v58, 16, v59
	v_and_b32_e32 v59, 0xffff0000, v59
	v_pk_add_f32 v[54:55], v[54:55], v[56:57]
	v_pk_add_f32 v[52:53], v[52:53], v[60:61]
	v_pk_add_f32 v[56:57], v[50:51], v[58:59]
	v_pk_add_f32 v[58:59], v[48:49], v[62:63]
	v_cvt_pk_bf16_f32 v48, v52, v53
	v_cvt_pk_bf16_f32 v49, v54, v55
	v_cvt_pk_bf16_f32 v50, v58, v59
	v_cvt_pk_bf16_f32 v51, v56, v57
	global_store_dwordx4 v[68:69], v[48:51], off offset:256
	s_nop 1
	v_mul_f32_e32 v48, v53, v53
	v_mul_f32_e32 v49, v55, v55
	v_fmac_f32_e32 v48, v52, v52
	v_fmac_f32_e32 v49, v54, v54
	v_add_f32_e32 v48, v48, v49
	v_mul_f32_e32 v49, v59, v59
	v_fmac_f32_e32 v49, v58, v58
	v_add_f32_e32 v48, v49, v48
	v_mul_f32_e32 v49, v57, v57
	v_fmac_f32_e32 v49, v56, v56
	v_add_f32_e32 v48, v49, v48
	v_add_f32_e32 v48, v64, v48
	ds_bpermute_b32 v49, v207, v48
	s_waitcnt lgkmcnt(0)
	v_add_f32_e32 v48, v48, v49
	ds_bpermute_b32 v49, v208, v48
	s_and_saveexec_b64 s[0:1], s[38:39]
	s_cbranch_execz .LBB0_2346
	s_waitcnt lgkmcnt(0)
	v_add_f32_e32 v48, v48, v49
	v_mul_f32_e32 v48, 0x49800000, v48
	v_trunc_f32_e32 v48, v48
	v_mul_f32_e32 v49, 0x2f800000, v48
	v_floor_f32_e32 v49, v49
	v_fmac_f32_e32 v48, 0xcf800000, v49
	v_cvt_u32_f32_e32 v48, v48
	v_cvt_u32_f32_e32 v49, v49
	global_atomic_add_x2 v[114:115], v[48:49], off offset:1024
.LBB0_2346:
	s_or_b64 exec, exec, s[0:1]
	v_add_u32_e32 v48, 0x90, v142
	s_waitcnt lgkmcnt(0)
	v_ashrrev_i32_e32 v49, 31, v48
	v_lshlrev_b64 v[48:49], 11, v[48:49]
	v_lshl_add_u64 v[48:49], s[4:5], 0, v[48:49]
	v_lshl_add_u64 v[52:53], v[140:141], 1, v[48:49]
	s_waitcnt vmcnt(13)
	v_mov_b64_e32 v[48:49], v[182:183]
	v_mov_b64_e32 v[50:51], v[184:185]
	v_lshlrev_b32_e32 v54, 16, v48
	v_and_b32_e32 v55, 0xffff0000, v48
	v_lshlrev_b32_e32 v48, 16, v49
	v_and_b32_e32 v49, 0xffff0000, v49
	v_lshlrev_b32_e32 v56, 16, v50
	v_and_b32_e32 v57, 0xffff0000, v50
	v_lshlrev_b32_e32 v50, 16, v51
	v_and_b32_e32 v51, 0xffff0000, v51
	v_pk_add_f32 v[46:47], v[46:47], v[48:49]
	v_pk_add_f32 v[44:45], v[44:45], v[54:55]
	v_pk_add_f32 v[48:49], v[42:43], v[50:51]
	v_pk_add_f32 v[50:51], v[40:41], v[56:57]
	v_cvt_pk_bf16_f32 v40, v44, v45
	v_cvt_pk_bf16_f32 v41, v46, v47
	v_cvt_pk_bf16_f32 v42, v50, v51
	v_cvt_pk_bf16_f32 v43, v48, v49
	global_store_dwordx4 v[52:53], v[40:43], off
	s_nop 1
	v_mul_f32_e32 v40, v45, v45
	v_mul_f32_e32 v41, v47, v47
	v_fmac_f32_e32 v40, v44, v44
	v_fmac_f32_e32 v41, v46, v46
	v_add_f32_e32 v40, v40, v41
	v_mul_f32_e32 v41, v51, v51
	v_fmac_f32_e32 v41, v50, v50
	v_add_f32_e32 v40, v41, v40
	v_mul_f32_e32 v41, v49, v49
	v_fmac_f32_e32 v41, v48, v48
	v_add_f32_e32 v48, v41, v40
	s_waitcnt vmcnt(12)
	v_mov_b64_e32 v[40:41], v[186:187]
	v_mov_b64_e32 v[42:43], v[188:189]
	v_lshlrev_b32_e32 v44, 16, v40
	v_and_b32_e32 v45, 0xffff0000, v40
	v_lshlrev_b32_e32 v40, 16, v41
	v_and_b32_e32 v41, 0xffff0000, v41
	v_lshlrev_b32_e32 v46, 16, v42
	v_and_b32_e32 v47, 0xffff0000, v42
	v_lshlrev_b32_e32 v42, 16, v43
	v_and_b32_e32 v43, 0xffff0000, v43
	v_pk_add_f32 v[38:39], v[38:39], v[40:41]
	v_pk_add_f32 v[36:37], v[36:37], v[44:45]
	v_pk_add_f32 v[40:41], v[34:35], v[42:43]
	v_pk_add_f32 v[42:43], v[32:33], v[46:47]
	v_cvt_pk_bf16_f32 v32, v36, v37
	v_cvt_pk_bf16_f32 v33, v38, v39
	v_cvt_pk_bf16_f32 v34, v42, v43
	v_cvt_pk_bf16_f32 v35, v40, v41
	global_store_dwordx4 v[52:53], v[32:35], off offset:256
	s_nop 1
	v_mul_f32_e32 v32, v37, v37
	v_mul_f32_e32 v33, v39, v39
	v_fmac_f32_e32 v32, v36, v36
	v_fmac_f32_e32 v33, v38, v38
	v_add_f32_e32 v32, v32, v33
	v_mul_f32_e32 v33, v43, v43
	v_fmac_f32_e32 v33, v42, v42
	v_add_f32_e32 v32, v33, v32
	v_mul_f32_e32 v33, v41, v41
	v_fmac_f32_e32 v33, v40, v40
	v_add_f32_e32 v32, v33, v32
	v_add_f32_e32 v32, v48, v32
	ds_bpermute_b32 v33, v207, v32
	s_waitcnt lgkmcnt(0)
	v_add_f32_e32 v32, v32, v33
	ds_bpermute_b32 v33, v208, v32
	s_and_saveexec_b64 s[0:1], s[38:39]
	s_cbranch_execz .LBB0_2348
	s_waitcnt lgkmcnt(0)
	v_add_f32_e32 v32, v32, v33
	v_mul_f32_e32 v32, 0x49800000, v32
	v_trunc_f32_e32 v32, v32
	v_mul_f32_e32 v33, 0x2f800000, v32
	v_floor_f32_e32 v33, v33
	v_fmac_f32_e32 v32, 0xcf800000, v33
	v_cvt_u32_f32_e32 v32, v32
	v_cvt_u32_f32_e32 v33, v33
	global_atomic_add_x2 v[114:115], v[32:33], off offset:1152
; DI unsigned pk2(float lo, float hi) { f32x2 v = {lo, hi}; bf16x2_t b = __builtin_convertvector(v, bf16x2_t); return __builtin_bit_cast(unsigned, b); }
; DI void acc_add(acc_t* p, float v, float scale) { atomicAdd(p, (acc_t)(v * scale)); }
;     DI void operator()(const f32x4 (&acc)[2][2][4][2], const Unit& u, int wr, int wc, int fr, int fq) const {
;         const int colb = u.pn * BM + wc * 32 + 8 * fq;
;         EPI_ROWS_BEGIN
;             float ss = 0.f;
; #pragma unroll
;             for (int bj = 0; bj < 2; ++bj) { const int col = colb + bj * HALF; bf16_t* xp = XB + (size_t)row * DM + col;
;                 float xv[8]; unpack8(*(const u32x4*)xp, xv);
;                 const f32x4 x0 = (f32x4){xv[0], xv[1], xv[2], xv[3]} + acc[ai][bj][m][0], x1 = (f32x4){xv[4], xv[5], xv[6], xv[7]} + acc[ai][bj][m][1];
;                 if (Y != nullptr) { float* yp = Y + (size_t)row * DM + col; *(f32x4*)yp = x0; *(f32x4*)(yp + 4) = x1; }
;                 u32x4 w; w.x = pk2(x0[0], x0[1]); w.y = pk2(x0[2], x0[3]); w.z = pk2(x1[0], x1[1]); w.w = pk2(x1[2], x1[3]); *(u32x4*)xp = w;
;                 ss += (x0[0] * x0[0] + x0[1] * x0[1]) + (x0[2] * x0[2] + x0[3] * x0[3]) + (x1[0] * x1[0] + x1[1] * x1[1]) + (x1[2] * x1[2] + x1[3] * x1[3]); }
;             ss += __shfl_xor(ss, 16); ss += __shfl_xor(ss, 32);
;             if (ssq_next != nullptr && fq == 0) acc_add(ssq_next + row, ss, SSQ_SCALE);
;         EPI_ROWS_END
.LBB0_2348:
	s_or_b64 exec, exec, s[0:1]
	v_add_u32_e32 v32, 0xa0, v142
	s_waitcnt lgkmcnt(0)
	v_ashrrev_i32_e32 v33, 31, v32
	v_lshlrev_b64 v[32:33], 11, v[32:33]
	v_lshl_add_u64 v[32:33], s[4:5], 0, v[32:33]
	v_lshl_add_u64 v[36:37], v[140:141], 1, v[32:33]
	s_waitcnt vmcnt(11)
	v_mov_b64_e32 v[32:33], v[190:191]
	v_mov_b64_e32 v[34:35], v[192:193]
	v_lshlrev_b32_e32 v38, 16, v32
	v_and_b32_e32 v39, 0xffff0000, v32
	v_lshlrev_b32_e32 v32, 16, v33
	v_and_b32_e32 v33, 0xffff0000, v33
	v_lshlrev_b32_e32 v40, 16, v34
	v_and_b32_e32 v41, 0xffff0000, v34
	v_lshlrev_b32_e32 v34, 16, v35
	v_and_b32_e32 v35, 0xffff0000, v35
	v_pk_add_f32 v[30:31], v[30:31], v[32:33]
	v_pk_add_f32 v[28:29], v[28:29], v[38:39]
	v_pk_add_f32 v[32:33], v[26:27], v[34:35]
	v_pk_add_f32 v[34:35], v[24:25], v[40:41]
	v_cvt_pk_bf16_f32 v24, v28, v29
	v_cvt_pk_bf16_f32 v25, v30, v31
	v_cvt_pk_bf16_f32 v26, v34, v35
	v_cvt_pk_bf16_f32 v27, v32, v33
	global_store_dwordx4 v[36:37], v[24:27], off
	s_nop 1
	v_mul_f32_e32 v24, v29, v29
	v_mul_f32_e32 v25, v31, v31
	v_fmac_f32_e32 v24, v28, v28
	v_fmac_f32_e32 v25, v30, v30
	v_add_f32_e32 v24, v24, v25
	v_mul_f32_e32 v25, v35, v35
	v_fmac_f32_e32 v25, v34, v34
	v_add_f32_e32 v24, v25, v24
	v_mul_f32_e32 v25, v33, v33
	v_fmac_f32_e32 v25, v32, v32
	v_add_f32_e32 v32, v25, v24
	s_waitcnt vmcnt(10)
	v_mov_b64_e32 v[24:25], v[194:195]
	v_mov_b64_e32 v[26:27], v[196:197]
	v_lshlrev_b32_e32 v28, 16, v24
	v_and_b32_e32 v29, 0xffff0000, v24
	v_lshlrev_b32_e32 v24, 16, v25
	v_and_b32_e32 v25, 0xffff0000, v25
	v_lshlrev_b32_e32 v30, 16, v26
	v_and_b32_e32 v31, 0xffff0000, v26
	v_lshlrev_b32_e32 v26, 16, v27
	v_and_b32_e32 v27, 0xffff0000, v27
	v_pk_add_f32 v[22:23], v[22:23], v[24:25]
	v_pk_add_f32 v[20:21], v[20:21], v[28:29]
	v_pk_add_f32 v[24:25], v[18:19], v[26:27]
	v_pk_add_f32 v[26:27], v[16:17], v[30:31]
	v_cvt_pk_bf16_f32 v16, v20, v21
	v_cvt_pk_bf16_f32 v17, v22, v23
	v_cvt_pk_bf16_f32 v18, v26, v27
	v_cvt_pk_bf16_f32 v19, v24, v25
	global_store_dwordx4 v[36:37], v[16:19], off offset:256
	s_nop 1
	v_mul_f32_e32 v16, v21, v21
	v_mul_f32_e32 v17, v23, v23
	v_fmac_f32_e32 v16, v20, v20
	v_fmac_f32_e32 v17, v22, v22
	v_add_f32_e32 v16, v16, v17
	v_mul_f32_e32 v17, v27, v27
	v_fmac_f32_e32 v17, v26, v26
	v_add_f32_e32 v16, v17, v16
	v_mul_f32_e32 v17, v25, v25
	v_fmac_f32_e32 v17, v24, v24
	v_add_f32_e32 v16, v17, v16
	v_add_f32_e32 v16, v32, v16
	ds_bpermute_b32 v17, v207, v16
	s_waitcnt lgkmcnt(0)
	v_add_f32_e32 v16, v16, v17
	ds_bpermute_b32 v17, v208, v16
	s_and_saveexec_b64 s[0:1], s[38:39]
	s_cbranch_execz .LBB0_2350
	s_waitcnt lgkmcnt(0)
	v_add_f32_e32 v16, v16, v17
	v_mul_f32_e32 v16, 0x49800000, v16
	v_trunc_f32_e32 v16, v16
	v_mul_f32_e32 v17, 0x2f800000, v16
	v_floor_f32_e32 v17, v17
	v_fmac_f32_e32 v16, 0xcf800000, v17
	v_cvt_u32_f32_e32 v16, v16
	v_cvt_u32_f32_e32 v17, v17
	global_atomic_add_x2 v[114:115], v[16:17], off offset:1280
.LBB0_2350:
	s_or_b64 exec, exec, s[0:1]
	v_add_u32_e32 v16, 0xb0, v142
	s_waitcnt lgkmcnt(0)
	v_ashrrev_i32_e32 v17, 31, v16
	v_lshlrev_b64 v[16:17], 11, v[16:17]
	v_lshl_add_u64 v[16:17], s[4:5], 0, v[16:17]
	v_lshl_add_u64 v[20:21], v[140:141], 1, v[16:17]
	s_waitcnt vmcnt(9)
	v_mov_b64_e32 v[16:17], v[198:199]
	v_mov_b64_e32 v[18:19], v[200:201]
	v_lshlrev_b32_e32 v22, 16, v16
	v_and_b32_e32 v23, 0xffff0000, v16
	v_lshlrev_b32_e32 v16, 16, v17
	v_and_b32_e32 v17, 0xffff0000, v17
	v_lshlrev_b32_e32 v24, 16, v18
	v_and_b32_e32 v25, 0xffff0000, v18
	v_lshlrev_b32_e32 v18, 16, v19
	v_and_b32_e32 v19, 0xffff0000, v19
	v_pk_add_f32 v[14:15], v[14:15], v[16:17]
	v_pk_add_f32 v[12:13], v[12:13], v[22:23]
	v_pk_add_f32 v[16:17], v[10:11], v[18:19]
	v_pk_add_f32 v[18:19], v[8:9], v[24:25]
	v_cvt_pk_bf16_f32 v8, v12, v13
	v_cvt_pk_bf16_f32 v9, v14, v15
	v_cvt_pk_bf16_f32 v10, v18, v19
	v_cvt_pk_bf16_f32 v11, v16, v17
	global_store_dwordx4 v[20:21], v[8:11], off
	s_nop 1
	v_mul_f32_e32 v8, v13, v13
	v_mul_f32_e32 v9, v15, v15
	v_fmac_f32_e32 v8, v12, v12
	v_fmac_f32_e32 v9, v14, v14
	v_add_f32_e32 v8, v8, v9
	v_mul_f32_e32 v9, v19, v19
	v_fmac_f32_e32 v9, v18, v18
	v_add_f32_e32 v8, v9, v8
	v_mul_f32_e32 v9, v17, v17
	v_fmac_f32_e32 v9, v16, v16
	v_add_f32_e32 v16, v9, v8
	s_waitcnt vmcnt(8)
	v_mov_b64_e32 v[8:9], v[202:203]
	v_mov_b64_e32 v[10:11], v[204:205]
	v_lshlrev_b32_e32 v12, 16, v8
	v_and_b32_e32 v13, 0xffff0000, v8
	v_lshlrev_b32_e32 v8, 16, v9
	v_and_b32_e32 v9, 0xffff0000, v9
	v_lshlrev_b32_e32 v14, 16, v10
	v_and_b32_e32 v15, 0xffff0000, v10
	v_lshlrev_b32_e32 v10, 16, v11
	v_and_b32_e32 v11, 0xffff0000, v11
	v_pk_add_f32 v[6:7], v[6:7], v[8:9]
	v_pk_add_f32 v[4:5], v[4:5], v[12:13]
	v_pk_add_f32 v[8:9], v[2:3], v[10:11]
	v_pk_add_f32 v[10:11], v[0:1], v[14:15]
	v_cvt_pk_bf16_f32 v0, v4, v5
	v_cvt_pk_bf16_f32 v1, v6, v7
	v_cvt_pk_bf16_f32 v2, v10, v11
	v_cvt_pk_bf16_f32 v3, v8, v9
	global_store_dwordx4 v[20:21], v[0:3], off offset:256
	s_nop 1
	v_mul_f32_e32 v0, v5, v5
	v_mul_f32_e32 v1, v7, v7
	v_fmac_f32_e32 v0, v4, v4
	v_fmac_f32_e32 v1, v6, v6
	v_add_f32_e32 v0, v0, v1
	v_mul_f32_e32 v1, v11, v11
	v_fmac_f32_e32 v1, v10, v10
	v_add_f32_e32 v0, v1, v0
	v_mul_f32_e32 v1, v9, v9
	v_fmac_f32_e32 v1, v8, v8
	v_add_f32_e32 v0, v1, v0
	v_add_f32_e32 v0, v16, v0
	ds_bpermute_b32 v1, v207, v0
	s_waitcnt lgkmcnt(0)
	v_add_f32_e32 v0, v0, v1
	ds_bpermute_b32 v1, v208, v0
	s_and_saveexec_b64 s[0:1], s[38:39]
	s_cbranch_execz .LBB0_2352
	s_waitcnt lgkmcnt(0)
	v_add_f32_e32 v0, v0, v1
	v_mul_f32_e32 v0, 0x49800000, v0
	v_trunc_f32_e32 v0, v0
	v_mul_f32_e32 v1, 0x2f800000, v0
	v_floor_f32_e32 v1, v1
	v_fmac_f32_e32 v0, 0xcf800000, v1
	v_cvt_u32_f32_e32 v0, v0
	v_cvt_u32_f32_e32 v1, v1
	global_atomic_add_x2 v[114:115], v[0:1], off offset:1408

; DI unsigned pk2(float lo, float hi) { f32x2 v = {lo, hi}; bf16x2_t b = __builtin_convertvector(v, bf16x2_t); return __builtin_bit_cast(unsigned, b); }
; DI float rstd_of(float ssq, float inv_n) { return 1.0f / sqrtf(ssq * inv_n + EPS); }
; DI void acc_add(acc_t* p, float v, float scale) { atomicAdd(p, (acc_t)(v * scale)); }
; DI float acc_get(const acc_t* p, float inv_scale) { return (float)(*p) * inv_scale; }
;     DI void operator()(const f32x4 (&acc)[2][2][4][2], const Unit& u, int wr, int wc, int fr, int fq) const {
;         const int colb = u.pn * BM + wc * 32 + 8 * fq;
;         EPI_ROWS_BEGIN
;             const float rs = rstd_of(acc_get(ssq + row, 1.0f / SSQ_SCALE), 1.0f / DM); float ss = 0.f;
; #pragma unroll
;             for (int bj = 0; bj < 2; ++bj) { const int col = colb + bj * HALF; const f32x4 v0 = acc[ai][bj][m][0] * rs, v1 = acc[ai][bj][m][1] * rs;
;                 u32x4 w; w.x = pk2(v0[0], v0[1]); w.y = pk2(v0[2], v0[3]); w.z = pk2(v1[0], v1[1]); w.w = pk2(v1[2], v1[3]); *(u32x4*)(Q + (size_t)row * DM + col) = w;
;                 ss += (v0[0] * v0[0] + v0[1] * v0[1]) + (v0[2] * v0[2] + v0[3] * v0[3]) + (v1[0] * v1[0] + v1[1] * v1[1]) + (v1[2] * v1[2] + v1[3] * v1[3]); }
;             ss += __shfl_xor(ss, 16); ss += __shfl_xor(ss, 32);
;             if (fq == 0) acc_add(ssqq + (size_t)row * 4 + u.pn, ss, SSQ_SCALE);
;         EPI_ROWS_END
.LBB0_2504:
	v_lshl_add_u32 v142, s4, 8, v146
	v_ashrrev_i32_e32 v143, 31, v142
	v_lshl_add_u64 v[144:145], v[142:143], 3, s[24:25]
	global_load_dwordx2 v[174:175], v[144:145], off
	global_load_dwordx2 v[176:177], v[144:145], off offset:128
	global_load_dwordx2 v[178:179], v[144:145], off offset:256
	global_load_dwordx2 v[180:181], v[144:145], off offset:384
	global_load_dwordx2 v[182:183], v[144:145], off offset:1024
	global_load_dwordx2 v[184:185], v[144:145], off offset:1152
	global_load_dwordx2 v[186:187], v[144:145], off offset:1280
	global_load_dwordx2 v[188:189], v[144:145], off offset:1408
	s_ashr_i32 s1, s0, 31
	s_waitcnt vmcnt(0)
	v_mov_b64_e32 v[140:141], v[174:175]
	v_ffbh_u32_e32 v150, v141
	v_min_u32_e32 v150, 32, v150
	v_lshlrev_b64 v[140:141], v150, v[140:141]
	v_min_u32_e32 v140, 1, v140
	v_or_b32_e32 v140, v141, v140
	v_cvt_f32_u32_e32 v140, v140
	v_sub_u32_e32 v141, 32, v150
	v_lshlrev_b64 v[150:151], 11, v[142:143]
	v_lshl_add_u64 v[150:151], s[14:15], 0, v[150:151]
	v_ldexp_f32 v140, v140, v141
	v_mul_f32_e32 v140, 0x35800000, v140
	v_fmamk_f32 v140, v140, 0x3a800000, v222
	s_nop 7
	v_rsq_f32_e32 v152, v140
	s_nop 0
	v_mul_f32_e32 v141, v140, v152
	v_fma_f32 v141, -v141, v152, 1.0
	v_mul_f32_e32 v141, 0.5, v141
	v_fmac_f32_e32 v152, v141, v152
	v_lshl_or_b32 v140, s0, 8, v148
	v_pk_mul_f32 v[128:129], v[128:129], v[152:153] op_sel_hi:[1,0]
	v_pk_mul_f32 v[126:127], v[126:127], v[152:153] op_sel_hi:[1,0]
	v_pk_mul_f32 v[120:121], v[120:121], v[152:153] op_sel_hi:[1,0]
	v_pk_mul_f32 v[118:119], v[118:119], v[152:153] op_sel_hi:[1,0]
	v_pk_mul_f32 v[124:125], v[124:125], v[152:153] op_sel_hi:[1,0]
	v_pk_mul_f32 v[122:123], v[122:123], v[152:153] op_sel_hi:[1,0]
	v_pk_mul_f32 v[162:163], v[116:117], v[152:153] op_sel_hi:[1,0]
	v_pk_mul_f32 v[152:153], v[114:115], v[152:153] op_sel_hi:[1,0]
	v_cvt_pk_bf16_f32 v114, v126, v127
	v_cvt_pk_bf16_f32 v115, v128, v129
	v_mul_f32_e32 v127, v127, v127
	v_mul_f32_e32 v129, v129, v129
	v_mul_f32_e32 v141, v119, v119
	v_mul_f32_e32 v164, v121, v121
	v_cvt_pk_bf16_f32 v116, v122, v123
	v_cvt_pk_bf16_f32 v117, v124, v125
	v_mul_f32_e32 v123, v123, v123
	v_mul_f32_e32 v125, v125, v125
	v_mul_f32_e32 v165, v153, v153
	v_fmac_f32_e32 v127, v126, v126
	v_fmac_f32_e32 v129, v128, v128
	v_fmac_f32_e32 v141, v118, v118
	v_fmac_f32_e32 v164, v120, v120
	v_mul_f32_e32 v166, v163, v163
	v_fmac_f32_e32 v123, v122, v122
	v_fmac_f32_e32 v125, v124, v124
	v_fmac_f32_e32 v165, v152, v152
	v_add_f32_e32 v122, v127, v129
	v_add_f32_e32 v124, v141, v164
	v_fmac_f32_e32 v166, v162, v162
	v_add_f32_e32 v122, v123, v122
	v_add_f32_e32 v123, v165, v124
	v_add_f32_e32 v122, v125, v122
	v_add_f32_e32 v123, v166, v123
	v_add_f32_e32 v124, v122, v123
	ds_bpermute_b32 v125, v207, v124
	v_ashrrev_i32_e32 v141, 31, v140
	v_lshl_add_u64 v[122:123], v[140:141], 1, v[150:151]
	global_store_dwordx4 v[122:123], v[114:117], off
	s_waitcnt lgkmcnt(0)
	s_nop 0
	v_add_f32_e32 v114, v124, v125
	ds_bpermute_b32 v115, v208, v114
	v_cvt_pk_bf16_f32 v116, v118, v119
	v_cvt_pk_bf16_f32 v117, v120, v121
	v_cvt_pk_bf16_f32 v118, v152, v153
	v_cvt_pk_bf16_f32 v119, v162, v163
	global_store_dwordx4 v[122:123], v[116:119], off offset:256
	s_and_saveexec_b64 s[4:5], s[2:3]
	s_cbranch_execz .LBB0_2506
	s_waitcnt lgkmcnt(0)
	v_add_f32_e32 v114, v114, v115
	v_mul_f32_e32 v114, 0x49800000, v114
	v_trunc_f32_e32 v114, v114
	v_mul_f32_e32 v115, 0x2f800000, v114
	v_floor_f32_e32 v115, v115
	v_fmac_f32_e32 v114, 0xcf800000, v115
	v_cvt_u32_f32_e32 v114, v114
	v_cvt_u32_f32_e32 v115, v115
	v_lshlrev_b64 v[116:117], 5, v[142:143]
	v_lshl_add_u64 v[116:117], s[28:29], 0, v[116:117]
	v_lshl_add_u64 v[116:117], s[0:1], 3, v[116:117]
	global_atomic_add_x2 v[116:117], v[114:115], off
.LBB0_2506:
	s_or_b64 exec, exec, s[4:5]
	s_waitcnt lgkmcnt(0)
	s_nop 1
	v_mov_b64_e32 v[114:115], v[176:177]
	v_ffbh_u32_e32 v116, v115
	v_min_u32_e32 v116, 32, v116
	v_lshlrev_b64 v[114:115], v116, v[114:115]
	v_min_u32_e32 v114, 1, v114
	v_or_b32_e32 v114, v115, v114
	v_cvt_f32_u32_e32 v114, v114
	v_sub_u32_e32 v115, 32, v116
	v_ldexp_f32 v114, v114, v115
	v_mul_f32_e32 v114, 0x35800000, v114
	v_fmamk_f32 v114, v114, 0x3a800000, v222
	v_rsq_f32_e32 v118, v114
	s_nop 0
	v_mul_f32_e32 v116, v114, v118
	v_fma_f32 v116, -v116, v118, 1.0
	v_mul_f32_e32 v116, 0.5, v116
	v_fmac_f32_e32 v118, v116, v118
	v_or_b32_e32 v114, 16, v142
	v_ashrrev_i32_e32 v115, 31, v114
	v_lshlrev_b64 v[116:117], 11, v[114:115]
	v_pk_mul_f32 v[112:113], v[112:113], v[118:119] op_sel_hi:[1,0]
	v_pk_mul_f32 v[110:111], v[110:111], v[118:119] op_sel_hi:[1,0]
	v_pk_mul_f32 v[104:105], v[104:105], v[118:119] op_sel_hi:[1,0]
	v_pk_mul_f32 v[102:103], v[102:103], v[118:119] op_sel_hi:[1,0]
	v_pk_mul_f32 v[108:109], v[108:109], v[118:119] op_sel_hi:[1,0]
	v_pk_mul_f32 v[106:107], v[106:107], v[118:119] op_sel_hi:[1,0]
	v_pk_mul_f32 v[120:121], v[100:101], v[118:119] op_sel_hi:[1,0]
	v_pk_mul_f32 v[118:119], v[98:99], v[118:119] op_sel_hi:[1,0]
	v_cvt_pk_bf16_f32 v98, v110, v111
	v_cvt_pk_bf16_f32 v99, v112, v113
	v_mul_f32_e32 v111, v111, v111
	v_mul_f32_e32 v113, v113, v113
	v_mul_f32_e32 v122, v103, v103
	v_mul_f32_e32 v123, v105, v105
	v_cvt_pk_bf16_f32 v100, v106, v107
	v_cvt_pk_bf16_f32 v101, v108, v109
	v_mul_f32_e32 v107, v107, v107
	v_mul_f32_e32 v109, v109, v109
	v_mul_f32_e32 v124, v119, v119
	v_fmac_f32_e32 v111, v110, v110
	v_fmac_f32_e32 v113, v112, v112
	v_fmac_f32_e32 v122, v102, v102
	v_fmac_f32_e32 v123, v104, v104
	v_mul_f32_e32 v125, v121, v121
	v_fmac_f32_e32 v107, v106, v106
	v_fmac_f32_e32 v109, v108, v108
	v_fmac_f32_e32 v124, v118, v118
	v_add_f32_e32 v106, v111, v113
	v_add_f32_e32 v108, v122, v123
	v_fmac_f32_e32 v125, v120, v120
	v_add_f32_e32 v106, v107, v106
	v_add_f32_e32 v107, v124, v108
	v_add_f32_e32 v106, v109, v106
	v_add_f32_e32 v107, v125, v107
	v_add_f32_e32 v108, v106, v107
	ds_bpermute_b32 v109, v207, v108
	v_lshl_add_u64 v[106:107], s[14:15], 0, v[116:117]
	v_lshl_add_u64 v[106:107], v[140:141], 1, v[106:107]
	global_store_dwordx4 v[106:107], v[98:101], off
	s_waitcnt lgkmcnt(0)
	s_nop 0
	v_add_f32_e32 v98, v108, v109
	ds_bpermute_b32 v99, v208, v98
	v_cvt_pk_bf16_f32 v100, v102, v103
	v_cvt_pk_bf16_f32 v101, v104, v105
	v_cvt_pk_bf16_f32 v102, v118, v119
	v_cvt_pk_bf16_f32 v103, v120, v121
	global_store_dwordx4 v[106:107], v[100:103], off offset:256
	s_and_saveexec_b64 s[4:5], s[2:3]
	s_cbranch_execz .LBB0_2508
	s_waitcnt lgkmcnt(0)
	v_add_f32_e32 v98, v98, v99
	v_mul_f32_e32 v98, 0x49800000, v98
	v_trunc_f32_e32 v98, v98
	v_mul_f32_e32 v99, 0x2f800000, v98
	v_floor_f32_e32 v99, v99
	v_fmac_f32_e32 v98, 0xcf800000, v99
	v_cvt_u32_f32_e32 v98, v98
	v_cvt_u32_f32_e32 v99, v99
	v_lshlrev_b64 v[100:101], 5, v[114:115]
	v_lshl_add_u64 v[100:101], s[28:29], 0, v[100:101]
	v_lshl_add_u64 v[100:101], s[0:1], 3, v[100:101]
	global_atomic_add_x2 v[100:101], v[98:99], off
; DI unsigned pk2(float lo, float hi) { f32x2 v = {lo, hi}; bf16x2_t b = __builtin_convertvector(v, bf16x2_t); return __builtin_bit_cast(unsigned, b); }
; DI float rstd_of(float ssq, float inv_n) { return 1.0f / sqrtf(ssq * inv_n + EPS); }
; DI void acc_add(acc_t* p, float v, float scale) { atomicAdd(p, (acc_t)(v * scale)); }
; DI float acc_get(const acc_t* p, float inv_scale) { return (float)(*p) * inv_scale; }
;     DI void operator()(const f32x4 (&acc)[2][2][4][2], const Unit& u, int wr, int wc, int fr, int fq) const {
;         const int colb = u.pn * BM + wc * 32 + 8 * fq;
;         EPI_ROWS_BEGIN
;             const float rs = rstd_of(acc_get(ssq + row, 1.0f / SSQ_SCALE), 1.0f / DM); float ss = 0.f;
; #pragma unroll
;             for (int bj = 0; bj < 2; ++bj) { const int col = colb + bj * HALF; const f32x4 v0 = acc[ai][bj][m][0] * rs, v1 = acc[ai][bj][m][1] * rs;
;                 u32x4 w; w.x = pk2(v0[0], v0[1]); w.y = pk2(v0[2], v0[3]); w.z = pk2(v1[0], v1[1]); w.w = pk2(v1[2], v1[3]); *(u32x4*)(Q + (size_t)row * DM + col) = w;
;                 ss += (v0[0] * v0[0] + v0[1] * v0[1]) + (v0[2] * v0[2] + v0[3] * v0[3]) + (v1[0] * v1[0] + v1[1] * v1[1]) + (v1[2] * v1[2] + v1[3] * v1[3]); }
;             ss += __shfl_xor(ss, 16); ss += __shfl_xor(ss, 32);
;             if (fq == 0) acc_add(ssqq + (size_t)row * 4 + u.pn, ss, SSQ_SCALE);
;         EPI_ROWS_END
.LBB0_2508:
	s_or_b64 exec, exec, s[4:5]
	s_waitcnt lgkmcnt(0)
	s_nop 1
	v_mov_b64_e32 v[98:99], v[178:179]
	v_ffbh_u32_e32 v100, v99
	v_min_u32_e32 v100, 32, v100
	v_lshlrev_b64 v[98:99], v100, v[98:99]
	v_min_u32_e32 v98, 1, v98
	v_or_b32_e32 v98, v99, v98
	v_cvt_f32_u32_e32 v98, v98
	v_sub_u32_e32 v99, 32, v100
	v_ldexp_f32 v98, v98, v99
	v_mul_f32_e32 v98, 0x35800000, v98
	v_fmamk_f32 v98, v98, 0x3a800000, v222
	v_rsq_f32_e32 v102, v98
	s_nop 0
	v_mul_f32_e32 v100, v98, v102
	v_fma_f32 v100, -v100, v102, 1.0
	v_mul_f32_e32 v100, 0.5, v100
	v_fmac_f32_e32 v102, v100, v102
	v_or_b32_e32 v98, 32, v142
	v_ashrrev_i32_e32 v99, 31, v98
	v_lshlrev_b64 v[100:101], 11, v[98:99]
	v_pk_mul_f32 v[94:95], v[94:95], v[102:103] op_sel_hi:[1,0]
	v_pk_mul_f32 v[92:93], v[92:93], v[102:103] op_sel_hi:[1,0]
	v_pk_mul_f32 v[86:87], v[86:87], v[102:103] op_sel_hi:[1,0]
	v_pk_mul_f32 v[84:85], v[84:85], v[102:103] op_sel_hi:[1,0]
	v_pk_mul_f32 v[90:91], v[90:91], v[102:103] op_sel_hi:[1,0]
	v_pk_mul_f32 v[88:89], v[88:89], v[102:103] op_sel_hi:[1,0]
	v_pk_mul_f32 v[104:105], v[82:83], v[102:103] op_sel_hi:[1,0]
	v_pk_mul_f32 v[102:103], v[80:81], v[102:103] op_sel_hi:[1,0]
	v_cvt_pk_bf16_f32 v80, v92, v93
	v_cvt_pk_bf16_f32 v81, v94, v95
	v_mul_f32_e32 v93, v93, v93
	v_mul_f32_e32 v95, v95, v95
	v_mul_f32_e32 v106, v85, v85
	v_mul_f32_e32 v107, v87, v87
	v_cvt_pk_bf16_f32 v82, v88, v89
	v_cvt_pk_bf16_f32 v83, v90, v91
	v_mul_f32_e32 v89, v89, v89
	v_mul_f32_e32 v91, v91, v91
	v_mul_f32_e32 v108, v103, v103
	v_fmac_f32_e32 v93, v92, v92
	v_fmac_f32_e32 v95, v94, v94
	v_fmac_f32_e32 v106, v84, v84
	v_fmac_f32_e32 v107, v86, v86
	v_mul_f32_e32 v109, v105, v105
	v_fmac_f32_e32 v89, v88, v88
	v_fmac_f32_e32 v91, v90, v90
	v_fmac_f32_e32 v108, v102, v102
	v_add_f32_e32 v88, v93, v95
	v_add_f32_e32 v90, v106, v107
	v_fmac_f32_e32 v109, v104, v104
	v_add_f32_e32 v88, v89, v88
	v_add_f32_e32 v89, v108, v90
	v_add_f32_e32 v88, v91, v88
	v_add_f32_e32 v89, v109, v89
	v_add_f32_e32 v90, v88, v89
	ds_bpermute_b32 v91, v207, v90
	v_lshl_add_u64 v[88:89], s[14:15], 0, v[100:101]
	v_lshl_add_u64 v[88:89], v[140:141], 1, v[88:89]
	global_store_dwordx4 v[88:89], v[80:83], off
	s_waitcnt lgkmcnt(0)
	s_nop 0
	v_add_f32_e32 v80, v90, v91
	ds_bpermute_b32 v81, v208, v80
	v_cvt_pk_bf16_f32 v82, v84, v85
	v_cvt_pk_bf16_f32 v83, v86, v87
	v_cvt_pk_bf16_f32 v84, v102, v103
	v_cvt_pk_bf16_f32 v85, v104, v105
	global_store_dwordx4 v[88:89], v[82:85], off offset:256
	s_and_saveexec_b64 s[4:5], s[2:3]
	s_cbranch_execz .LBB0_2510
	s_waitcnt lgkmcnt(0)
	v_add_f32_e32 v80, v80, v81
	v_mul_f32_e32 v80, 0x49800000, v80
	v_trunc_f32_e32 v80, v80
	v_mul_f32_e32 v81, 0x2f800000, v80
	v_floor_f32_e32 v81, v81
	v_fmac_f32_e32 v80, 0xcf800000, v81
	v_cvt_u32_f32_e32 v80, v80
	v_cvt_u32_f32_e32 v81, v81
	v_lshlrev_b64 v[82:83], 5, v[98:99]
	v_lshl_add_u64 v[82:83], s[28:29], 0, v[82:83]
	v_lshl_add_u64 v[82:83], s[0:1], 3, v[82:83]
	global_atomic_add_x2 v[82:83], v[80:81], off
.LBB0_2510:
	s_or_b64 exec, exec, s[4:5]
	s_waitcnt lgkmcnt(0)
	s_nop 1
	v_mov_b64_e32 v[80:81], v[180:181]
	v_ffbh_u32_e32 v82, v81
	v_min_u32_e32 v82, 32, v82
	v_lshlrev_b64 v[80:81], v82, v[80:81]
	v_min_u32_e32 v80, 1, v80
	v_or_b32_e32 v80, v81, v80
	v_cvt_f32_u32_e32 v80, v80
	v_sub_u32_e32 v81, 32, v82
	v_ldexp_f32 v80, v80, v81
	v_mul_f32_e32 v80, 0x35800000, v80
	v_fmamk_f32 v80, v80, 0x3a800000, v222
	v_rsq_f32_e32 v84, v80
	s_nop 0
	v_mul_f32_e32 v82, v80, v84
	v_fma_f32 v82, -v82, v84, 1.0
	v_mul_f32_e32 v82, 0.5, v82
	v_fmac_f32_e32 v84, v82, v84
	v_or_b32_e32 v80, 48, v142
	v_ashrrev_i32_e32 v81, 31, v80
	v_lshlrev_b64 v[82:83], 11, v[80:81]
	v_pk_mul_f32 v[78:79], v[78:79], v[84:85] op_sel_hi:[1,0]
	v_pk_mul_f32 v[76:77], v[76:77], v[84:85] op_sel_hi:[1,0]
	v_pk_mul_f32 v[70:71], v[70:71], v[84:85] op_sel_hi:[1,0]
	v_pk_mul_f32 v[68:69], v[68:69], v[84:85] op_sel_hi:[1,0]
	v_pk_mul_f32 v[74:75], v[74:75], v[84:85] op_sel_hi:[1,0]
	v_pk_mul_f32 v[72:73], v[72:73], v[84:85] op_sel_hi:[1,0]
	v_pk_mul_f32 v[86:87], v[66:67], v[84:85] op_sel_hi:[1,0]
	v_pk_mul_f32 v[84:85], v[64:65], v[84:85] op_sel_hi:[1,0]
	v_cvt_pk_bf16_f32 v64, v76, v77
	v_cvt_pk_bf16_f32 v65, v78, v79
	v_mul_f32_e32 v77, v77, v77
	v_mul_f32_e32 v79, v79, v79
	v_mul_f32_e32 v88, v69, v69
	v_mul_f32_e32 v89, v71, v71
	v_cvt_pk_bf16_f32 v66, v72, v73
	v_cvt_pk_bf16_f32 v67, v74, v75
	v_mul_f32_e32 v73, v73, v73
	v_mul_f32_e32 v75, v75, v75
	v_mul_f32_e32 v90, v85, v85
	v_fmac_f32_e32 v77, v76, v76
	v_fmac_f32_e32 v79, v78, v78
	v_fmac_f32_e32 v88, v68, v68
	v_fmac_f32_e32 v89, v70, v70
	v_mul_f32_e32 v91, v87, v87
	v_fmac_f32_e32 v73, v72, v72
	v_fmac_f32_e32 v75, v74, v74
	v_fmac_f32_e32 v90, v84, v84
	v_add_f32_e32 v72, v77, v79
	v_add_f32_e32 v74, v88, v89
	v_fmac_f32_e32 v91, v86, v86
	v_add_f32_e32 v72, v73, v72
	v_add_f32_e32 v73, v90, v74
	v_add_f32_e32 v72, v75, v72
	v_add_f32_e32 v73, v91, v73
	v_add_f32_e32 v74, v72, v73
	ds_bpermute_b32 v75, v207, v74
	v_lshl_add_u64 v[72:73], s[14:15], 0, v[82:83]
	v_lshl_add_u64 v[72:73], v[140:141], 1, v[72:73]
	global_store_dwordx4 v[72:73], v[64:67], off
	s_waitcnt lgkmcnt(0)
	s_nop 0
	v_add_f32_e32 v64, v74, v75
	ds_bpermute_b32 v65, v208, v64
	v_cvt_pk_bf16_f32 v66, v68, v69
	v_cvt_pk_bf16_f32 v67, v70, v71
	v_cvt_pk_bf16_f32 v68, v84, v85
	v_cvt_pk_bf16_f32 v69, v86, v87
	global_store_dwordx4 v[72:73], v[66:69], off offset:256
	s_and_saveexec_b64 s[4:5], s[2:3]
	s_cbranch_execz .LBB0_2512
	s_waitcnt lgkmcnt(0)
	v_add_f32_e32 v64, v64, v65
	v_mul_f32_e32 v64, 0x49800000, v64
	v_trunc_f32_e32 v64, v64
	v_mul_f32_e32 v65, 0x2f800000, v64
	v_floor_f32_e32 v65, v65
	v_fmac_f32_e32 v64, 0xcf800000, v65
	v_cvt_u32_f32_e32 v64, v64
	v_cvt_u32_f32_e32 v65, v65
	v_lshlrev_b64 v[66:67], 5, v[80:81]
	v_lshl_add_u64 v[66:67], s[28:29], 0, v[66:67]
	v_lshl_add_u64 v[66:67], s[0:1], 3, v[66:67]
	global_atomic_add_x2 v[66:67], v[64:65], off
; DI unsigned pk2(float lo, float hi) { f32x2 v = {lo, hi}; bf16x2_t b = __builtin_convertvector(v, bf16x2_t); return __builtin_bit_cast(unsigned, b); }
; DI float rstd_of(float ssq, float inv_n) { return 1.0f / sqrtf(ssq * inv_n + EPS); }
; DI void acc_add(acc_t* p, float v, float scale) { atomicAdd(p, (acc_t)(v * scale)); }
; DI float acc_get(const acc_t* p, float inv_scale) { return (float)(*p) * inv_scale; }
;     DI void operator()(const f32x4 (&acc)[2][2][4][2], const Unit& u, int wr, int wc, int fr, int fq) const {
;         const int colb = u.pn * BM + wc * 32 + 8 * fq;
;         EPI_ROWS_BEGIN
;             const float rs = rstd_of(acc_get(ssq + row, 1.0f / SSQ_SCALE), 1.0f / DM); float ss = 0.f;
; #pragma unroll
;             for (int bj = 0; bj < 2; ++bj) { const int col = colb + bj * HALF; const f32x4 v0 = acc[ai][bj][m][0] * rs, v1 = acc[ai][bj][m][1] * rs;
;                 u32x4 w; w.x = pk2(v0[0], v0[1]); w.y = pk2(v0[2], v0[3]); w.z = pk2(v1[0], v1[1]); w.w = pk2(v1[2], v1[3]); *(u32x4*)(Q + (size_t)row * DM + col) = w;
;                 ss += (v0[0] * v0[0] + v0[1] * v0[1]) + (v0[2] * v0[2] + v0[3] * v0[3]) + (v1[0] * v1[0] + v1[1] * v1[1]) + (v1[2] * v1[2] + v1[3] * v1[3]); }
;             ss += __shfl_xor(ss, 16); ss += __shfl_xor(ss, 32);
;             if (fq == 0) acc_add(ssqq + (size_t)row * 4 + u.pn, ss, SSQ_SCALE);
;         EPI_ROWS_END
.LBB0_2512:
	s_or_b64 exec, exec, s[4:5]
	s_waitcnt lgkmcnt(0)
	s_nop 1
	v_mov_b64_e32 v[64:65], v[182:183]
	v_ffbh_u32_e32 v66, v65
	v_min_u32_e32 v66, 32, v66
	v_lshlrev_b64 v[64:65], v66, v[64:65]
	v_min_u32_e32 v64, 1, v64
	v_or_b32_e32 v64, v65, v64
	v_cvt_f32_u32_e32 v64, v64
	v_sub_u32_e32 v65, 32, v66
	v_ldexp_f32 v64, v64, v65
	v_mul_f32_e32 v64, 0x35800000, v64
	v_fmamk_f32 v64, v64, 0x3a800000, v222
	v_rsq_f32_e32 v68, v64
	s_nop 0
	v_mul_f32_e32 v66, v64, v68
	v_fma_f32 v66, -v66, v68, 1.0
	v_mul_f32_e32 v66, 0.5, v66
	v_fmac_f32_e32 v68, v66, v68
	v_add_u32_e32 v64, 0x80, v142
	v_ashrrev_i32_e32 v65, 31, v64
	v_lshlrev_b64 v[66:67], 11, v[64:65]
	v_pk_mul_f32 v[62:63], v[62:63], v[68:69] op_sel_hi:[1,0]
	v_pk_mul_f32 v[60:61], v[60:61], v[68:69] op_sel_hi:[1,0]
	v_pk_mul_f32 v[54:55], v[54:55], v[68:69] op_sel_hi:[1,0]
	v_pk_mul_f32 v[52:53], v[52:53], v[68:69] op_sel_hi:[1,0]
	v_pk_mul_f32 v[58:59], v[58:59], v[68:69] op_sel_hi:[1,0]
	v_pk_mul_f32 v[56:57], v[56:57], v[68:69] op_sel_hi:[1,0]
	v_pk_mul_f32 v[70:71], v[50:51], v[68:69] op_sel_hi:[1,0]
	v_pk_mul_f32 v[68:69], v[48:49], v[68:69] op_sel_hi:[1,0]
	v_cvt_pk_bf16_f32 v48, v60, v61
	v_cvt_pk_bf16_f32 v49, v62, v63
	v_mul_f32_e32 v61, v61, v61
	v_mul_f32_e32 v63, v63, v63
	v_mul_f32_e32 v72, v53, v53
	v_mul_f32_e32 v73, v55, v55
	v_cvt_pk_bf16_f32 v50, v56, v57
	v_cvt_pk_bf16_f32 v51, v58, v59
	v_mul_f32_e32 v57, v57, v57
	v_mul_f32_e32 v59, v59, v59
	v_mul_f32_e32 v74, v69, v69
	v_fmac_f32_e32 v61, v60, v60
	v_fmac_f32_e32 v63, v62, v62
	v_fmac_f32_e32 v72, v52, v52
	v_fmac_f32_e32 v73, v54, v54
	v_mul_f32_e32 v75, v71, v71
	v_fmac_f32_e32 v57, v56, v56
	v_fmac_f32_e32 v59, v58, v58
	v_fmac_f32_e32 v74, v68, v68
	v_add_f32_e32 v56, v61, v63
	v_add_f32_e32 v58, v72, v73
	v_fmac_f32_e32 v75, v70, v70
	v_add_f32_e32 v56, v57, v56
	v_add_f32_e32 v57, v74, v58
	v_add_f32_e32 v56, v59, v56
	v_add_f32_e32 v57, v75, v57
	v_add_f32_e32 v58, v56, v57
	ds_bpermute_b32 v59, v207, v58
	v_lshl_add_u64 v[56:57], s[14:15], 0, v[66:67]
	v_lshl_add_u64 v[56:57], v[140:141], 1, v[56:57]
	global_store_dwordx4 v[56:57], v[48:51], off
	s_waitcnt lgkmcnt(0)
	s_nop 0
	v_add_f32_e32 v48, v58, v59
	ds_bpermute_b32 v49, v208, v48
	v_cvt_pk_bf16_f32 v50, v52, v53
	v_cvt_pk_bf16_f32 v51, v54, v55
	v_cvt_pk_bf16_f32 v52, v68, v69
	v_cvt_pk_bf16_f32 v53, v70, v71
	global_store_dwordx4 v[56:57], v[50:53], off offset:256
	s_and_saveexec_b64 s[4:5], s[2:3]
	s_cbranch_execz .LBB0_2514
	s_waitcnt lgkmcnt(0)
	v_add_f32_e32 v48, v48, v49
	v_mul_f32_e32 v48, 0x49800000, v48
	v_trunc_f32_e32 v48, v48
	v_mul_f32_e32 v49, 0x2f800000, v48
	v_floor_f32_e32 v49, v49
	v_fmac_f32_e32 v48, 0xcf800000, v49
	v_cvt_u32_f32_e32 v48, v48
	v_cvt_u32_f32_e32 v49, v49
	v_lshlrev_b64 v[50:51], 5, v[64:65]
	v_lshl_add_u64 v[50:51], s[28:29], 0, v[50:51]
	v_lshl_add_u64 v[50:51], s[0:1], 3, v[50:51]
	global_atomic_add_x2 v[50:51], v[48:49], off
.LBB0_2514:
	s_or_b64 exec, exec, s[4:5]
	s_waitcnt lgkmcnt(0)
	s_nop 1
	v_mov_b64_e32 v[48:49], v[184:185]
	v_ffbh_u32_e32 v50, v49
	v_min_u32_e32 v50, 32, v50
	v_lshlrev_b64 v[48:49], v50, v[48:49]
	v_min_u32_e32 v48, 1, v48
	v_or_b32_e32 v48, v49, v48
	v_cvt_f32_u32_e32 v48, v48
	v_sub_u32_e32 v49, 32, v50
	v_ldexp_f32 v48, v48, v49
	v_mul_f32_e32 v48, 0x35800000, v48
	v_fmamk_f32 v48, v48, 0x3a800000, v222
	v_rsq_f32_e32 v52, v48
	s_nop 0
	v_mul_f32_e32 v50, v48, v52
	v_fma_f32 v50, -v50, v52, 1.0
	v_mul_f32_e32 v50, 0.5, v50
	v_fmac_f32_e32 v52, v50, v52
	v_add_u32_e32 v48, 0x90, v142
	v_ashrrev_i32_e32 v49, 31, v48
	v_lshlrev_b64 v[50:51], 11, v[48:49]
	v_pk_mul_f32 v[46:47], v[46:47], v[52:53] op_sel_hi:[1,0]
	v_pk_mul_f32 v[44:45], v[44:45], v[52:53] op_sel_hi:[1,0]
	v_pk_mul_f32 v[38:39], v[38:39], v[52:53] op_sel_hi:[1,0]
	v_pk_mul_f32 v[36:37], v[36:37], v[52:53] op_sel_hi:[1,0]
	v_pk_mul_f32 v[42:43], v[42:43], v[52:53] op_sel_hi:[1,0]
	v_pk_mul_f32 v[40:41], v[40:41], v[52:53] op_sel_hi:[1,0]
	v_pk_mul_f32 v[54:55], v[34:35], v[52:53] op_sel_hi:[1,0]
	v_pk_mul_f32 v[52:53], v[32:33], v[52:53] op_sel_hi:[1,0]
	v_cvt_pk_bf16_f32 v32, v44, v45
	v_cvt_pk_bf16_f32 v33, v46, v47
	v_mul_f32_e32 v45, v45, v45
	v_mul_f32_e32 v47, v47, v47
	v_mul_f32_e32 v56, v37, v37
	v_mul_f32_e32 v57, v39, v39
	v_cvt_pk_bf16_f32 v34, v40, v41
	v_cvt_pk_bf16_f32 v35, v42, v43
	v_mul_f32_e32 v41, v41, v41
	v_mul_f32_e32 v43, v43, v43
	v_mul_f32_e32 v58, v53, v53
	v_fmac_f32_e32 v45, v44, v44
	v_fmac_f32_e32 v47, v46, v46
	v_fmac_f32_e32 v56, v36, v36
	v_fmac_f32_e32 v57, v38, v38
	v_mul_f32_e32 v59, v55, v55
	v_fmac_f32_e32 v41, v40, v40
	v_fmac_f32_e32 v43, v42, v42
	v_fmac_f32_e32 v58, v52, v52
	v_add_f32_e32 v40, v45, v47
	v_add_f32_e32 v42, v56, v57
	v_fmac_f32_e32 v59, v54, v54
	v_add_f32_e32 v40, v41, v40
	v_add_f32_e32 v41, v58, v42
	v_add_f32_e32 v40, v43, v40
	v_add_f32_e32 v41, v59, v41
	v_add_f32_e32 v42, v40, v41
	ds_bpermute_b32 v43, v207, v42
	v_lshl_add_u64 v[40:41], s[14:15], 0, v[50:51]
	v_lshl_add_u64 v[40:41], v[140:141], 1, v[40:41]
	global_store_dwordx4 v[40:41], v[32:35], off
	s_waitcnt lgkmcnt(0)
	s_nop 0
	v_add_f32_e32 v32, v42, v43
	ds_bpermute_b32 v33, v208, v32
	v_cvt_pk_bf16_f32 v34, v36, v37
	v_cvt_pk_bf16_f32 v35, v38, v39
	v_cvt_pk_bf16_f32 v36, v52, v53
	v_cvt_pk_bf16_f32 v37, v54, v55
	global_store_dwordx4 v[40:41], v[34:37], off offset:256
	s_and_saveexec_b64 s[4:5], s[2:3]
	s_cbranch_execz .LBB0_2516
	s_waitcnt lgkmcnt(0)
	v_add_f32_e32 v32, v32, v33
	v_mul_f32_e32 v32, 0x49800000, v32
	v_trunc_f32_e32 v32, v32
	v_mul_f32_e32 v33, 0x2f800000, v32
	v_floor_f32_e32 v33, v33
	v_fmac_f32_e32 v32, 0xcf800000, v33
	v_cvt_u32_f32_e32 v32, v32
	v_cvt_u32_f32_e32 v33, v33
	v_lshlrev_b64 v[34:35], 5, v[48:49]
	v_lshl_add_u64 v[34:35], s[28:29], 0, v[34:35]
	v_lshl_add_u64 v[34:35], s[0:1], 3, v[34:35]
	global_atomic_add_x2 v[34:35], v[32:33], off
; DI unsigned pk2(float lo, float hi) { f32x2 v = {lo, hi}; bf16x2_t b = __builtin_convertvector(v, bf16x2_t); return __builtin_bit_cast(unsigned, b); }
; DI float rstd_of(float ssq, float inv_n) { return 1.0f / sqrtf(ssq * inv_n + EPS); }
; DI void acc_add(acc_t* p, float v, float scale) { atomicAdd(p, (acc_t)(v * scale)); }
; DI float acc_get(const acc_t* p, float inv_scale) { return (float)(*p) * inv_scale; }
;     DI void operator()(const f32x4 (&acc)[2][2][4][2], const Unit& u, int wr, int wc, int fr, int fq) const {
;         const int colb = u.pn * BM + wc * 32 + 8 * fq;
;         EPI_ROWS_BEGIN
;             const float rs = rstd_of(acc_get(ssq + row, 1.0f / SSQ_SCALE), 1.0f / DM); float ss = 0.f;
; #pragma unroll
;             for (int bj = 0; bj < 2; ++bj) { const int col = colb + bj * HALF; const f32x4 v0 = acc[ai][bj][m][0] * rs, v1 = acc[ai][bj][m][1] * rs;
;                 u32x4 w; w.x = pk2(v0[0], v0[1]); w.y = pk2(v0[2], v0[3]); w.z = pk2(v1[0], v1[1]); w.w = pk2(v1[2], v1[3]); *(u32x4*)(Q + (size_t)row * DM + col) = w;
;                 ss += (v0[0] * v0[0] + v0[1] * v0[1]) + (v0[2] * v0[2] + v0[3] * v0[3]) + (v1[0] * v1[0] + v1[1] * v1[1]) + (v1[2] * v1[2] + v1[3] * v1[3]); }
;             ss += __shfl_xor(ss, 16); ss += __shfl_xor(ss, 32);
;             if (fq == 0) acc_add(ssqq + (size_t)row * 4 + u.pn, ss, SSQ_SCALE);
;         EPI_ROWS_END
.LBB0_2516:
	s_or_b64 exec, exec, s[4:5]
	s_waitcnt lgkmcnt(0)
	s_nop 1
	v_mov_b64_e32 v[32:33], v[186:187]
	v_ffbh_u32_e32 v34, v33
	v_min_u32_e32 v34, 32, v34
	v_lshlrev_b64 v[32:33], v34, v[32:33]
	v_min_u32_e32 v32, 1, v32
	v_or_b32_e32 v32, v33, v32
	v_cvt_f32_u32_e32 v32, v32
	v_sub_u32_e32 v33, 32, v34
	v_ldexp_f32 v32, v32, v33
	v_mul_f32_e32 v32, 0x35800000, v32
	v_fmamk_f32 v32, v32, 0x3a800000, v222
	v_rsq_f32_e32 v36, v32
	s_nop 0
	v_mul_f32_e32 v34, v32, v36
	v_fma_f32 v34, -v34, v36, 1.0
	v_mul_f32_e32 v34, 0.5, v34
	v_fmac_f32_e32 v36, v34, v36
	v_add_u32_e32 v32, 0xa0, v142
	v_ashrrev_i32_e32 v33, 31, v32
	v_lshlrev_b64 v[34:35], 11, v[32:33]
	v_pk_mul_f32 v[30:31], v[30:31], v[36:37] op_sel_hi:[1,0]
	v_pk_mul_f32 v[28:29], v[28:29], v[36:37] op_sel_hi:[1,0]
	v_pk_mul_f32 v[22:23], v[22:23], v[36:37] op_sel_hi:[1,0]
	v_pk_mul_f32 v[20:21], v[20:21], v[36:37] op_sel_hi:[1,0]
	v_pk_mul_f32 v[26:27], v[26:27], v[36:37] op_sel_hi:[1,0]
	v_pk_mul_f32 v[24:25], v[24:25], v[36:37] op_sel_hi:[1,0]
	v_pk_mul_f32 v[38:39], v[18:19], v[36:37] op_sel_hi:[1,0]
	v_pk_mul_f32 v[36:37], v[16:17], v[36:37] op_sel_hi:[1,0]
	v_cvt_pk_bf16_f32 v16, v28, v29
	v_cvt_pk_bf16_f32 v17, v30, v31
	v_mul_f32_e32 v29, v29, v29
	v_mul_f32_e32 v31, v31, v31
	v_mul_f32_e32 v40, v21, v21
	v_mul_f32_e32 v41, v23, v23
	v_cvt_pk_bf16_f32 v18, v24, v25
	v_cvt_pk_bf16_f32 v19, v26, v27
	v_mul_f32_e32 v25, v25, v25
	v_mul_f32_e32 v27, v27, v27
	v_mul_f32_e32 v42, v37, v37
	v_fmac_f32_e32 v29, v28, v28
	v_fmac_f32_e32 v31, v30, v30
	v_fmac_f32_e32 v40, v20, v20
	v_fmac_f32_e32 v41, v22, v22
	v_mul_f32_e32 v43, v39, v39
	v_fmac_f32_e32 v25, v24, v24
	v_fmac_f32_e32 v27, v26, v26
	v_fmac_f32_e32 v42, v36, v36
	v_add_f32_e32 v24, v29, v31
	v_add_f32_e32 v26, v40, v41
	v_fmac_f32_e32 v43, v38, v38
	v_add_f32_e32 v24, v25, v24
	v_add_f32_e32 v25, v42, v26
	v_add_f32_e32 v24, v27, v24
	v_add_f32_e32 v25, v43, v25
	v_add_f32_e32 v26, v24, v25
	ds_bpermute_b32 v27, v207, v26
	v_lshl_add_u64 v[24:25], s[14:15], 0, v[34:35]
	v_lshl_add_u64 v[24:25], v[140:141], 1, v[24:25]
	global_store_dwordx4 v[24:25], v[16:19], off
	s_waitcnt lgkmcnt(0)
	s_nop 0
	v_add_f32_e32 v16, v26, v27
	ds_bpermute_b32 v17, v208, v16
	v_cvt_pk_bf16_f32 v18, v20, v21
	v_cvt_pk_bf16_f32 v19, v22, v23
	v_cvt_pk_bf16_f32 v20, v36, v37
	v_cvt_pk_bf16_f32 v21, v38, v39
	global_store_dwordx4 v[24:25], v[18:21], off offset:256
	s_and_saveexec_b64 s[4:5], s[2:3]
	s_cbranch_execz .LBB0_2518
	s_waitcnt lgkmcnt(0)
	v_add_f32_e32 v16, v16, v17
	v_mul_f32_e32 v16, 0x49800000, v16
	v_trunc_f32_e32 v16, v16
	v_mul_f32_e32 v17, 0x2f800000, v16
	v_floor_f32_e32 v17, v17
	v_fmac_f32_e32 v16, 0xcf800000, v17
	v_cvt_u32_f32_e32 v16, v16
	v_cvt_u32_f32_e32 v17, v17
	v_lshlrev_b64 v[18:19], 5, v[32:33]
	v_lshl_add_u64 v[18:19], s[28:29], 0, v[18:19]
	v_lshl_add_u64 v[18:19], s[0:1], 3, v[18:19]
	global_atomic_add_x2 v[18:19], v[16:17], off
.LBB0_2518:
	s_or_b64 exec, exec, s[4:5]
	s_waitcnt lgkmcnt(0)
	s_nop 1
	v_mov_b64_e32 v[16:17], v[188:189]
	v_ffbh_u32_e32 v18, v17
	v_min_u32_e32 v18, 32, v18
	v_lshlrev_b64 v[16:17], v18, v[16:17]
	v_min_u32_e32 v16, 1, v16
	v_or_b32_e32 v16, v17, v16
	v_cvt_f32_u32_e32 v16, v16
	v_sub_u32_e32 v17, 32, v18
	v_ldexp_f32 v16, v16, v17
	v_mul_f32_e32 v16, 0x35800000, v16
	v_fmamk_f32 v16, v16, 0x3a800000, v222
	v_rsq_f32_e32 v20, v16
	s_nop 0
	v_mul_f32_e32 v18, v16, v20
	v_fma_f32 v18, -v18, v20, 1.0
	v_mul_f32_e32 v18, 0.5, v18
	v_fmac_f32_e32 v20, v18, v20
	v_add_u32_e32 v16, 0xb0, v142
	v_ashrrev_i32_e32 v17, 31, v16
	v_lshlrev_b64 v[18:19], 11, v[16:17]
	v_pk_mul_f32 v[14:15], v[14:15], v[20:21] op_sel_hi:[1,0]
	v_pk_mul_f32 v[12:13], v[12:13], v[20:21] op_sel_hi:[1,0]
	v_pk_mul_f32 v[6:7], v[6:7], v[20:21] op_sel_hi:[1,0]
	v_pk_mul_f32 v[4:5], v[4:5], v[20:21] op_sel_hi:[1,0]
	v_pk_mul_f32 v[10:11], v[10:11], v[20:21] op_sel_hi:[1,0]
	v_pk_mul_f32 v[8:9], v[8:9], v[20:21] op_sel_hi:[1,0]
	v_pk_mul_f32 v[22:23], v[2:3], v[20:21] op_sel_hi:[1,0]
	v_pk_mul_f32 v[20:21], v[0:1], v[20:21] op_sel_hi:[1,0]
	v_cvt_pk_bf16_f32 v0, v12, v13
	v_cvt_pk_bf16_f32 v1, v14, v15
	v_mul_f32_e32 v13, v13, v13
	v_mul_f32_e32 v15, v15, v15
	v_mul_f32_e32 v24, v5, v5
	v_mul_f32_e32 v25, v7, v7
	v_cvt_pk_bf16_f32 v2, v8, v9
	v_cvt_pk_bf16_f32 v3, v10, v11
	v_mul_f32_e32 v9, v9, v9
	v_mul_f32_e32 v11, v11, v11
	v_mul_f32_e32 v26, v21, v21
	v_fmac_f32_e32 v13, v12, v12
	v_fmac_f32_e32 v15, v14, v14
	v_fmac_f32_e32 v24, v4, v4
	v_fmac_f32_e32 v25, v6, v6
	v_mul_f32_e32 v27, v23, v23
	v_fmac_f32_e32 v9, v8, v8
	v_fmac_f32_e32 v11, v10, v10
	v_fmac_f32_e32 v26, v20, v20
	v_add_f32_e32 v8, v13, v15
	v_add_f32_e32 v10, v24, v25
	v_fmac_f32_e32 v27, v22, v22
	v_add_f32_e32 v8, v9, v8
	v_add_f32_e32 v9, v26, v10
	v_add_f32_e32 v8, v11, v8
	v_add_f32_e32 v9, v27, v9
	v_add_f32_e32 v10, v8, v9
	ds_bpermute_b32 v11, v207, v10
	v_lshl_add_u64 v[8:9], s[14:15], 0, v[18:19]
	v_lshl_add_u64 v[8:9], v[140:141], 1, v[8:9]
	global_store_dwordx4 v[8:9], v[0:3], off
	s_waitcnt lgkmcnt(0)
	s_nop 0
	v_add_f32_e32 v0, v10, v11
	ds_bpermute_b32 v1, v208, v0
	v_cvt_pk_bf16_f32 v2, v4, v5
	v_cvt_pk_bf16_f32 v3, v6, v7
	v_cvt_pk_bf16_f32 v4, v20, v21
	v_cvt_pk_bf16_f32 v5, v22, v23
	global_store_dwordx4 v[8:9], v[2:5], off offset:256
	s_and_saveexec_b64 s[4:5], s[2:3]
	s_cbranch_execz .LBB0_2520
	s_waitcnt lgkmcnt(0)
	v_add_f32_e32 v0, v0, v1
	v_mul_f32_e32 v0, 0x49800000, v0
	v_trunc_f32_e32 v0, v0
	v_mul_f32_e32 v1, 0x2f800000, v0
	v_floor_f32_e32 v1, v1
	v_fmac_f32_e32 v0, 0xcf800000, v1
	v_cvt_u32_f32_e32 v0, v0
	v_cvt_u32_f32_e32 v1, v1
	v_lshlrev_b64 v[2:3], 5, v[16:17]
	v_lshl_add_u64 v[2:3], s[28:29], 0, v[2:3]
	v_lshl_add_u64 v[2:3], s[0:1], 3, v[2:3]
	global_atomic_add_x2 v[2:3], v[0:1], off

; DI unsigned pk2(float lo, float hi) { f32x2 v = {lo, hi}; bf16x2_t b = __builtin_convertvector(v, bf16x2_t); return __builtin_bit_cast(unsigned, b); }
; DI float rstd_of(float ssq, float inv_n) { return 1.0f / sqrtf(ssq * inv_n + EPS); }
; DI void acc_add(acc_t* p, float v, float scale) { atomicAdd(p, (acc_t)(v * scale)); }
; DI float acc_get(const acc_t* p, float inv_scale) { return (float)(*p) * inv_scale; }
;     DI void operator()(const f32x4 (&acc)[2][2][4][2], const Unit& u, int wr, int wc, int fr, int fq) const {
;         const int colb = u.pn * BM + wc * 32 + 8 * fq;
;         EPI_ROWS_BEGIN
;             const float rs = rstd_of(acc_get(ssqq + (size_t)row * 4 + u.pn, 1.0f / SSQ_SCALE), 1.0f / 256.f) * XSCALE; float ss = 0.f;
; #pragma unroll
;             for (int bj = 0; bj < 2; ++bj) { const int col = colb + bj * HALF; f32x4 v0 = acc[ai][bj][m][0] * rs, v1 = acc[ai][bj][m][1] * rs;
; #pragma unroll
;                 for (int j = 0; j < 4; ++j) { v0[j] = __builtin_amdgcn_exp2f(v0[j]); v1[j] = __builtin_amdgcn_exp2f(v1[j]); }
;                 u32x4 w; w.x = pk2(v0[0], v0[1]); w.y = pk2(v0[2], v0[3]); w.z = pk2(v1[0], v1[1]); w.w = pk2(v1[2], v1[3]); *(u32x4*)(P + (size_t)row * DM + col) = w;
;                 ss += (v0[0] + v0[1]) + (v0[2] + v0[3]) + (v1[0] + v1[1]) + (v1[2] + v1[3]); }
;             ss += __shfl_xor(ss, 16); ss += __shfl_xor(ss, 32);
;             if (fq == 0) acc_add(lsum + (size_t)row * 4 + u.pn, ss, LS_SCALE);
;         EPI_ROWS_END
.LBB0_2796:
	v_lshl_add_u32 v138, s4, 8, v141
	v_ashrrev_i32_e32 v139, 31, v138
	v_lshlrev_b64 v[146:147], 5, v[138:139]
	v_lshl_add_u64 v[146:147], s[14:15], 0, v[146:147]
	v_lshl_add_u64 v[146:147], s[6:7], 3, v[146:147]
	v_mov_b32_e32 v190, 0x1000
	v_mov_b32_e32 v191, 0
	v_lshl_add_u64 v[192:193], v[190:191], 0, v[146:147]
	global_load_dwordx2 v[174:175], v[146:147], off
	global_load_dwordx2 v[176:177], v[146:147], off offset:512
	global_load_dwordx2 v[178:179], v[146:147], off offset:1024
	global_load_dwordx2 v[180:181], v[146:147], off offset:1536
	global_load_dwordx2 v[182:183], v[192:193], off
	global_load_dwordx2 v[184:185], v[192:193], off offset:512
	global_load_dwordx2 v[186:187], v[192:193], off offset:1024
	global_load_dwordx2 v[188:189], v[192:193], off offset:1536
	v_lshl_or_b32 v148, s6, 8, v143
	s_waitcnt vmcnt(0)
	v_mov_b64_e32 v[146:147], v[174:175]
	v_ffbh_u32_e32 v96, v147
	v_min_u32_e32 v96, 32, v96
	v_lshlrev_b64 v[146:147], v96, v[146:147]
	v_min_u32_e32 v145, 1, v146
	v_or_b32_e32 v145, v147, v145
	v_cvt_f32_u32_e32 v145, v145
	v_sub_u32_e32 v96, 32, v96
	v_lshlrev_b64 v[146:147], 11, v[138:139]
	v_lshl_add_u64 v[146:147], s[10:11], 0, v[146:147]
	v_ldexp_f32 v96, v145, v96
	v_mul_f32_e32 v96, 0x35800000, v96
	v_fmamk_f32 v96, v96, 0x3b800000, v222
	s_nop 7
	v_rsq_f32_e32 v149, v96
	s_nop 0
	v_mul_f32_e32 v145, v96, v149
	v_fma_f32 v145, -v145, v149, 1.0
	v_mul_f32_e32 v145, 0.5, v145
	v_fma_f32 v96, v145, v149, v149
	v_mul_f32_e32 v96, 0x3db8aa3b, v96
	v_pk_mul_f32 v[128:129], v[128:129], v[96:97] op_sel_hi:[1,0]
	v_pk_mul_f32 v[126:127], v[126:127], v[96:97] op_sel_hi:[1,0]
	v_pk_mul_f32 v[124:125], v[124:125], v[96:97] op_sel_hi:[1,0]
	v_pk_mul_f32 v[122:123], v[122:123], v[96:97] op_sel_hi:[1,0]
	v_pk_mul_f32 v[120:121], v[120:121], v[96:97] op_sel_hi:[1,0]
	v_pk_mul_f32 v[118:119], v[118:119], v[96:97] op_sel_hi:[1,0]
	v_pk_mul_f32 v[116:117], v[116:117], v[96:97] op_sel_hi:[1,0]
	v_pk_mul_f32 v[114:115], v[114:115], v[96:97] op_sel_hi:[1,0]
	v_exp_f32_e32 v96, v126
	v_exp_f32_e32 v126, v127
	v_exp_f32_e32 v127, v128
	v_exp_f32_e32 v128, v129
	v_exp_f32_e32 v122, v122
	v_exp_f32_e32 v123, v123
	v_exp_f32_e32 v124, v124
	v_exp_f32_e32 v125, v125
	v_exp_f32_e32 v118, v118
	v_exp_f32_e32 v119, v119
	v_exp_f32_e32 v149, v120
	v_exp_f32_e32 v151, v121
	v_exp_f32_e32 v129, v114
	v_exp_f32_e32 v145, v115
	v_exp_f32_e32 v150, v116
	v_exp_f32_e32 v152, v117
	v_cvt_pk_bf16_f32 v114, v96, v126
	v_add_f32_e32 v96, v96, v126
	v_add_f32_e32 v120, v127, v128
	v_cvt_pk_bf16_f32 v116, v122, v123
	v_cvt_pk_bf16_f32 v117, v124, v125
	v_add_f32_e32 v121, v122, v123
	v_add_f32_e32 v122, v124, v125
	v_add_f32_e32 v123, v118, v119
	v_add_f32_e32 v124, v149, v151
	v_add_f32_e32 v96, v96, v120
	v_add_f32_e32 v125, v129, v145
	v_add_f32_e32 v120, v123, v124
	v_add_f32_e32 v96, v121, v96
	v_add_f32_e32 v126, v150, v152
	v_add_f32_e32 v120, v125, v120
	v_add_f32_e32 v96, v122, v96
	v_add_f32_e32 v96, 0, v96
	v_add_f32_e32 v120, v126, v120
	v_add_f32_e32 v122, v120, v96
	ds_bpermute_b32 v123, v207, v122
	v_lshlrev_b32_e32 v96, 1, v148
	v_cvt_pk_bf16_f32 v115, v127, v128
	v_lshl_add_u64 v[120:121], v[146:147], 0, v[96:97]
	global_store_dwordx4 v[120:121], v[114:117], off
	s_waitcnt lgkmcnt(0)
	s_nop 0
	v_add_f32_e32 v114, v122, v123
	ds_bpermute_b32 v115, v208, v114
	v_cvt_pk_bf16_f32 v116, v118, v119
	v_cvt_pk_bf16_f32 v117, v149, v151
	v_cvt_pk_bf16_f32 v118, v129, v145
	v_cvt_pk_bf16_f32 v119, v150, v152
	global_store_dwordx4 v[120:121], v[116:119], off offset:256
	s_and_saveexec_b64 s[4:5], s[2:3]
	s_cbranch_execz .LBB0_2798
	s_waitcnt lgkmcnt(0)
	v_add_f32_e32 v114, v114, v115
	v_mul_f32_e32 v114, 0x4b800000, v114
	v_trunc_f32_e32 v114, v114
	v_mul_f32_e32 v115, 0x2f800000, v114
	v_floor_f32_e32 v115, v115
	v_fmac_f32_e32 v114, 0xcf800000, v115
	v_cvt_u32_f32_e32 v114, v114
	v_cvt_u32_f32_e32 v115, v115
	v_lshlrev_b64 v[116:117], 2, v[138:139]
	v_lshl_add_u64 v[116:117], v[116:117], 3, s[28:29]
	v_lshl_add_u64 v[116:117], s[6:7], 3, v[116:117]
	global_atomic_add_x2 v[116:117], v[114:115], off
.LBB0_2798:
	s_or_b64 exec, exec, s[4:5]
	v_or_b32_e32 v114, 16, v138
	s_waitcnt lgkmcnt(0)
	v_ashrrev_i32_e32 v115, 31, v114
	v_lshlrev_b64 v[116:117], 5, v[114:115]
	v_lshl_add_u64 v[116:117], s[14:15], 0, v[116:117]
	v_lshl_add_u64 v[116:117], s[6:7], 3, v[116:117]
	s_nop 1
	v_mov_b64_e32 v[116:117], v[176:177]
	v_ffbh_u32_e32 v118, v117
	v_min_u32_e32 v118, 32, v118
	v_lshlrev_b64 v[116:117], v118, v[116:117]
	v_min_u32_e32 v116, 1, v116
	v_or_b32_e32 v116, v117, v116
	v_cvt_f32_u32_e32 v116, v116
	v_sub_u32_e32 v117, 32, v118
	v_ldexp_f32 v116, v116, v117
	v_mul_f32_e32 v116, 0x35800000, v116
	v_fmamk_f32 v116, v116, 0x3b800000, v222
	v_rsq_f32_e32 v118, v116
	s_nop 0
	v_mul_f32_e32 v117, v116, v118
	v_fma_f32 v117, -v117, v118, 1.0
	v_mul_f32_e32 v117, 0.5, v117
	v_fmac_f32_e32 v118, v117, v118
	v_lshlrev_b64 v[116:117], 11, v[114:115]
	v_mul_f32_e32 v118, 0x3db8aa3b, v118
	v_pk_mul_f32 v[112:113], v[112:113], v[118:119] op_sel_hi:[1,0]
	v_pk_mul_f32 v[110:111], v[110:111], v[118:119] op_sel_hi:[1,0]
	v_pk_mul_f32 v[106:107], v[106:107], v[118:119] op_sel_hi:[1,0]
	v_pk_mul_f32 v[104:105], v[104:105], v[118:119] op_sel_hi:[1,0]
	v_pk_mul_f32 v[102:103], v[102:103], v[118:119] op_sel_hi:[1,0]
	v_exp_f32_e32 v110, v110
	v_exp_f32_e32 v111, v111
	v_exp_f32_e32 v112, v112
	v_exp_f32_e32 v113, v113
	v_pk_mul_f32 v[108:109], v[108:109], v[118:119] op_sel_hi:[1,0]
	v_pk_mul_f32 v[100:101], v[100:101], v[118:119] op_sel_hi:[1,0]
	v_pk_mul_f32 v[98:99], v[98:99], v[118:119] op_sel_hi:[1,0]
	v_exp_f32_e32 v106, v106
	v_exp_f32_e32 v107, v107
	v_exp_f32_e32 v118, v102
	v_exp_f32_e32 v120, v103
	v_exp_f32_e32 v122, v104
	v_exp_f32_e32 v124, v105
	v_exp_f32_e32 v108, v108
	v_exp_f32_e32 v109, v109
	v_exp_f32_e32 v119, v98
	v_exp_f32_e32 v121, v99
	v_exp_f32_e32 v123, v100
	v_exp_f32_e32 v125, v101
	v_add_f32_e32 v102, v110, v111
	v_add_f32_e32 v103, v112, v113
	v_cvt_pk_bf16_f32 v100, v106, v107
	v_add_f32_e32 v104, v106, v107
	v_add_f32_e32 v106, v118, v120
	v_add_f32_e32 v107, v122, v124
	v_add_f32_e32 v102, v102, v103
	v_cvt_pk_bf16_f32 v101, v108, v109
	v_add_f32_e32 v105, v108, v109
	v_add_f32_e32 v108, v119, v121
	v_add_f32_e32 v103, v106, v107
	v_add_f32_e32 v102, v104, v102
	v_add_f32_e32 v109, v123, v125
	v_add_f32_e32 v103, v108, v103
	v_add_f32_e32 v102, v105, v102
	v_add_f32_e32 v102, 0, v102
	v_add_f32_e32 v103, v109, v103
	v_add_f32_e32 v106, v103, v102
	ds_bpermute_b32 v107, v207, v106
	v_lshl_add_u64 v[102:103], s[10:11], 0, v[116:117]
	v_cvt_pk_bf16_f32 v98, v110, v111
	v_cvt_pk_bf16_f32 v99, v112, v113
	v_lshl_add_u64 v[104:105], v[102:103], 0, v[96:97]
	global_store_dwordx4 v[104:105], v[98:101], off
	v_cvt_pk_bf16_f32 v102, v119, v121
	v_cvt_pk_bf16_f32 v103, v123, v125
	s_waitcnt lgkmcnt(0)
; DI unsigned pk2(float lo, float hi) { f32x2 v = {lo, hi}; bf16x2_t b = __builtin_convertvector(v, bf16x2_t); return __builtin_bit_cast(unsigned, b); }
; DI float rstd_of(float ssq, float inv_n) { return 1.0f / sqrtf(ssq * inv_n + EPS); }
; DI void acc_add(acc_t* p, float v, float scale) { atomicAdd(p, (acc_t)(v * scale)); }
; DI float acc_get(const acc_t* p, float inv_scale) { return (float)(*p) * inv_scale; }
;     DI void operator()(const f32x4 (&acc)[2][2][4][2], const Unit& u, int wr, int wc, int fr, int fq) const {
;         const int colb = u.pn * BM + wc * 32 + 8 * fq;
;         EPI_ROWS_BEGIN
;             const float rs = rstd_of(acc_get(ssqq + (size_t)row * 4 + u.pn, 1.0f / SSQ_SCALE), 1.0f / 256.f) * XSCALE; float ss = 0.f;
; #pragma unroll
;             for (int bj = 0; bj < 2; ++bj) { const int col = colb + bj * HALF; f32x4 v0 = acc[ai][bj][m][0] * rs, v1 = acc[ai][bj][m][1] * rs;
; #pragma unroll
;                 for (int j = 0; j < 4; ++j) { v0[j] = __builtin_amdgcn_exp2f(v0[j]); v1[j] = __builtin_amdgcn_exp2f(v1[j]); }
;                 u32x4 w; w.x = pk2(v0[0], v0[1]); w.y = pk2(v0[2], v0[3]); w.z = pk2(v1[0], v1[1]); w.w = pk2(v1[2], v1[3]); *(u32x4*)(P + (size_t)row * DM + col) = w;
;                 ss += (v0[0] + v0[1]) + (v0[2] + v0[3]) + (v1[0] + v1[1]) + (v1[2] + v1[3]); }
;             ss += __shfl_xor(ss, 16); ss += __shfl_xor(ss, 32);
;             if (fq == 0) acc_add(lsum + (size_t)row * 4 + u.pn, ss, LS_SCALE);
;         EPI_ROWS_END
	v_add_f32_e32 v98, v106, v107
	ds_bpermute_b32 v99, v208, v98
	v_cvt_pk_bf16_f32 v100, v118, v120
	v_cvt_pk_bf16_f32 v101, v122, v124
	global_store_dwordx4 v[104:105], v[100:103], off offset:256
	s_and_saveexec_b64 s[4:5], s[2:3]
	s_cbranch_execz .LBB0_2800
	s_waitcnt lgkmcnt(0)
	v_add_f32_e32 v98, v98, v99
	v_mul_f32_e32 v98, 0x4b800000, v98
	v_trunc_f32_e32 v98, v98
	v_mul_f32_e32 v99, 0x2f800000, v98
	v_floor_f32_e32 v99, v99
	v_fmac_f32_e32 v98, 0xcf800000, v99
	v_cvt_u32_f32_e32 v98, v98
	v_cvt_u32_f32_e32 v99, v99
	v_lshlrev_b64 v[100:101], 2, v[114:115]
	v_lshl_add_u64 v[100:101], v[100:101], 3, s[28:29]
	v_lshl_add_u64 v[100:101], s[6:7], 3, v[100:101]
	global_atomic_add_x2 v[100:101], v[98:99], off
.LBB0_2800:
	s_or_b64 exec, exec, s[4:5]
	v_or_b32_e32 v98, 32, v138
	s_waitcnt lgkmcnt(0)
	v_ashrrev_i32_e32 v99, 31, v98
	v_lshlrev_b64 v[100:101], 5, v[98:99]
	v_lshl_add_u64 v[100:101], s[14:15], 0, v[100:101]
	v_lshl_add_u64 v[100:101], s[6:7], 3, v[100:101]
	s_nop 1
	v_mov_b64_e32 v[100:101], v[178:179]
	v_ffbh_u32_e32 v102, v101
	v_min_u32_e32 v102, 32, v102
	v_lshlrev_b64 v[100:101], v102, v[100:101]
	v_min_u32_e32 v100, 1, v100
	v_or_b32_e32 v100, v101, v100
	v_cvt_f32_u32_e32 v100, v100
	v_sub_u32_e32 v101, 32, v102
	v_ldexp_f32 v100, v100, v101
	v_mul_f32_e32 v100, 0x35800000, v100
	v_fmamk_f32 v100, v100, 0x3b800000, v222
	v_rsq_f32_e32 v102, v100
	s_nop 0
	v_mul_f32_e32 v101, v100, v102
	v_fma_f32 v101, -v101, v102, 1.0
	v_mul_f32_e32 v101, 0.5, v101
	v_fmac_f32_e32 v102, v101, v102
	v_lshlrev_b64 v[100:101], 11, v[98:99]
	v_mul_f32_e32 v102, 0x3db8aa3b, v102
	v_pk_mul_f32 v[94:95], v[94:95], v[102:103] op_sel_hi:[1,0]
	v_pk_mul_f32 v[92:93], v[92:93], v[102:103] op_sel_hi:[1,0]
	v_pk_mul_f32 v[88:89], v[88:89], v[102:103] op_sel_hi:[1,0]
	v_pk_mul_f32 v[86:87], v[86:87], v[102:103] op_sel_hi:[1,0]
	v_pk_mul_f32 v[84:85], v[84:85], v[102:103] op_sel_hi:[1,0]
	v_exp_f32_e32 v92, v92
	v_exp_f32_e32 v93, v93
	v_exp_f32_e32 v94, v94
	v_exp_f32_e32 v95, v95
	v_pk_mul_f32 v[90:91], v[90:91], v[102:103] op_sel_hi:[1,0]
	v_pk_mul_f32 v[82:83], v[82:83], v[102:103] op_sel_hi:[1,0]
	v_pk_mul_f32 v[80:81], v[80:81], v[102:103] op_sel_hi:[1,0]
	v_exp_f32_e32 v88, v88
	v_exp_f32_e32 v89, v89
	v_exp_f32_e32 v102, v84
	v_exp_f32_e32 v104, v85
	v_exp_f32_e32 v106, v86
	v_exp_f32_e32 v108, v87
	v_exp_f32_e32 v90, v90
	v_exp_f32_e32 v91, v91
	v_exp_f32_e32 v103, v80
	v_exp_f32_e32 v105, v81
	v_exp_f32_e32 v107, v82
	v_exp_f32_e32 v109, v83
	v_add_f32_e32 v84, v92, v93
	v_add_f32_e32 v85, v94, v95
	v_cvt_pk_bf16_f32 v82, v88, v89
	v_add_f32_e32 v86, v88, v89
	v_add_f32_e32 v88, v102, v104
	v_add_f32_e32 v89, v106, v108
	v_add_f32_e32 v84, v84, v85
	v_cvt_pk_bf16_f32 v83, v90, v91
	v_add_f32_e32 v87, v90, v91
	v_add_f32_e32 v90, v103, v105
	v_add_f32_e32 v85, v88, v89
	v_add_f32_e32 v84, v86, v84
	v_add_f32_e32 v91, v107, v109
	v_add_f32_e32 v85, v90, v85
	v_add_f32_e32 v84, v87, v84
	v_add_f32_e32 v84, 0, v84
	v_add_f32_e32 v85, v91, v85
	v_add_f32_e32 v88, v85, v84
	ds_bpermute_b32 v89, v207, v88
	v_lshl_add_u64 v[84:85], s[10:11], 0, v[100:101]
	v_cvt_pk_bf16_f32 v80, v92, v93
	v_cvt_pk_bf16_f32 v81, v94, v95
	v_lshl_add_u64 v[86:87], v[84:85], 0, v[96:97]
	global_store_dwordx4 v[86:87], v[80:83], off
	v_cvt_pk_bf16_f32 v84, v103, v105
	v_cvt_pk_bf16_f32 v85, v107, v109
	s_waitcnt lgkmcnt(0)
	v_add_f32_e32 v80, v88, v89
	ds_bpermute_b32 v81, v208, v80
	v_cvt_pk_bf16_f32 v82, v102, v104
	v_cvt_pk_bf16_f32 v83, v106, v108
	global_store_dwordx4 v[86:87], v[82:85], off offset:256
	s_and_saveexec_b64 s[4:5], s[2:3]
	v_readlane_b32 s80, v255, 34
	v_readlane_b32 s79, v255, 24
	s_movk_i32 s89, 0x1000
	s_movk_i32 s90, 0xb00
	s_movk_i32 s84, 0x2c00
	s_mov_b64 s[82:83], 0x2c00
	v_readlane_b32 s81, v255, 35
	s_cbranch_execz .LBB0_2802
	s_waitcnt lgkmcnt(0)
	v_add_f32_e32 v80, v80, v81
	v_mul_f32_e32 v80, 0x4b800000, v80
	v_trunc_f32_e32 v80, v80
	v_mul_f32_e32 v81, 0x2f800000, v80
	v_floor_f32_e32 v81, v81
	v_fmac_f32_e32 v80, 0xcf800000, v81
	v_cvt_u32_f32_e32 v80, v80
	v_cvt_u32_f32_e32 v81, v81
	v_lshlrev_b64 v[82:83], 2, v[98:99]
	v_lshl_add_u64 v[82:83], v[82:83], 3, s[28:29]
	v_lshl_add_u64 v[82:83], s[6:7], 3, v[82:83]
	global_atomic_add_x2 v[82:83], v[80:81], off
; DI unsigned pk2(float lo, float hi) { f32x2 v = {lo, hi}; bf16x2_t b = __builtin_convertvector(v, bf16x2_t); return __builtin_bit_cast(unsigned, b); }
; DI float rstd_of(float ssq, float inv_n) { return 1.0f / sqrtf(ssq * inv_n + EPS); }
; DI void acc_add(acc_t* p, float v, float scale) { atomicAdd(p, (acc_t)(v * scale)); }
; DI float acc_get(const acc_t* p, float inv_scale) { return (float)(*p) * inv_scale; }
;     DI void operator()(const f32x4 (&acc)[2][2][4][2], const Unit& u, int wr, int wc, int fr, int fq) const {
;         const int colb = u.pn * BM + wc * 32 + 8 * fq;
;         EPI_ROWS_BEGIN
;             const float rs = rstd_of(acc_get(ssqq + (size_t)row * 4 + u.pn, 1.0f / SSQ_SCALE), 1.0f / 256.f) * XSCALE; float ss = 0.f;
; #pragma unroll
;             for (int bj = 0; bj < 2; ++bj) { const int col = colb + bj * HALF; f32x4 v0 = acc[ai][bj][m][0] * rs, v1 = acc[ai][bj][m][1] * rs;
; #pragma unroll
;                 for (int j = 0; j < 4; ++j) { v0[j] = __builtin_amdgcn_exp2f(v0[j]); v1[j] = __builtin_amdgcn_exp2f(v1[j]); }
;                 u32x4 w; w.x = pk2(v0[0], v0[1]); w.y = pk2(v0[2], v0[3]); w.z = pk2(v1[0], v1[1]); w.w = pk2(v1[2], v1[3]); *(u32x4*)(P + (size_t)row * DM + col) = w;
;                 ss += (v0[0] + v0[1]) + (v0[2] + v0[3]) + (v1[0] + v1[1]) + (v1[2] + v1[3]); }
;             ss += __shfl_xor(ss, 16); ss += __shfl_xor(ss, 32);
;             if (fq == 0) acc_add(lsum + (size_t)row * 4 + u.pn, ss, LS_SCALE);
;         EPI_ROWS_END
.LBB0_2802:
	s_or_b64 exec, exec, s[4:5]
	v_or_b32_e32 v80, 48, v138
	s_waitcnt lgkmcnt(0)
	v_ashrrev_i32_e32 v81, 31, v80
	v_lshlrev_b64 v[82:83], 5, v[80:81]
	v_lshl_add_u64 v[82:83], s[14:15], 0, v[82:83]
	v_lshl_add_u64 v[82:83], s[6:7], 3, v[82:83]
	s_nop 1
	v_mov_b64_e32 v[82:83], v[180:181]
	v_ffbh_u32_e32 v84, v83
	v_min_u32_e32 v84, 32, v84
	v_lshlrev_b64 v[82:83], v84, v[82:83]
	v_min_u32_e32 v82, 1, v82
	v_or_b32_e32 v82, v83, v82
	v_cvt_f32_u32_e32 v82, v82
	v_sub_u32_e32 v83, 32, v84
	v_ldexp_f32 v82, v82, v83
	v_mul_f32_e32 v82, 0x35800000, v82
	v_fmamk_f32 v82, v82, 0x3b800000, v222
	v_rsq_f32_e32 v84, v82
	s_nop 0
	v_mul_f32_e32 v83, v82, v84
	v_fma_f32 v83, -v83, v84, 1.0
	v_mul_f32_e32 v83, 0.5, v83
	v_fmac_f32_e32 v84, v83, v84
	v_lshlrev_b64 v[82:83], 11, v[80:81]
	v_mul_f32_e32 v84, 0x3db8aa3b, v84
	v_pk_mul_f32 v[78:79], v[78:79], v[84:85] op_sel_hi:[1,0]
	v_pk_mul_f32 v[76:77], v[76:77], v[84:85] op_sel_hi:[1,0]
	v_pk_mul_f32 v[72:73], v[72:73], v[84:85] op_sel_hi:[1,0]
	v_pk_mul_f32 v[70:71], v[70:71], v[84:85] op_sel_hi:[1,0]
	v_pk_mul_f32 v[68:69], v[68:69], v[84:85] op_sel_hi:[1,0]
	v_exp_f32_e32 v76, v76
	v_exp_f32_e32 v77, v77
	v_exp_f32_e32 v78, v78
	v_exp_f32_e32 v79, v79
	v_pk_mul_f32 v[74:75], v[74:75], v[84:85] op_sel_hi:[1,0]
	v_pk_mul_f32 v[66:67], v[66:67], v[84:85] op_sel_hi:[1,0]
	v_pk_mul_f32 v[64:65], v[64:65], v[84:85] op_sel_hi:[1,0]
	v_exp_f32_e32 v72, v72
	v_exp_f32_e32 v73, v73
	v_exp_f32_e32 v84, v68
	v_exp_f32_e32 v86, v69
	v_exp_f32_e32 v88, v70
	v_exp_f32_e32 v90, v71
	v_exp_f32_e32 v74, v74
	v_exp_f32_e32 v75, v75
	v_exp_f32_e32 v85, v64
	v_exp_f32_e32 v87, v65
	v_exp_f32_e32 v89, v66
	v_exp_f32_e32 v91, v67
	v_add_f32_e32 v68, v76, v77
	v_add_f32_e32 v69, v78, v79
	v_cvt_pk_bf16_f32 v66, v72, v73
	v_add_f32_e32 v70, v72, v73
	v_add_f32_e32 v72, v84, v86
	v_add_f32_e32 v73, v88, v90
	v_add_f32_e32 v68, v68, v69
	v_cvt_pk_bf16_f32 v67, v74, v75
	v_add_f32_e32 v71, v74, v75
	v_add_f32_e32 v74, v85, v87
	v_add_f32_e32 v69, v72, v73
	v_add_f32_e32 v68, v70, v68
	v_add_f32_e32 v75, v89, v91
	v_add_f32_e32 v69, v74, v69
	v_add_f32_e32 v68, v71, v68
	v_add_f32_e32 v68, 0, v68
	v_add_f32_e32 v69, v75, v69
	v_add_f32_e32 v72, v69, v68
	ds_bpermute_b32 v73, v207, v72
	v_lshl_add_u64 v[68:69], s[10:11], 0, v[82:83]
	v_cvt_pk_bf16_f32 v64, v76, v77
	v_cvt_pk_bf16_f32 v65, v78, v79
	v_lshl_add_u64 v[70:71], v[68:69], 0, v[96:97]
	global_store_dwordx4 v[70:71], v[64:67], off
	v_cvt_pk_bf16_f32 v68, v85, v87
	v_cvt_pk_bf16_f32 v69, v89, v91
	s_waitcnt lgkmcnt(0)
	v_add_f32_e32 v64, v72, v73
	ds_bpermute_b32 v65, v208, v64
	v_cvt_pk_bf16_f32 v66, v84, v86
	v_cvt_pk_bf16_f32 v67, v88, v90
	global_store_dwordx4 v[70:71], v[66:69], off offset:256
	s_and_saveexec_b64 s[4:5], s[2:3]
	s_cbranch_execz .LBB0_2804
	s_waitcnt lgkmcnt(0)
	v_add_f32_e32 v64, v64, v65
	v_mul_f32_e32 v64, 0x4b800000, v64
	v_trunc_f32_e32 v64, v64
	v_mul_f32_e32 v65, 0x2f800000, v64
	v_floor_f32_e32 v65, v65
	v_fmac_f32_e32 v64, 0xcf800000, v65
	v_cvt_u32_f32_e32 v64, v64
	v_cvt_u32_f32_e32 v65, v65
	v_lshlrev_b64 v[66:67], 2, v[80:81]
	v_lshl_add_u64 v[66:67], v[66:67], 3, s[28:29]
	v_lshl_add_u64 v[66:67], s[6:7], 3, v[66:67]
	global_atomic_add_x2 v[66:67], v[64:65], off
.LBB0_2804:
	s_or_b64 exec, exec, s[4:5]
	v_add_u32_e32 v64, 0x80, v138
	s_waitcnt lgkmcnt(0)
	v_ashrrev_i32_e32 v65, 31, v64
	v_lshlrev_b64 v[66:67], 5, v[64:65]
	v_lshl_add_u64 v[66:67], s[14:15], 0, v[66:67]
	v_lshl_add_u64 v[66:67], s[6:7], 3, v[66:67]
	s_nop 1
	v_mov_b64_e32 v[66:67], v[182:183]
	v_ffbh_u32_e32 v68, v67
	v_min_u32_e32 v68, 32, v68
	v_lshlrev_b64 v[66:67], v68, v[66:67]
	v_min_u32_e32 v66, 1, v66
	v_or_b32_e32 v66, v67, v66
	v_cvt_f32_u32_e32 v66, v66
	v_sub_u32_e32 v67, 32, v68
	v_ldexp_f32 v66, v66, v67
	v_mul_f32_e32 v66, 0x35800000, v66
	v_fmamk_f32 v66, v66, 0x3b800000, v222
	v_rsq_f32_e32 v68, v66
	s_nop 0
	v_mul_f32_e32 v67, v66, v68
	v_fma_f32 v67, -v67, v68, 1.0
	v_mul_f32_e32 v67, 0.5, v67
	v_fmac_f32_e32 v68, v67, v68
	v_lshlrev_b64 v[66:67], 11, v[64:65]
	v_mul_f32_e32 v68, 0x3db8aa3b, v68
	v_pk_mul_f32 v[62:63], v[62:63], v[68:69] op_sel_hi:[1,0]
	v_pk_mul_f32 v[60:61], v[60:61], v[68:69] op_sel_hi:[1,0]
	v_pk_mul_f32 v[56:57], v[56:57], v[68:69] op_sel_hi:[1,0]
	v_pk_mul_f32 v[54:55], v[54:55], v[68:69] op_sel_hi:[1,0]
	v_pk_mul_f32 v[52:53], v[52:53], v[68:69] op_sel_hi:[1,0]
	v_exp_f32_e32 v60, v60
	v_exp_f32_e32 v61, v61
	v_exp_f32_e32 v62, v62
	v_exp_f32_e32 v63, v63
	v_pk_mul_f32 v[58:59], v[58:59], v[68:69] op_sel_hi:[1,0]
	v_pk_mul_f32 v[50:51], v[50:51], v[68:69] op_sel_hi:[1,0]
	v_pk_mul_f32 v[48:49], v[48:49], v[68:69] op_sel_hi:[1,0]
	v_exp_f32_e32 v56, v56
	v_exp_f32_e32 v57, v57
	v_exp_f32_e32 v68, v52
	v_exp_f32_e32 v70, v53
	v_exp_f32_e32 v72, v54
	v_exp_f32_e32 v74, v55
	v_exp_f32_e32 v58, v58
	v_exp_f32_e32 v59, v59
	v_exp_f32_e32 v69, v48
	v_exp_f32_e32 v71, v49
	v_exp_f32_e32 v73, v50
	v_exp_f32_e32 v75, v51
	v_add_f32_e32 v52, v60, v61
	v_add_f32_e32 v53, v62, v63
	v_cvt_pk_bf16_f32 v50, v56, v57
	v_add_f32_e32 v54, v56, v57
	v_add_f32_e32 v56, v68, v70
	v_add_f32_e32 v57, v72, v74
	v_add_f32_e32 v52, v52, v53
	v_cvt_pk_bf16_f32 v51, v58, v59
	v_add_f32_e32 v55, v58, v59
	v_add_f32_e32 v58, v69, v71
	v_add_f32_e32 v53, v56, v57
	v_add_f32_e32 v52, v54, v52
	v_add_f32_e32 v59, v73, v75
	v_add_f32_e32 v53, v58, v53
	v_add_f32_e32 v52, v55, v52
	v_add_f32_e32 v52, 0, v52
	v_add_f32_e32 v53, v59, v53
	v_add_f32_e32 v56, v53, v52
	ds_bpermute_b32 v57, v207, v56
	v_lshl_add_u64 v[52:53], s[10:11], 0, v[66:67]
	v_cvt_pk_bf16_f32 v48, v60, v61
	v_cvt_pk_bf16_f32 v49, v62, v63
	v_lshl_add_u64 v[54:55], v[52:53], 0, v[96:97]
	global_store_dwordx4 v[54:55], v[48:51], off
	v_cvt_pk_bf16_f32 v52, v69, v71
	v_cvt_pk_bf16_f32 v53, v73, v75
	s_waitcnt lgkmcnt(0)
	v_add_f32_e32 v48, v56, v57
	ds_bpermute_b32 v49, v208, v48
	v_cvt_pk_bf16_f32 v50, v68, v70
	v_cvt_pk_bf16_f32 v51, v72, v74
	global_store_dwordx4 v[54:55], v[50:53], off offset:256
	s_and_saveexec_b64 s[4:5], s[2:3]
	s_cbranch_execz .LBB0_2806
	s_waitcnt lgkmcnt(0)
	v_add_f32_e32 v48, v48, v49
	v_mul_f32_e32 v48, 0x4b800000, v48
	v_trunc_f32_e32 v48, v48
	v_mul_f32_e32 v49, 0x2f800000, v48
	v_floor_f32_e32 v49, v49
	v_fmac_f32_e32 v48, 0xcf800000, v49
	v_cvt_u32_f32_e32 v48, v48
	v_cvt_u32_f32_e32 v49, v49
	v_lshlrev_b64 v[50:51], 2, v[64:65]
	v_lshl_add_u64 v[50:51], v[50:51], 3, s[28:29]
	v_lshl_add_u64 v[50:51], s[6:7], 3, v[50:51]
	global_atomic_add_x2 v[50:51], v[48:49], off
; DI unsigned pk2(float lo, float hi) { f32x2 v = {lo, hi}; bf16x2_t b = __builtin_convertvector(v, bf16x2_t); return __builtin_bit_cast(unsigned, b); }
; DI float rstd_of(float ssq, float inv_n) { return 1.0f / sqrtf(ssq * inv_n + EPS); }
; DI void acc_add(acc_t* p, float v, float scale) { atomicAdd(p, (acc_t)(v * scale)); }
; DI float acc_get(const acc_t* p, float inv_scale) { return (float)(*p) * inv_scale; }
;     DI void operator()(const f32x4 (&acc)[2][2][4][2], const Unit& u, int wr, int wc, int fr, int fq) const {
;         const int colb = u.pn * BM + wc * 32 + 8 * fq;
;         EPI_ROWS_BEGIN
;             const float rs = rstd_of(acc_get(ssqq + (size_t)row * 4 + u.pn, 1.0f / SSQ_SCALE), 1.0f / 256.f) * XSCALE; float ss = 0.f;
; #pragma unroll
;             for (int bj = 0; bj < 2; ++bj) { const int col = colb + bj * HALF; f32x4 v0 = acc[ai][bj][m][0] * rs, v1 = acc[ai][bj][m][1] * rs;
; #pragma unroll
;                 for (int j = 0; j < 4; ++j) { v0[j] = __builtin_amdgcn_exp2f(v0[j]); v1[j] = __builtin_amdgcn_exp2f(v1[j]); }
;                 u32x4 w; w.x = pk2(v0[0], v0[1]); w.y = pk2(v0[2], v0[3]); w.z = pk2(v1[0], v1[1]); w.w = pk2(v1[2], v1[3]); *(u32x4*)(P + (size_t)row * DM + col) = w;
;                 ss += (v0[0] + v0[1]) + (v0[2] + v0[3]) + (v1[0] + v1[1]) + (v1[2] + v1[3]); }
;             ss += __shfl_xor(ss, 16); ss += __shfl_xor(ss, 32);
;             if (fq == 0) acc_add(lsum + (size_t)row * 4 + u.pn, ss, LS_SCALE);
;         EPI_ROWS_END
.LBB0_2806:
	s_or_b64 exec, exec, s[4:5]
	v_add_u32_e32 v48, 0x90, v138
	s_waitcnt lgkmcnt(0)
	v_ashrrev_i32_e32 v49, 31, v48
	v_lshlrev_b64 v[50:51], 5, v[48:49]
	v_lshl_add_u64 v[50:51], s[14:15], 0, v[50:51]
	v_lshl_add_u64 v[50:51], s[6:7], 3, v[50:51]
	s_nop 1
	v_mov_b64_e32 v[50:51], v[184:185]
	v_ffbh_u32_e32 v52, v51
	v_min_u32_e32 v52, 32, v52
	v_lshlrev_b64 v[50:51], v52, v[50:51]
	v_min_u32_e32 v50, 1, v50
	v_or_b32_e32 v50, v51, v50
	v_cvt_f32_u32_e32 v50, v50
	v_sub_u32_e32 v51, 32, v52
	v_ldexp_f32 v50, v50, v51
	v_mul_f32_e32 v50, 0x35800000, v50
	v_fmamk_f32 v50, v50, 0x3b800000, v222
	v_rsq_f32_e32 v52, v50
	s_nop 0
	v_mul_f32_e32 v51, v50, v52
	v_fma_f32 v51, -v51, v52, 1.0
	v_mul_f32_e32 v51, 0.5, v51
	v_fmac_f32_e32 v52, v51, v52
	v_lshlrev_b64 v[50:51], 11, v[48:49]
	v_mul_f32_e32 v52, 0x3db8aa3b, v52
	v_pk_mul_f32 v[46:47], v[46:47], v[52:53] op_sel_hi:[1,0]
	v_pk_mul_f32 v[44:45], v[44:45], v[52:53] op_sel_hi:[1,0]
	v_pk_mul_f32 v[40:41], v[40:41], v[52:53] op_sel_hi:[1,0]
	v_pk_mul_f32 v[38:39], v[38:39], v[52:53] op_sel_hi:[1,0]
	v_pk_mul_f32 v[36:37], v[36:37], v[52:53] op_sel_hi:[1,0]
	v_exp_f32_e32 v44, v44
	v_exp_f32_e32 v45, v45
	v_exp_f32_e32 v46, v46
	v_exp_f32_e32 v47, v47
	v_pk_mul_f32 v[42:43], v[42:43], v[52:53] op_sel_hi:[1,0]
	v_pk_mul_f32 v[34:35], v[34:35], v[52:53] op_sel_hi:[1,0]
	v_pk_mul_f32 v[32:33], v[32:33], v[52:53] op_sel_hi:[1,0]
	v_exp_f32_e32 v40, v40
	v_exp_f32_e32 v41, v41
	v_exp_f32_e32 v52, v36
	v_exp_f32_e32 v54, v37
	v_exp_f32_e32 v56, v38
	v_exp_f32_e32 v58, v39
	v_exp_f32_e32 v42, v42
	v_exp_f32_e32 v43, v43
	v_exp_f32_e32 v53, v32
	v_exp_f32_e32 v55, v33
	v_exp_f32_e32 v57, v34
	v_exp_f32_e32 v59, v35
	v_add_f32_e32 v36, v44, v45
	v_add_f32_e32 v37, v46, v47
	v_cvt_pk_bf16_f32 v34, v40, v41
	v_add_f32_e32 v38, v40, v41
	v_add_f32_e32 v40, v52, v54
	v_add_f32_e32 v41, v56, v58
	v_add_f32_e32 v36, v36, v37
	v_cvt_pk_bf16_f32 v35, v42, v43
	v_add_f32_e32 v39, v42, v43
	v_add_f32_e32 v42, v53, v55
	v_add_f32_e32 v37, v40, v41
	v_add_f32_e32 v36, v38, v36
	v_add_f32_e32 v43, v57, v59
	v_add_f32_e32 v37, v42, v37
	v_add_f32_e32 v36, v39, v36
	v_add_f32_e32 v36, 0, v36
	v_add_f32_e32 v37, v43, v37
	v_add_f32_e32 v40, v37, v36
	ds_bpermute_b32 v41, v207, v40
	v_lshl_add_u64 v[36:37], s[10:11], 0, v[50:51]
	v_cvt_pk_bf16_f32 v32, v44, v45
	v_cvt_pk_bf16_f32 v33, v46, v47
	v_lshl_add_u64 v[38:39], v[36:37], 0, v[96:97]
	global_store_dwordx4 v[38:39], v[32:35], off
	v_cvt_pk_bf16_f32 v36, v53, v55
	v_cvt_pk_bf16_f32 v37, v57, v59
	s_waitcnt lgkmcnt(0)
	v_add_f32_e32 v32, v40, v41
	ds_bpermute_b32 v33, v208, v32
	v_cvt_pk_bf16_f32 v34, v52, v54
	v_cvt_pk_bf16_f32 v35, v56, v58
	global_store_dwordx4 v[38:39], v[34:37], off offset:256
	s_and_saveexec_b64 s[4:5], s[2:3]
	s_cbranch_execz .LBB0_2808
	s_waitcnt lgkmcnt(0)
	v_add_f32_e32 v32, v32, v33
	v_mul_f32_e32 v32, 0x4b800000, v32
	v_trunc_f32_e32 v32, v32
	v_mul_f32_e32 v33, 0x2f800000, v32
	v_floor_f32_e32 v33, v33
	v_fmac_f32_e32 v32, 0xcf800000, v33
	v_cvt_u32_f32_e32 v32, v32
	v_cvt_u32_f32_e32 v33, v33
	v_lshlrev_b64 v[34:35], 2, v[48:49]
	v_lshl_add_u64 v[34:35], v[34:35], 3, s[28:29]
	v_lshl_add_u64 v[34:35], s[6:7], 3, v[34:35]
	global_atomic_add_x2 v[34:35], v[32:33], off
; DI unsigned pk2(float lo, float hi) { f32x2 v = {lo, hi}; bf16x2_t b = __builtin_convertvector(v, bf16x2_t); return __builtin_bit_cast(unsigned, b); }
; DI float rstd_of(float ssq, float inv_n) { return 1.0f / sqrtf(ssq * inv_n + EPS); }
; DI void acc_add(acc_t* p, float v, float scale) { atomicAdd(p, (acc_t)(v * scale)); }
; DI float acc_get(const acc_t* p, float inv_scale) { return (float)(*p) * inv_scale; }
;     DI void operator()(const f32x4 (&acc)[2][2][4][2], const Unit& u, int wr, int wc, int fr, int fq) const {
;         const int colb = u.pn * BM + wc * 32 + 8 * fq;
;         EPI_ROWS_BEGIN
;             const float rs = rstd_of(acc_get(ssqq + (size_t)row * 4 + u.pn, 1.0f / SSQ_SCALE), 1.0f / 256.f) * XSCALE; float ss = 0.f;
; #pragma unroll
;             for (int bj = 0; bj < 2; ++bj) { const int col = colb + bj * HALF; f32x4 v0 = acc[ai][bj][m][0] * rs, v1 = acc[ai][bj][m][1] * rs;
; #pragma unroll
;                 for (int j = 0; j < 4; ++j) { v0[j] = __builtin_amdgcn_exp2f(v0[j]); v1[j] = __builtin_amdgcn_exp2f(v1[j]); }
;                 u32x4 w; w.x = pk2(v0[0], v0[1]); w.y = pk2(v0[2], v0[3]); w.z = pk2(v1[0], v1[1]); w.w = pk2(v1[2], v1[3]); *(u32x4*)(P + (size_t)row * DM + col) = w;
;                 ss += (v0[0] + v0[1]) + (v0[2] + v0[3]) + (v1[0] + v1[1]) + (v1[2] + v1[3]); }
;             ss += __shfl_xor(ss, 16); ss += __shfl_xor(ss, 32);
;             if (fq == 0) acc_add(lsum + (size_t)row * 4 + u.pn, ss, LS_SCALE);
;         EPI_ROWS_END
.LBB0_2808:
	s_or_b64 exec, exec, s[4:5]
	v_add_u32_e32 v32, 0xa0, v138
	s_waitcnt lgkmcnt(0)
	v_ashrrev_i32_e32 v33, 31, v32
	v_lshlrev_b64 v[34:35], 5, v[32:33]
	v_lshl_add_u64 v[34:35], s[14:15], 0, v[34:35]
	v_lshl_add_u64 v[34:35], s[6:7], 3, v[34:35]
	s_nop 1
	v_mov_b64_e32 v[34:35], v[186:187]
	v_ffbh_u32_e32 v36, v35
	v_min_u32_e32 v36, 32, v36
	v_lshlrev_b64 v[34:35], v36, v[34:35]
	v_min_u32_e32 v34, 1, v34
	v_or_b32_e32 v34, v35, v34
	v_cvt_f32_u32_e32 v34, v34
	v_sub_u32_e32 v35, 32, v36
	v_ldexp_f32 v34, v34, v35
	v_mul_f32_e32 v34, 0x35800000, v34
	v_fmamk_f32 v34, v34, 0x3b800000, v222
	v_rsq_f32_e32 v36, v34
	s_nop 0
	v_mul_f32_e32 v35, v34, v36
	v_fma_f32 v35, -v35, v36, 1.0
	v_mul_f32_e32 v35, 0.5, v35
	v_fmac_f32_e32 v36, v35, v36
	v_lshlrev_b64 v[34:35], 11, v[32:33]
	v_mul_f32_e32 v36, 0x3db8aa3b, v36
	v_pk_mul_f32 v[30:31], v[30:31], v[36:37] op_sel_hi:[1,0]
	v_pk_mul_f32 v[28:29], v[28:29], v[36:37] op_sel_hi:[1,0]
	v_pk_mul_f32 v[24:25], v[24:25], v[36:37] op_sel_hi:[1,0]
	v_pk_mul_f32 v[22:23], v[22:23], v[36:37] op_sel_hi:[1,0]
	v_pk_mul_f32 v[20:21], v[20:21], v[36:37] op_sel_hi:[1,0]
	v_exp_f32_e32 v28, v28
	v_exp_f32_e32 v29, v29
	v_exp_f32_e32 v30, v30
	v_exp_f32_e32 v31, v31
	v_pk_mul_f32 v[26:27], v[26:27], v[36:37] op_sel_hi:[1,0]
	v_pk_mul_f32 v[18:19], v[18:19], v[36:37] op_sel_hi:[1,0]
	v_pk_mul_f32 v[16:17], v[16:17], v[36:37] op_sel_hi:[1,0]
	v_exp_f32_e32 v24, v24
	v_exp_f32_e32 v25, v25
	v_exp_f32_e32 v36, v20
	v_exp_f32_e32 v38, v21
	v_exp_f32_e32 v40, v22
	v_exp_f32_e32 v42, v23
	v_exp_f32_e32 v26, v26
	v_exp_f32_e32 v27, v27
	v_exp_f32_e32 v37, v16
	v_exp_f32_e32 v39, v17
	v_exp_f32_e32 v41, v18
	v_exp_f32_e32 v43, v19
	v_add_f32_e32 v20, v28, v29
	v_add_f32_e32 v21, v30, v31
	v_cvt_pk_bf16_f32 v18, v24, v25
	v_add_f32_e32 v22, v24, v25
	v_add_f32_e32 v24, v36, v38
	v_add_f32_e32 v25, v40, v42
	v_add_f32_e32 v20, v20, v21
	v_cvt_pk_bf16_f32 v19, v26, v27
	v_add_f32_e32 v23, v26, v27
	v_add_f32_e32 v26, v37, v39
	v_add_f32_e32 v21, v24, v25
	v_add_f32_e32 v20, v22, v20
	v_add_f32_e32 v27, v41, v43
	v_add_f32_e32 v21, v26, v21
	v_add_f32_e32 v20, v23, v20
	v_add_f32_e32 v20, 0, v20
	v_add_f32_e32 v21, v27, v21
	v_add_f32_e32 v24, v21, v20
	ds_bpermute_b32 v25, v207, v24
	v_lshl_add_u64 v[20:21], s[10:11], 0, v[34:35]
	v_cvt_pk_bf16_f32 v16, v28, v29
	v_cvt_pk_bf16_f32 v17, v30, v31
	v_lshl_add_u64 v[22:23], v[20:21], 0, v[96:97]
	global_store_dwordx4 v[22:23], v[16:19], off
	v_cvt_pk_bf16_f32 v20, v37, v39
	v_cvt_pk_bf16_f32 v21, v41, v43
	s_waitcnt lgkmcnt(0)
	v_add_f32_e32 v16, v24, v25
	ds_bpermute_b32 v17, v208, v16
	v_cvt_pk_bf16_f32 v18, v36, v38
	v_cvt_pk_bf16_f32 v19, v40, v42
	global_store_dwordx4 v[22:23], v[18:21], off offset:256
	s_and_saveexec_b64 s[4:5], s[2:3]
	s_cbranch_execz .LBB0_2810
	s_waitcnt lgkmcnt(0)
	v_add_f32_e32 v16, v16, v17
	v_mul_f32_e32 v16, 0x4b800000, v16
	v_trunc_f32_e32 v16, v16
	v_mul_f32_e32 v17, 0x2f800000, v16
	v_floor_f32_e32 v17, v17
	v_fmac_f32_e32 v16, 0xcf800000, v17
	v_cvt_u32_f32_e32 v16, v16
	v_cvt_u32_f32_e32 v17, v17
	v_lshlrev_b64 v[18:19], 2, v[32:33]
	v_lshl_add_u64 v[18:19], v[18:19], 3, s[28:29]
	v_lshl_add_u64 v[18:19], s[6:7], 3, v[18:19]
	global_atomic_add_x2 v[18:19], v[16:17], off
.LBB0_2810:
	s_or_b64 exec, exec, s[4:5]
	v_add_u32_e32 v16, 0xb0, v138
	s_waitcnt lgkmcnt(0)
	v_ashrrev_i32_e32 v17, 31, v16
	v_lshlrev_b64 v[18:19], 5, v[16:17]
	v_lshl_add_u64 v[18:19], s[14:15], 0, v[18:19]
	v_lshl_add_u64 v[18:19], s[6:7], 3, v[18:19]
	s_nop 1
	v_mov_b64_e32 v[18:19], v[188:189]
	v_ffbh_u32_e32 v20, v19
	v_min_u32_e32 v20, 32, v20
	v_lshlrev_b64 v[18:19], v20, v[18:19]
	v_min_u32_e32 v18, 1, v18
	v_or_b32_e32 v18, v19, v18
	v_cvt_f32_u32_e32 v18, v18
	v_sub_u32_e32 v19, 32, v20
	v_ldexp_f32 v18, v18, v19
	v_mul_f32_e32 v18, 0x35800000, v18
	v_fmamk_f32 v18, v18, 0x3b800000, v222
	v_rsq_f32_e32 v20, v18
	s_nop 0
	v_mul_f32_e32 v19, v18, v20
	v_fma_f32 v19, -v19, v20, 1.0
	v_mul_f32_e32 v19, 0.5, v19
	v_fmac_f32_e32 v20, v19, v20
	v_lshlrev_b64 v[18:19], 11, v[16:17]
	v_mul_f32_e32 v20, 0x3db8aa3b, v20
	v_pk_mul_f32 v[14:15], v[14:15], v[20:21] op_sel_hi:[1,0]
	v_pk_mul_f32 v[12:13], v[12:13], v[20:21] op_sel_hi:[1,0]
	v_pk_mul_f32 v[8:9], v[8:9], v[20:21] op_sel_hi:[1,0]
	v_pk_mul_f32 v[6:7], v[6:7], v[20:21] op_sel_hi:[1,0]
	v_pk_mul_f32 v[4:5], v[4:5], v[20:21] op_sel_hi:[1,0]
	v_exp_f32_e32 v12, v12
	v_exp_f32_e32 v13, v13
	v_exp_f32_e32 v14, v14
	v_exp_f32_e32 v15, v15
	v_pk_mul_f32 v[10:11], v[10:11], v[20:21] op_sel_hi:[1,0]
	v_pk_mul_f32 v[2:3], v[2:3], v[20:21] op_sel_hi:[1,0]
	v_pk_mul_f32 v[0:1], v[0:1], v[20:21] op_sel_hi:[1,0]
	v_exp_f32_e32 v8, v8
	v_exp_f32_e32 v9, v9
	v_exp_f32_e32 v20, v4
	v_exp_f32_e32 v22, v5
	v_exp_f32_e32 v24, v6
	v_exp_f32_e32 v26, v7
	v_exp_f32_e32 v10, v10
	v_exp_f32_e32 v11, v11
	v_exp_f32_e32 v21, v0
	v_exp_f32_e32 v23, v1
	v_exp_f32_e32 v25, v2
	v_exp_f32_e32 v27, v3
	v_add_f32_e32 v4, v12, v13
	v_add_f32_e32 v5, v14, v15
	v_cvt_pk_bf16_f32 v2, v8, v9
	v_add_f32_e32 v6, v8, v9
	v_add_f32_e32 v8, v20, v22
	v_add_f32_e32 v9, v24, v26
	v_add_f32_e32 v4, v4, v5
	v_cvt_pk_bf16_f32 v3, v10, v11
	v_add_f32_e32 v7, v10, v11
	v_add_f32_e32 v10, v21, v23
	v_add_f32_e32 v5, v8, v9
	v_add_f32_e32 v4, v6, v4
	v_add_f32_e32 v11, v25, v27
	v_add_f32_e32 v5, v10, v5
	v_add_f32_e32 v4, v7, v4
	v_add_f32_e32 v4, 0, v4
	v_add_f32_e32 v5, v11, v5
	v_add_f32_e32 v8, v5, v4
	ds_bpermute_b32 v9, v207, v8
	v_lshl_add_u64 v[4:5], s[10:11], 0, v[18:19]
	v_cvt_pk_bf16_f32 v0, v12, v13
	v_cvt_pk_bf16_f32 v1, v14, v15
	v_lshl_add_u64 v[6:7], v[4:5], 0, v[96:97]
	global_store_dwordx4 v[6:7], v[0:3], off
	v_cvt_pk_bf16_f32 v4, v21, v23
	v_cvt_pk_bf16_f32 v5, v25, v27
	s_waitcnt lgkmcnt(0)
	v_add_f32_e32 v0, v8, v9
	ds_bpermute_b32 v1, v208, v0
	v_cvt_pk_bf16_f32 v2, v20, v22
	v_cvt_pk_bf16_f32 v3, v24, v26
	global_store_dwordx4 v[6:7], v[2:5], off offset:256
	s_and_saveexec_b64 s[4:5], s[2:3]
	s_cbranch_execz .LBB0_2812
	s_waitcnt lgkmcnt(0)
	v_add_f32_e32 v0, v0, v1
	v_mul_f32_e32 v0, 0x4b800000, v0
	v_trunc_f32_e32 v0, v0
	v_mul_f32_e32 v1, 0x2f800000, v0
	v_floor_f32_e32 v1, v1
	v_fmac_f32_e32 v0, 0xcf800000, v1
	v_cvt_u32_f32_e32 v0, v0
	v_cvt_u32_f32_e32 v1, v1
	v_lshlrev_b64 v[2:3], 2, v[16:17]
	v_lshl_add_u64 v[2:3], v[2:3], 3, s[28:29]
	v_lshl_add_u64 v[2:3], s[6:7], 3, v[2:3]
	global_atomic_add_x2 v[2:3], v[0:1], off

; DI unsigned pk2(float lo, float hi) { f32x2 v = {lo, hi}; bf16x2_t b = __builtin_convertvector(v, bf16x2_t); return __builtin_bit_cast(unsigned, b); }
; DI float acc_get(const acc_t* p, float inv_scale) { return (float)(*p) * inv_scale; }
;     DI void operator()(const f32x4 (&acc)[2][2][4][2], const Unit& u, int wr, int wc, int fr, int fq) const {
;         const int colb = u.pn * BM + wc * 32 + 8 * fq;
;         EPI_ROWS_BEGIN
;             const float rs = 1.0f / acc_get(lsum + (size_t)row * 4 + u.pn, 1.0f / LS_SCALE);
; #pragma unroll
;             for (int bj = 0; bj < 2; ++bj) { const int col = colb + bj * HALF; const f32x4 v0 = acc[ai][bj][m][0] * rs, v1 = acc[ai][bj][m][1] * rs;
;                 u32x4 w; w.x = pk2(v0[0], v0[1]); w.y = pk2(v0[2], v0[3]); w.z = pk2(v1[0], v1[1]); w.w = pk2(v1[2], v1[3]); *(u32x4*)(H + (size_t)row * DM + col) = w; }
;         EPI_ROWS_END
;     }
.LBB0_2843:
	v_lshl_add_u32 v138, s28, 8, v140
	v_ashrrev_i32_e32 v139, 31, v138
	v_lshlrev_b64 v[144:145], 5, v[138:139]
	v_lshl_add_u64 v[144:145], s[4:5], 0, v[144:145]
	s_lshl_b64 s[28:29], s[6:7], 3
	v_lshl_add_u64 v[144:145], v[144:145], 0, s[28:29]
	v_mov_b32_e32 v190, 0x1000
	v_mov_b32_e32 v191, 0
	v_lshl_add_u64 v[192:193], v[190:191], 0, v[144:145]
	global_load_dwordx2 v[174:175], v[144:145], off
	global_load_dwordx2 v[176:177], v[144:145], off offset:512
	global_load_dwordx2 v[178:179], v[144:145], off offset:1024
	global_load_dwordx2 v[180:181], v[144:145], off offset:1536
	global_load_dwordx2 v[182:183], v[192:193], off
	global_load_dwordx2 v[184:185], v[192:193], off offset:512
	global_load_dwordx2 v[186:187], v[192:193], off offset:1024
	global_load_dwordx2 v[188:189], v[192:193], off offset:1536
	v_lshlrev_b64 v[148:149], 11, v[138:139]
	v_or_b32_e32 v146, 16, v138
	v_ashrrev_i32_e32 v147, 31, v146
	v_lshl_or_b32 v96, s6, 9, v143
	v_lshl_add_u64 v[148:149], s[2:3], 0, v[148:149]
	v_lshlrev_b64 v[150:151], 5, v[146:147]
	s_waitcnt vmcnt(0)
	v_mov_b64_e32 v[144:145], v[174:175]
	v_ffbh_u32_e32 v139, v145
	v_min_u32_e32 v139, 32, v139
	v_lshlrev_b64 v[144:145], v139, v[144:145]
	v_min_u32_e32 v144, 1, v144
	v_or_b32_e32 v144, v145, v144
	v_cvt_f32_u32_e32 v152, v144
	v_sub_u32_e32 v139, 32, v139
	v_lshl_add_u64 v[144:145], v[148:149], 0, v[96:97]
	v_lshl_add_u64 v[148:149], s[4:5], 0, v[150:151]
	v_ldexp_f32 v139, v152, v139
	v_mul_f32_e32 v139, 0x33800000, v139
	v_div_scale_f32 v150, s[30:31], v139, v139, 1.0
	v_rcp_f32_e32 v151, v150
	v_div_scale_f32 v152, vcc, 1.0, v139, 1.0
	v_lshl_add_u64 v[148:149], v[148:149], 0, s[28:29]
	v_fma_f32 v153, -v150, v151, 1.0
	v_fmac_f32_e32 v151, v153, v151
	v_mul_f32_e32 v153, v152, v151
	v_fma_f32 v162, -v150, v153, v152
	v_fmac_f32_e32 v153, v162, v151
	v_fma_f32 v150, -v150, v153, v152
	v_div_fmas_f32 v150, v150, v151, v153
	v_div_fixup_f32 v150, v150, v139, 1.0
	v_pk_mul_f32 v[128:129], v[128:129], v[150:151] op_sel_hi:[1,0]
	v_pk_mul_f32 v[126:127], v[126:127], v[150:151] op_sel_hi:[1,0]
	v_pk_mul_f32 v[124:125], v[124:125], v[150:151] op_sel_hi:[1,0]
	v_pk_mul_f32 v[122:123], v[122:123], v[150:151] op_sel_hi:[1,0]
	v_pk_mul_f32 v[120:121], v[120:121], v[150:151] op_sel_hi:[1,0]
	v_pk_mul_f32 v[118:119], v[118:119], v[150:151] op_sel_hi:[1,0]
	v_pk_mul_f32 v[152:153], v[116:117], v[150:151] op_sel_hi:[1,0]
	v_pk_mul_f32 v[150:151], v[114:115], v[150:151] op_sel_hi:[1,0]
	v_cvt_pk_bf16_f32 v114, v126, v127
	v_cvt_pk_bf16_f32 v115, v128, v129
	v_cvt_pk_bf16_f32 v116, v122, v123
	v_cvt_pk_bf16_f32 v117, v124, v125
	v_cvt_pk_bf16_f32 v118, v118, v119
	v_cvt_pk_bf16_f32 v119, v120, v121
	v_cvt_pk_bf16_f32 v120, v150, v151
	v_cvt_pk_bf16_f32 v121, v152, v153
	global_store_dwordx4 v[144:145], v[114:117], off
	global_store_dwordx4 v[144:145], v[118:121], off offset:256
	v_or_b32_e32 v116, 32, v138
	v_ashrrev_i32_e32 v117, 31, v116
	v_lshlrev_b64 v[120:121], 5, v[116:117]
	v_lshlrev_b64 v[118:119], 11, v[146:147]
	v_lshl_add_u64 v[118:119], s[2:3], 0, v[118:119]
	v_lshl_add_u64 v[118:119], v[118:119], 0, v[96:97]
	s_nop 1
	v_mov_b64_e32 v[114:115], v[176:177]
	v_ffbh_u32_e32 v122, v115
	v_min_u32_e32 v122, 32, v122
	v_lshlrev_b64 v[114:115], v122, v[114:115]
	v_min_u32_e32 v114, 1, v114
	v_or_b32_e32 v114, v115, v114
	v_cvt_f32_u32_e32 v123, v114
	v_lshl_add_u64 v[114:115], s[4:5], 0, v[120:121]
	v_sub_u32_e32 v120, 32, v122
	v_lshl_add_u64 v[114:115], v[114:115], 0, s[28:29]
	v_ldexp_f32 v120, v123, v120
	v_mul_f32_e32 v120, 0x33800000, v120
	v_div_scale_f32 v121, s[30:31], v120, v120, 1.0
	v_rcp_f32_e32 v122, v121
	v_div_scale_f32 v123, vcc, 1.0, v120, 1.0
	v_fma_f32 v124, -v121, v122, 1.0
	v_fmac_f32_e32 v122, v124, v122
	v_mul_f32_e32 v124, v123, v122
	v_fma_f32 v125, -v121, v124, v123
	v_fmac_f32_e32 v124, v125, v122
	v_fma_f32 v121, -v121, v124, v123
	v_div_fmas_f32 v121, v121, v122, v124
	v_div_fixup_f32 v120, v121, v120, 1.0
	v_pk_mul_f32 v[112:113], v[112:113], v[120:121] op_sel_hi:[1,0]
	v_pk_mul_f32 v[110:111], v[110:111], v[120:121] op_sel_hi:[1,0]
	v_pk_mul_f32 v[108:109], v[108:109], v[120:121] op_sel_hi:[1,0]
	v_pk_mul_f32 v[106:107], v[106:107], v[120:121] op_sel_hi:[1,0]
	v_pk_mul_f32 v[104:105], v[104:105], v[120:121] op_sel_hi:[1,0]
	v_pk_mul_f32 v[102:103], v[102:103], v[120:121] op_sel_hi:[1,0]
	v_pk_mul_f32 v[122:123], v[100:101], v[120:121] op_sel_hi:[1,0]
	v_pk_mul_f32 v[120:121], v[98:99], v[120:121] op_sel_hi:[1,0]
	v_cvt_pk_bf16_f32 v98, v110, v111
	v_cvt_pk_bf16_f32 v99, v112, v113
	v_cvt_pk_bf16_f32 v100, v106, v107
	v_cvt_pk_bf16_f32 v101, v108, v109
	v_cvt_pk_bf16_f32 v102, v102, v103
	v_cvt_pk_bf16_f32 v103, v104, v105
	v_cvt_pk_bf16_f32 v104, v120, v121
	v_cvt_pk_bf16_f32 v105, v122, v123
	global_store_dwordx4 v[118:119], v[98:101], off
	global_store_dwordx4 v[118:119], v[102:105], off offset:256
	v_or_b32_e32 v100, 48, v138
	v_ashrrev_i32_e32 v101, 31, v100
	v_lshlrev_b64 v[104:105], 5, v[100:101]
	v_lshlrev_b64 v[102:103], 11, v[116:117]
	v_lshl_add_u64 v[102:103], s[2:3], 0, v[102:103]
	v_lshl_add_u64 v[102:103], v[102:103], 0, v[96:97]
	s_nop 1
	v_mov_b64_e32 v[98:99], v[178:179]
	v_ffbh_u32_e32 v106, v99
	v_min_u32_e32 v106, 32, v106
	v_lshlrev_b64 v[98:99], v106, v[98:99]
	v_min_u32_e32 v98, 1, v98
	v_or_b32_e32 v98, v99, v98
	v_cvt_f32_u32_e32 v107, v98
	v_lshl_add_u64 v[98:99], s[4:5], 0, v[104:105]
	v_sub_u32_e32 v104, 32, v106
	v_lshl_add_u64 v[98:99], v[98:99], 0, s[28:29]
	v_ldexp_f32 v104, v107, v104
	v_mul_f32_e32 v104, 0x33800000, v104
	v_div_scale_f32 v105, s[30:31], v104, v104, 1.0
	v_rcp_f32_e32 v106, v105
	v_div_scale_f32 v107, vcc, 1.0, v104, 1.0
; DI unsigned pk2(float lo, float hi) { f32x2 v = {lo, hi}; bf16x2_t b = __builtin_convertvector(v, bf16x2_t); return __builtin_bit_cast(unsigned, b); }
; DI float acc_get(const acc_t* p, float inv_scale) { return (float)(*p) * inv_scale; }
;     DI void operator()(const f32x4 (&acc)[2][2][4][2], const Unit& u, int wr, int wc, int fr, int fq) const {
;         const int colb = u.pn * BM + wc * 32 + 8 * fq;
;         EPI_ROWS_BEGIN
;             const float rs = 1.0f / acc_get(lsum + (size_t)row * 4 + u.pn, 1.0f / LS_SCALE);
; #pragma unroll
;             for (int bj = 0; bj < 2; ++bj) { const int col = colb + bj * HALF; const f32x4 v0 = acc[ai][bj][m][0] * rs, v1 = acc[ai][bj][m][1] * rs;
;                 u32x4 w; w.x = pk2(v0[0], v0[1]); w.y = pk2(v0[2], v0[3]); w.z = pk2(v1[0], v1[1]); w.w = pk2(v1[2], v1[3]); *(u32x4*)(H + (size_t)row * DM + col) = w; }
;         EPI_ROWS_END
;     }
	v_fma_f32 v108, -v105, v106, 1.0
	v_fmac_f32_e32 v106, v108, v106
	v_mul_f32_e32 v108, v107, v106
	v_fma_f32 v109, -v105, v108, v107
	v_fmac_f32_e32 v108, v109, v106
	v_fma_f32 v105, -v105, v108, v107
	v_div_fmas_f32 v105, v105, v106, v108
	v_div_fixup_f32 v104, v105, v104, 1.0
	v_pk_mul_f32 v[94:95], v[94:95], v[104:105] op_sel_hi:[1,0]
	v_pk_mul_f32 v[92:93], v[92:93], v[104:105] op_sel_hi:[1,0]
	v_pk_mul_f32 v[90:91], v[90:91], v[104:105] op_sel_hi:[1,0]
	v_pk_mul_f32 v[88:89], v[88:89], v[104:105] op_sel_hi:[1,0]
	v_pk_mul_f32 v[86:87], v[86:87], v[104:105] op_sel_hi:[1,0]
	v_pk_mul_f32 v[84:85], v[84:85], v[104:105] op_sel_hi:[1,0]
	v_pk_mul_f32 v[106:107], v[82:83], v[104:105] op_sel_hi:[1,0]
	v_pk_mul_f32 v[104:105], v[80:81], v[104:105] op_sel_hi:[1,0]
	v_cvt_pk_bf16_f32 v80, v92, v93
	v_cvt_pk_bf16_f32 v81, v94, v95
	v_cvt_pk_bf16_f32 v82, v88, v89
	v_cvt_pk_bf16_f32 v83, v90, v91
	v_cvt_pk_bf16_f32 v84, v84, v85
	v_cvt_pk_bf16_f32 v85, v86, v87
	v_cvt_pk_bf16_f32 v86, v104, v105
	v_cvt_pk_bf16_f32 v87, v106, v107
	global_store_dwordx4 v[102:103], v[80:83], off
	global_store_dwordx4 v[102:103], v[84:87], off offset:256
	v_add_u32_e32 v82, 0x80, v138
	v_ashrrev_i32_e32 v83, 31, v82
	v_lshlrev_b64 v[86:87], 5, v[82:83]
	v_lshlrev_b64 v[84:85], 11, v[100:101]
	v_lshl_add_u64 v[84:85], s[2:3], 0, v[84:85]
	v_lshl_add_u64 v[84:85], v[84:85], 0, v[96:97]
	s_nop 1
	v_mov_b64_e32 v[80:81], v[180:181]
	v_ffbh_u32_e32 v88, v81
	v_min_u32_e32 v88, 32, v88
	v_lshlrev_b64 v[80:81], v88, v[80:81]
	v_min_u32_e32 v80, 1, v80
	v_or_b32_e32 v80, v81, v80
	v_cvt_f32_u32_e32 v89, v80
	v_lshl_add_u64 v[80:81], s[4:5], 0, v[86:87]
	v_sub_u32_e32 v86, 32, v88
	v_lshl_add_u64 v[80:81], v[80:81], 0, s[28:29]
	v_ldexp_f32 v86, v89, v86
	v_mul_f32_e32 v86, 0x33800000, v86
	v_div_scale_f32 v87, s[30:31], v86, v86, 1.0
	v_rcp_f32_e32 v88, v87
	v_div_scale_f32 v89, vcc, 1.0, v86, 1.0
	v_fma_f32 v90, -v87, v88, 1.0
	v_fmac_f32_e32 v88, v90, v88
	v_mul_f32_e32 v90, v89, v88
	v_fma_f32 v91, -v87, v90, v89
	v_fmac_f32_e32 v90, v91, v88
	v_fma_f32 v87, -v87, v90, v89
	v_div_fmas_f32 v87, v87, v88, v90
	v_div_fixup_f32 v86, v87, v86, 1.0
	v_pk_mul_f32 v[78:79], v[78:79], v[86:87] op_sel_hi:[1,0]
	v_pk_mul_f32 v[76:77], v[76:77], v[86:87] op_sel_hi:[1,0]
	v_pk_mul_f32 v[74:75], v[74:75], v[86:87] op_sel_hi:[1,0]
	v_pk_mul_f32 v[72:73], v[72:73], v[86:87] op_sel_hi:[1,0]
	v_pk_mul_f32 v[70:71], v[70:71], v[86:87] op_sel_hi:[1,0]
	v_pk_mul_f32 v[68:69], v[68:69], v[86:87] op_sel_hi:[1,0]
	v_pk_mul_f32 v[88:89], v[66:67], v[86:87] op_sel_hi:[1,0]
	v_pk_mul_f32 v[86:87], v[64:65], v[86:87] op_sel_hi:[1,0]
	v_cvt_pk_bf16_f32 v64, v76, v77
	v_cvt_pk_bf16_f32 v65, v78, v79
	v_cvt_pk_bf16_f32 v66, v72, v73
	v_cvt_pk_bf16_f32 v67, v74, v75
	v_cvt_pk_bf16_f32 v68, v68, v69
	v_cvt_pk_bf16_f32 v69, v70, v71
	v_cvt_pk_bf16_f32 v70, v86, v87
	v_cvt_pk_bf16_f32 v71, v88, v89
	global_store_dwordx4 v[84:85], v[64:67], off
	global_store_dwordx4 v[84:85], v[68:71], off offset:256
	v_add_u32_e32 v66, 0x90, v138
	v_ashrrev_i32_e32 v67, 31, v66
	v_lshlrev_b64 v[70:71], 5, v[66:67]
	v_lshlrev_b64 v[68:69], 11, v[82:83]
	v_lshl_add_u64 v[68:69], s[2:3], 0, v[68:69]
	v_lshl_add_u64 v[68:69], v[68:69], 0, v[96:97]
	s_nop 1
	v_mov_b64_e32 v[64:65], v[182:183]
	v_ffbh_u32_e32 v72, v65
	v_min_u32_e32 v72, 32, v72
	v_lshlrev_b64 v[64:65], v72, v[64:65]
	v_min_u32_e32 v64, 1, v64
	v_or_b32_e32 v64, v65, v64
	v_cvt_f32_u32_e32 v73, v64
	v_lshl_add_u64 v[64:65], s[4:5], 0, v[70:71]
	v_sub_u32_e32 v70, 32, v72
	v_lshl_add_u64 v[64:65], v[64:65], 0, s[28:29]
	v_ldexp_f32 v70, v73, v70
	v_mul_f32_e32 v70, 0x33800000, v70
	v_div_scale_f32 v71, s[30:31], v70, v70, 1.0
	v_rcp_f32_e32 v72, v71
	v_div_scale_f32 v73, vcc, 1.0, v70, 1.0
	v_fma_f32 v74, -v71, v72, 1.0
	v_fmac_f32_e32 v72, v74, v72
	v_mul_f32_e32 v74, v73, v72
	v_fma_f32 v75, -v71, v74, v73
	v_fmac_f32_e32 v74, v75, v72
	v_fma_f32 v71, -v71, v74, v73
	v_div_fmas_f32 v71, v71, v72, v74
	v_div_fixup_f32 v70, v71, v70, 1.0
	v_pk_mul_f32 v[62:63], v[62:63], v[70:71] op_sel_hi:[1,0]
	v_pk_mul_f32 v[60:61], v[60:61], v[70:71] op_sel_hi:[1,0]
	v_pk_mul_f32 v[58:59], v[58:59], v[70:71] op_sel_hi:[1,0]
	v_pk_mul_f32 v[56:57], v[56:57], v[70:71] op_sel_hi:[1,0]
	v_pk_mul_f32 v[54:55], v[54:55], v[70:71] op_sel_hi:[1,0]
	v_pk_mul_f32 v[52:53], v[52:53], v[70:71] op_sel_hi:[1,0]
	v_pk_mul_f32 v[72:73], v[50:51], v[70:71] op_sel_hi:[1,0]
	v_pk_mul_f32 v[70:71], v[48:49], v[70:71] op_sel_hi:[1,0]
	v_cvt_pk_bf16_f32 v48, v60, v61
	v_cvt_pk_bf16_f32 v49, v62, v63
	v_cvt_pk_bf16_f32 v50, v56, v57
	v_cvt_pk_bf16_f32 v51, v58, v59
	v_cvt_pk_bf16_f32 v52, v52, v53
	v_cvt_pk_bf16_f32 v53, v54, v55
	v_cvt_pk_bf16_f32 v54, v70, v71
	v_cvt_pk_bf16_f32 v55, v72, v73
	global_store_dwordx4 v[68:69], v[48:51], off
	global_store_dwordx4 v[68:69], v[52:55], off offset:256
	v_add_u32_e32 v50, 0xa0, v138
	v_ashrrev_i32_e32 v51, 31, v50
	v_lshlrev_b64 v[54:55], 5, v[50:51]
	v_lshlrev_b64 v[52:53], 11, v[66:67]
	v_lshl_add_u64 v[52:53], s[2:3], 0, v[52:53]
	v_lshl_add_u64 v[52:53], v[52:53], 0, v[96:97]
	s_nop 1
	v_mov_b64_e32 v[48:49], v[184:185]
	v_ffbh_u32_e32 v56, v49
	v_min_u32_e32 v56, 32, v56
; DI unsigned pk2(float lo, float hi) { f32x2 v = {lo, hi}; bf16x2_t b = __builtin_convertvector(v, bf16x2_t); return __builtin_bit_cast(unsigned, b); }
; DI float acc_get(const acc_t* p, float inv_scale) { return (float)(*p) * inv_scale; }
; #define PG8_BAR __builtin_amdgcn_s_barrier()
; template <class Epi, class Sched>
; DI void gemm_phase(LAS unsigned char* lds, const int tid, const int K, const int lda, const int ldb, const Sched& S, const Epi& E) {
;     ...
;         if (wr == 0) PG8_BAR;
;         E(acc, cur, wr, wc, fr, fq);
;         if (!has_next) break;
; #pragma unroll
;         for (int a = 0; a < 2; ++a)
; #pragma unroll
;             for (int b = 0; b < 2; ++b)
; #pragma unroll
;                 for (int m = 0; m < 4; ++m)
; #pragma unroll
;                     for (int n = 0; n < 2; ++n) acc[a][b][m][n] = (f32x4){0.f, 0.f, 0.f, 0.f};
;         cur = nxt; cA = nA; cB = nB; ++ui;
;         if (wr == 1) PG8_BAR;
;     DI void operator()(const f32x4 (&acc)[2][2][4][2], const Unit& u, int wr, int wc, int fr, int fq) const {
;         const int colb = u.pn * BM + wc * 32 + 8 * fq;
;         EPI_ROWS_BEGIN
;             const float rs = 1.0f / acc_get(lsum + (size_t)row * 4 + u.pn, 1.0f / LS_SCALE);
; #pragma unroll
;             for (int bj = 0; bj < 2; ++bj) { const int col = colb + bj * HALF; const f32x4 v0 = acc[ai][bj][m][0] * rs, v1 = acc[ai][bj][m][1] * rs;
;                 u32x4 w; w.x = pk2(v0[0], v0[1]); w.y = pk2(v0[2], v0[3]); w.z = pk2(v1[0], v1[1]); w.w = pk2(v1[2], v1[3]); *(u32x4*)(H + (size_t)row * DM + col) = w; }
;         EPI_ROWS_END
;     }
	v_lshlrev_b64 v[48:49], v56, v[48:49]
	v_min_u32_e32 v48, 1, v48
	v_or_b32_e32 v48, v49, v48
	v_cvt_f32_u32_e32 v57, v48
	v_lshl_add_u64 v[48:49], s[4:5], 0, v[54:55]
	v_sub_u32_e32 v54, 32, v56
	v_lshl_add_u64 v[48:49], v[48:49], 0, s[28:29]
	v_ldexp_f32 v54, v57, v54
	v_mul_f32_e32 v54, 0x33800000, v54
	v_div_scale_f32 v55, s[30:31], v54, v54, 1.0
	v_rcp_f32_e32 v56, v55
	v_div_scale_f32 v57, vcc, 1.0, v54, 1.0
	v_fma_f32 v58, -v55, v56, 1.0
	v_fmac_f32_e32 v56, v58, v56
	v_mul_f32_e32 v58, v57, v56
	v_fma_f32 v59, -v55, v58, v57
	v_fmac_f32_e32 v58, v59, v56
	v_fma_f32 v55, -v55, v58, v57
	v_div_fmas_f32 v55, v55, v56, v58
	v_div_fixup_f32 v54, v55, v54, 1.0
	v_pk_mul_f32 v[46:47], v[46:47], v[54:55] op_sel_hi:[1,0]
	v_pk_mul_f32 v[44:45], v[44:45], v[54:55] op_sel_hi:[1,0]
	v_pk_mul_f32 v[42:43], v[42:43], v[54:55] op_sel_hi:[1,0]
	v_pk_mul_f32 v[40:41], v[40:41], v[54:55] op_sel_hi:[1,0]
	v_pk_mul_f32 v[38:39], v[38:39], v[54:55] op_sel_hi:[1,0]
	v_pk_mul_f32 v[36:37], v[36:37], v[54:55] op_sel_hi:[1,0]
	v_pk_mul_f32 v[56:57], v[34:35], v[54:55] op_sel_hi:[1,0]
	v_pk_mul_f32 v[54:55], v[32:33], v[54:55] op_sel_hi:[1,0]
	v_cvt_pk_bf16_f32 v32, v44, v45
	v_cvt_pk_bf16_f32 v33, v46, v47
	v_cvt_pk_bf16_f32 v34, v40, v41
	v_cvt_pk_bf16_f32 v35, v42, v43
	v_cvt_pk_bf16_f32 v36, v36, v37
	v_cvt_pk_bf16_f32 v37, v38, v39
	v_cvt_pk_bf16_f32 v38, v54, v55
	v_cvt_pk_bf16_f32 v39, v56, v57
	global_store_dwordx4 v[52:53], v[32:35], off
	global_store_dwordx4 v[52:53], v[36:39], off offset:256
	v_add_u32_e32 v34, 0xb0, v138
	v_ashrrev_i32_e32 v35, 31, v34
	v_lshlrev_b64 v[38:39], 5, v[34:35]
	v_lshlrev_b64 v[36:37], 11, v[50:51]
	v_lshl_add_u64 v[36:37], s[2:3], 0, v[36:37]
	v_lshl_add_u64 v[36:37], v[36:37], 0, v[96:97]
	s_nop 1
	v_mov_b64_e32 v[32:33], v[186:187]
	v_ffbh_u32_e32 v40, v33
	v_min_u32_e32 v40, 32, v40
	v_lshlrev_b64 v[32:33], v40, v[32:33]
	v_min_u32_e32 v32, 1, v32
	v_or_b32_e32 v32, v33, v32
	v_cvt_f32_u32_e32 v41, v32
	v_lshl_add_u64 v[32:33], s[4:5], 0, v[38:39]
	v_sub_u32_e32 v38, 32, v40
	v_lshl_add_u64 v[32:33], v[32:33], 0, s[28:29]
	v_ldexp_f32 v38, v41, v38
	v_mul_f32_e32 v38, 0x33800000, v38
	v_div_scale_f32 v39, s[30:31], v38, v38, 1.0
	v_rcp_f32_e32 v40, v39
	v_div_scale_f32 v41, vcc, 1.0, v38, 1.0
	v_fma_f32 v42, -v39, v40, 1.0
	v_fmac_f32_e32 v40, v42, v40
	v_mul_f32_e32 v42, v41, v40
	v_fma_f32 v43, -v39, v42, v41
	v_fmac_f32_e32 v42, v43, v40
	v_fma_f32 v39, -v39, v42, v41
	v_div_fmas_f32 v39, v39, v40, v42
	v_div_fixup_f32 v38, v39, v38, 1.0
	v_pk_mul_f32 v[30:31], v[30:31], v[38:39] op_sel_hi:[1,0]
	v_pk_mul_f32 v[28:29], v[28:29], v[38:39] op_sel_hi:[1,0]
	v_pk_mul_f32 v[26:27], v[26:27], v[38:39] op_sel_hi:[1,0]
	v_pk_mul_f32 v[24:25], v[24:25], v[38:39] op_sel_hi:[1,0]
	v_pk_mul_f32 v[22:23], v[22:23], v[38:39] op_sel_hi:[1,0]
	v_pk_mul_f32 v[20:21], v[20:21], v[38:39] op_sel_hi:[1,0]
	v_pk_mul_f32 v[40:41], v[18:19], v[38:39] op_sel_hi:[1,0]
	v_pk_mul_f32 v[38:39], v[16:17], v[38:39] op_sel_hi:[1,0]
	v_cvt_pk_bf16_f32 v16, v28, v29
	v_cvt_pk_bf16_f32 v17, v30, v31
	v_cvt_pk_bf16_f32 v18, v24, v25
	v_cvt_pk_bf16_f32 v19, v26, v27
	v_cvt_pk_bf16_f32 v20, v20, v21
	v_cvt_pk_bf16_f32 v21, v22, v23
	v_cvt_pk_bf16_f32 v22, v38, v39
	v_cvt_pk_bf16_f32 v23, v40, v41
	global_store_dwordx4 v[36:37], v[16:19], off
	global_store_dwordx4 v[36:37], v[20:23], off offset:256
	s_nop 1
	v_mov_b64_e32 v[16:17], v[188:189]
	v_ffbh_u32_e32 v18, v17
	v_min_u32_e32 v18, 32, v18
	v_lshlrev_b64 v[16:17], v18, v[16:17]
	v_min_u32_e32 v16, 1, v16
	v_or_b32_e32 v16, v17, v16
	v_cvt_f32_u32_e32 v19, v16
	v_sub_u32_e32 v18, 32, v18
	v_lshlrev_b64 v[16:17], 11, v[34:35]
	v_lshl_add_u64 v[16:17], s[2:3], 0, v[16:17]
	v_ldexp_f32 v18, v19, v18
	v_mul_f32_e32 v18, 0x33800000, v18
	v_div_scale_f32 v19, s[28:29], v18, v18, 1.0
	v_rcp_f32_e32 v20, v19
	v_div_scale_f32 v21, vcc, 1.0, v18, 1.0
	v_lshl_add_u64 v[16:17], v[16:17], 0, v[96:97]
	v_fma_f32 v22, -v19, v20, 1.0
	v_fmac_f32_e32 v20, v22, v20
	v_mul_f32_e32 v22, v21, v20
	v_fma_f32 v23, -v19, v22, v21
	v_fmac_f32_e32 v22, v23, v20
	v_fma_f32 v19, -v19, v22, v21
	v_div_fmas_f32 v19, v19, v20, v22
	v_div_fixup_f32 v18, v19, v18, 1.0
	v_pk_mul_f32 v[14:15], v[14:15], v[18:19] op_sel_hi:[1,0]
	v_pk_mul_f32 v[12:13], v[12:13], v[18:19] op_sel_hi:[1,0]
	v_pk_mul_f32 v[10:11], v[10:11], v[18:19] op_sel_hi:[1,0]
	v_pk_mul_f32 v[8:9], v[8:9], v[18:19] op_sel_hi:[1,0]
	s_andn2_b64 vcc, exec, s[24:25]
	v_pk_mul_f32 v[6:7], v[6:7], v[18:19] op_sel_hi:[1,0]
	v_pk_mul_f32 v[4:5], v[4:5], v[18:19] op_sel_hi:[1,0]
	v_pk_mul_f32 v[20:21], v[2:3], v[18:19] op_sel_hi:[1,0]
	v_pk_mul_f32 v[18:19], v[0:1], v[18:19] op_sel_hi:[1,0]
	v_cvt_pk_bf16_f32 v0, v12, v13
	v_cvt_pk_bf16_f32 v1, v14, v15
	v_cvt_pk_bf16_f32 v2, v8, v9
	v_cvt_pk_bf16_f32 v3, v10, v11
	s_mov_b64 s[24:25], -1
	v_cvt_pk_bf16_f32 v4, v4, v5
	v_cvt_pk_bf16_f32 v5, v6, v7
	v_cvt_pk_bf16_f32 v6, v18, v19
	v_cvt_pk_bf16_f32 v7, v20, v21
	global_store_dwordx4 v[16:17], v[0:3], off
	global_store_dwordx4 v[16:17], v[4:7], off offset:256
	s_cbranch_vccnz .LBB0_2836
	s_andn2_b64 vcc, exec, s[0:1]
	s_cbranch_vccnz .LBB0_2835
	s_barrier
	s_branch .LBB0_2835

; DI unsigned pk2(float lo, float hi) { f32x2 v = {lo, hi}; bf16x2_t b = __builtin_convertvector(v, bf16x2_t); return __builtin_bit_cast(unsigned, b); }
; DI void acc_add(acc_t* p, float v, float scale) { atomicAdd(p, (acc_t)(v * scale)); }
;     DI void operator()(const f32x4 (&acc)[2][2][4][2], const Unit& u, int wr, int wc, int fr, int fq) const {
;         const int colb = u.pn * BM + wc * 32 + 8 * fq;
;         EPI_ROWS_BEGIN
;             float ss = 0.f;
; #pragma unroll
;             for (int bj = 0; bj < 2; ++bj) { const int col = colb + bj * HALF; bf16_t* xp = XB + (size_t)row * DM + col;
;                 float xv[8]; unpack8(*(const u32x4*)xp, xv);
;                 const f32x4 x0 = (f32x4){xv[0], xv[1], xv[2], xv[3]} + acc[ai][bj][m][0], x1 = (f32x4){xv[4], xv[5], xv[6], xv[7]} + acc[ai][bj][m][1];
;                 if (Y != nullptr) { float* yp = Y + (size_t)row * DM + col; *(f32x4*)yp = x0; *(f32x4*)(yp + 4) = x1; }
;                 u32x4 w; w.x = pk2(x0[0], x0[1]); w.y = pk2(x0[2], x0[3]); w.z = pk2(x1[0], x1[1]); w.w = pk2(x1[2], x1[3]); *(u32x4*)xp = w;
;                 ss += (x0[0] * x0[0] + x0[1] * x0[1]) + (x0[2] * x0[2] + x0[3] * x0[3]) + (x1[0] * x1[0] + x1[1] * x1[1]) + (x1[2] * x1[2] + x1[3] * x1[3]); }
;             ss += __shfl_xor(ss, 16); ss += __shfl_xor(ss, 32);
;             if (ssq_next != nullptr && fq == 0) acc_add(ssq_next + row, ss, SSQ_SCALE);
;         EPI_ROWS_END
.LBB0_2924:
	v_lshl_add_u32 v142, s14, 8, v144
	v_ashrrev_i32_e32 v143, 31, v142
	v_lshl_or_b32 v140, s0, 8, v146
	v_lshlrev_b64 v[148:149], 11, v[142:143]
	v_lshl_add_u64 v[148:149], s[4:5], 0, v[148:149]
	v_ashrrev_i32_e32 v141, 31, v140
	v_lshl_add_u64 v[152:153], v[140:141], 1, v[148:149]
	v_mov_b32_e32 v218, 0x8000
	v_mov_b32_e32 v219, 0
	global_load_dwordx4 v[174:177], v[152:153], off
	global_load_dwordx4 v[178:181], v[152:153], off offset:256
	v_lshl_add_u64 v[220:221], v[218:219], 0, v[152:153]
	global_load_dwordx4 v[182:185], v[220:221], off
	global_load_dwordx4 v[186:189], v[220:221], off offset:256
	v_lshl_add_u64 v[220:221], v[218:219], 1, v[152:153]
	global_load_dwordx4 v[190:193], v[220:221], off
	global_load_dwordx4 v[194:197], v[220:221], off offset:256
	v_lshl_add_u64 v[220:221], v[218:219], 0, v[220:221]
	global_load_dwordx4 v[198:201], v[220:221], off
	global_load_dwordx4 v[202:205], v[220:221], off offset:256
	v_lshl_add_u64 v[210:211], v[218:219], 3, v[152:153]
	v_lshl_add_u64 v[212:213], v[218:219], 0, v[210:211]
	v_lshl_add_u64 v[214:215], v[218:219], 1, v[210:211]
	v_lshl_add_u64 v[216:217], v[218:219], 0, v[214:215]
	s_waitcnt vmcnt(7)
	v_mov_b64_e32 v[148:149], v[174:175]
	v_mov_b64_e32 v[150:151], v[176:177]
	global_load_dwordx4 v[174:177], v[210:211], off
	v_lshlrev_b32_e32 v162, 16, v148
	v_and_b32_e32 v163, 0xffff0000, v148
	v_lshlrev_b32_e32 v148, 16, v149
	v_and_b32_e32 v149, 0xffff0000, v149
	v_lshlrev_b32_e32 v164, 16, v150
	v_and_b32_e32 v165, 0xffff0000, v150
	v_lshlrev_b32_e32 v150, 16, v151
	v_and_b32_e32 v151, 0xffff0000, v151
	v_pk_add_f32 v[128:129], v[128:129], v[148:149]
	v_pk_add_f32 v[126:127], v[126:127], v[162:163]
	v_pk_add_f32 v[148:149], v[124:125], v[150:151]
	v_pk_add_f32 v[150:151], v[122:123], v[164:165]
	v_cvt_pk_bf16_f32 v122, v126, v127
	v_cvt_pk_bf16_f32 v123, v128, v129
	v_cvt_pk_bf16_f32 v124, v150, v151
	v_cvt_pk_bf16_f32 v125, v148, v149
	global_store_dwordx4 v[152:153], v[122:125], off
	s_nop 1
	v_mul_f32_e32 v122, v127, v127
	v_mul_f32_e32 v123, v129, v129
	v_fmac_f32_e32 v122, v126, v126
	v_fmac_f32_e32 v123, v128, v128
	v_add_f32_e32 v122, v122, v123
	v_mul_f32_e32 v123, v151, v151
	v_fmac_f32_e32 v123, v150, v150
	v_add_f32_e32 v122, v123, v122
	v_mul_f32_e32 v123, v149, v149
	v_fmac_f32_e32 v123, v148, v148
	v_add_f32_e32 v148, v123, v122
	s_waitcnt vmcnt(8)
	v_mov_b64_e32 v[122:123], v[178:179]
	v_mov_b64_e32 v[124:125], v[180:181]
	global_load_dwordx4 v[178:181], v[210:211], off offset:256
	v_lshlrev_b32_e32 v126, 16, v122
	v_and_b32_e32 v127, 0xffff0000, v122
	v_lshlrev_b32_e32 v122, 16, v123
	v_and_b32_e32 v123, 0xffff0000, v123
	v_lshlrev_b32_e32 v128, 16, v124
	v_and_b32_e32 v129, 0xffff0000, v124
	v_lshlrev_b32_e32 v124, 16, v125
	v_and_b32_e32 v125, 0xffff0000, v125
	v_pk_add_f32 v[120:121], v[120:121], v[122:123]
	v_pk_add_f32 v[118:119], v[118:119], v[126:127]
	v_pk_add_f32 v[122:123], v[116:117], v[124:125]
	v_pk_add_f32 v[124:125], v[114:115], v[128:129]
	v_cvt_pk_bf16_f32 v114, v118, v119
	v_cvt_pk_bf16_f32 v115, v120, v121
	v_cvt_pk_bf16_f32 v116, v124, v125
	v_cvt_pk_bf16_f32 v117, v122, v123
	global_store_dwordx4 v[152:153], v[114:117], off offset:256
	s_nop 1
	v_mul_f32_e32 v114, v119, v119
	v_mul_f32_e32 v115, v121, v121
	v_fmac_f32_e32 v114, v118, v118
	v_fmac_f32_e32 v115, v120, v120
	v_add_f32_e32 v114, v114, v115
	v_mul_f32_e32 v115, v125, v125
	v_fmac_f32_e32 v115, v124, v124
	v_add_f32_e32 v114, v115, v114
	v_mul_f32_e32 v115, v123, v123
	v_fmac_f32_e32 v115, v122, v122
	v_add_f32_e32 v114, v115, v114
	v_add_f32_e32 v114, v148, v114
	ds_bpermute_b32 v115, v207, v114
	s_waitcnt lgkmcnt(0)
	v_add_f32_e32 v116, v114, v115
	ds_bpermute_b32 v117, v208, v116
	v_lshl_add_u64 v[114:115], v[142:143], 3, s[8:9]
	s_and_saveexec_b64 s[0:1], s[36:37]
	s_cbranch_execz .LBB0_2926
	s_waitcnt lgkmcnt(0)
	v_add_f32_e32 v116, v116, v117
	v_mul_f32_e32 v116, 0x49800000, v116
	v_trunc_f32_e32 v116, v116
	v_mul_f32_e32 v117, 0x2f800000, v116
	v_floor_f32_e32 v117, v117
	v_fmac_f32_e32 v116, 0xcf800000, v117
	v_cvt_u32_f32_e32 v116, v116
	v_cvt_u32_f32_e32 v117, v117
	global_atomic_add_x2 v[114:115], v[116:117], off
.LBB0_2926:
	s_or_b64 exec, exec, s[0:1]
	v_or_b32_e32 v116, 16, v142
	s_waitcnt lgkmcnt(0)
	v_ashrrev_i32_e32 v117, 31, v116
	v_lshlrev_b64 v[116:117], 11, v[116:117]
	v_lshl_add_u64 v[116:117], s[4:5], 0, v[116:117]
	v_lshl_add_u64 v[120:121], v[140:141], 1, v[116:117]
	s_waitcnt vmcnt(9)
	v_mov_b64_e32 v[116:117], v[182:183]
	v_mov_b64_e32 v[118:119], v[184:185]
	global_load_dwordx4 v[182:185], v[212:213], off
	v_lshlrev_b32_e32 v122, 16, v116
	v_and_b32_e32 v123, 0xffff0000, v116
	v_lshlrev_b32_e32 v116, 16, v117
	v_and_b32_e32 v117, 0xffff0000, v117
	v_lshlrev_b32_e32 v124, 16, v118
	v_and_b32_e32 v125, 0xffff0000, v118
	v_lshlrev_b32_e32 v118, 16, v119
	v_and_b32_e32 v119, 0xffff0000, v119
	v_pk_add_f32 v[112:113], v[112:113], v[116:117]
	v_pk_add_f32 v[110:111], v[110:111], v[122:123]
	v_pk_add_f32 v[116:117], v[108:109], v[118:119]
	v_pk_add_f32 v[118:119], v[106:107], v[124:125]
	v_cvt_pk_bf16_f32 v106, v110, v111
	v_cvt_pk_bf16_f32 v107, v112, v113
	v_cvt_pk_bf16_f32 v108, v118, v119
	v_cvt_pk_bf16_f32 v109, v116, v117
	global_store_dwordx4 v[120:121], v[106:109], off
	s_nop 1
	v_mul_f32_e32 v106, v111, v111
	v_mul_f32_e32 v107, v113, v113
	v_fmac_f32_e32 v106, v110, v110
	v_fmac_f32_e32 v107, v112, v112
	v_add_f32_e32 v106, v106, v107
	v_mul_f32_e32 v107, v119, v119
	v_fmac_f32_e32 v107, v118, v118
	v_add_f32_e32 v106, v107, v106
	v_mul_f32_e32 v107, v117, v117
	v_fmac_f32_e32 v107, v116, v116
	v_add_f32_e32 v116, v107, v106
	s_waitcnt vmcnt(10)
	v_mov_b64_e32 v[106:107], v[186:187]
	v_mov_b64_e32 v[108:109], v[188:189]
	global_load_dwordx4 v[186:189], v[212:213], off offset:256
	v_lshlrev_b32_e32 v110, 16, v106
	v_and_b32_e32 v111, 0xffff0000, v106
	v_lshlrev_b32_e32 v106, 16, v107
	v_and_b32_e32 v107, 0xffff0000, v107
	v_lshlrev_b32_e32 v112, 16, v108
	v_and_b32_e32 v113, 0xffff0000, v108
	v_lshlrev_b32_e32 v108, 16, v109
	v_and_b32_e32 v109, 0xffff0000, v109
	v_pk_add_f32 v[104:105], v[104:105], v[106:107]
	v_pk_add_f32 v[102:103], v[102:103], v[110:111]
	v_pk_add_f32 v[106:107], v[100:101], v[108:109]
	v_pk_add_f32 v[108:109], v[98:99], v[112:113]
	v_cvt_pk_bf16_f32 v98, v102, v103
	v_cvt_pk_bf16_f32 v99, v104, v105
	v_cvt_pk_bf16_f32 v100, v108, v109
	v_cvt_pk_bf16_f32 v101, v106, v107
	global_store_dwordx4 v[120:121], v[98:101], off offset:256
	s_nop 1
	v_mul_f32_e32 v98, v103, v103
	v_mul_f32_e32 v99, v105, v105
	v_fmac_f32_e32 v98, v102, v102
	v_fmac_f32_e32 v99, v104, v104
	v_add_f32_e32 v98, v98, v99
	v_mul_f32_e32 v99, v109, v109
	v_fmac_f32_e32 v99, v108, v108
	v_add_f32_e32 v98, v99, v98
	v_mul_f32_e32 v99, v107, v107
	v_fmac_f32_e32 v99, v106, v106
	v_add_f32_e32 v98, v99, v98
	v_add_f32_e32 v98, v116, v98
	ds_bpermute_b32 v99, v207, v98
	s_waitcnt lgkmcnt(0)
	v_add_f32_e32 v98, v98, v99
	ds_bpermute_b32 v99, v208, v98
	s_and_saveexec_b64 s[0:1], s[36:37]
	s_cbranch_execz .LBB0_2928
; DI unsigned pk2(float lo, float hi) { f32x2 v = {lo, hi}; bf16x2_t b = __builtin_convertvector(v, bf16x2_t); return __builtin_bit_cast(unsigned, b); }
; DI void acc_add(acc_t* p, float v, float scale) { atomicAdd(p, (acc_t)(v * scale)); }
;     DI void operator()(const f32x4 (&acc)[2][2][4][2], const Unit& u, int wr, int wc, int fr, int fq) const {
;         const int colb = u.pn * BM + wc * 32 + 8 * fq;
;         EPI_ROWS_BEGIN
;             float ss = 0.f;
; #pragma unroll
;             for (int bj = 0; bj < 2; ++bj) { const int col = colb + bj * HALF; bf16_t* xp = XB + (size_t)row * DM + col;
;                 float xv[8]; unpack8(*(const u32x4*)xp, xv);
;                 const f32x4 x0 = (f32x4){xv[0], xv[1], xv[2], xv[3]} + acc[ai][bj][m][0], x1 = (f32x4){xv[4], xv[5], xv[6], xv[7]} + acc[ai][bj][m][1];
;                 if (Y != nullptr) { float* yp = Y + (size_t)row * DM + col; *(f32x4*)yp = x0; *(f32x4*)(yp + 4) = x1; }
;                 u32x4 w; w.x = pk2(x0[0], x0[1]); w.y = pk2(x0[2], x0[3]); w.z = pk2(x1[0], x1[1]); w.w = pk2(x1[2], x1[3]); *(u32x4*)xp = w;
;                 ss += (x0[0] * x0[0] + x0[1] * x0[1]) + (x0[2] * x0[2] + x0[3] * x0[3]) + (x1[0] * x1[0] + x1[1] * x1[1]) + (x1[2] * x1[2] + x1[3] * x1[3]); }
;             ss += __shfl_xor(ss, 16); ss += __shfl_xor(ss, 32);
;             if (ssq_next != nullptr && fq == 0) acc_add(ssq_next + row, ss, SSQ_SCALE);
;         EPI_ROWS_END
	s_waitcnt lgkmcnt(0)
	v_add_f32_e32 v98, v98, v99
	v_mul_f32_e32 v98, 0x49800000, v98
	v_trunc_f32_e32 v98, v98
	v_mul_f32_e32 v99, 0x2f800000, v98
	v_floor_f32_e32 v99, v99
	v_fmac_f32_e32 v98, 0xcf800000, v99
	v_cvt_u32_f32_e32 v98, v98
	v_cvt_u32_f32_e32 v99, v99
	global_atomic_add_x2 v[114:115], v[98:99], off offset:128
.LBB0_2928:
	s_or_b64 exec, exec, s[0:1]
	v_or_b32_e32 v98, 32, v142
	s_waitcnt lgkmcnt(0)
	v_ashrrev_i32_e32 v99, 31, v98
	v_lshlrev_b64 v[98:99], 11, v[98:99]
	v_lshl_add_u64 v[98:99], s[4:5], 0, v[98:99]
	v_lshl_add_u64 v[102:103], v[140:141], 1, v[98:99]
	s_waitcnt vmcnt(11)
	v_mov_b64_e32 v[98:99], v[190:191]
	v_mov_b64_e32 v[100:101], v[192:193]
	global_load_dwordx4 v[190:193], v[214:215], off
	v_lshlrev_b32_e32 v104, 16, v98
	v_and_b32_e32 v105, 0xffff0000, v98
	v_lshlrev_b32_e32 v98, 16, v99
	v_and_b32_e32 v99, 0xffff0000, v99
	v_lshlrev_b32_e32 v106, 16, v100
	v_and_b32_e32 v107, 0xffff0000, v100
	v_lshlrev_b32_e32 v100, 16, v101
	v_and_b32_e32 v101, 0xffff0000, v101
	v_pk_add_f32 v[94:95], v[94:95], v[98:99]
	v_pk_add_f32 v[92:93], v[92:93], v[104:105]
	v_pk_add_f32 v[98:99], v[90:91], v[100:101]
	v_pk_add_f32 v[100:101], v[88:89], v[106:107]
	v_cvt_pk_bf16_f32 v88, v92, v93
	v_cvt_pk_bf16_f32 v89, v94, v95
	v_cvt_pk_bf16_f32 v90, v100, v101
	v_cvt_pk_bf16_f32 v91, v98, v99
	global_store_dwordx4 v[102:103], v[88:91], off
	s_nop 1
	v_mul_f32_e32 v88, v93, v93
	v_mul_f32_e32 v89, v95, v95
	v_fmac_f32_e32 v88, v92, v92
	v_fmac_f32_e32 v89, v94, v94
	v_add_f32_e32 v88, v88, v89
	v_mul_f32_e32 v89, v101, v101
	v_fmac_f32_e32 v89, v100, v100
	v_add_f32_e32 v88, v89, v88
	v_mul_f32_e32 v89, v99, v99
	v_fmac_f32_e32 v89, v98, v98
	v_add_f32_e32 v98, v89, v88
	s_waitcnt vmcnt(12)
	v_mov_b64_e32 v[88:89], v[194:195]
	v_mov_b64_e32 v[90:91], v[196:197]
	global_load_dwordx4 v[194:197], v[214:215], off offset:256
	v_lshlrev_b32_e32 v92, 16, v88
	v_and_b32_e32 v93, 0xffff0000, v88
	v_lshlrev_b32_e32 v88, 16, v89
	v_and_b32_e32 v89, 0xffff0000, v89
	v_lshlrev_b32_e32 v94, 16, v90
	v_and_b32_e32 v95, 0xffff0000, v90
	v_lshlrev_b32_e32 v90, 16, v91
	v_and_b32_e32 v91, 0xffff0000, v91
	v_pk_add_f32 v[86:87], v[86:87], v[88:89]
	v_pk_add_f32 v[84:85], v[84:85], v[92:93]
	v_pk_add_f32 v[88:89], v[82:83], v[90:91]
	v_pk_add_f32 v[90:91], v[80:81], v[94:95]
	v_cvt_pk_bf16_f32 v80, v84, v85
	v_cvt_pk_bf16_f32 v81, v86, v87
	v_cvt_pk_bf16_f32 v82, v90, v91
	v_cvt_pk_bf16_f32 v83, v88, v89
	global_store_dwordx4 v[102:103], v[80:83], off offset:256
	s_nop 1
	v_mul_f32_e32 v80, v85, v85
	v_mul_f32_e32 v81, v87, v87
	v_fmac_f32_e32 v80, v84, v84
	v_fmac_f32_e32 v81, v86, v86
	v_add_f32_e32 v80, v80, v81
	v_mul_f32_e32 v81, v91, v91
	v_fmac_f32_e32 v81, v90, v90
	v_add_f32_e32 v80, v81, v80
	v_mul_f32_e32 v81, v89, v89
	v_fmac_f32_e32 v81, v88, v88
	v_add_f32_e32 v80, v81, v80
	v_add_f32_e32 v80, v98, v80
	ds_bpermute_b32 v81, v207, v80
	s_waitcnt lgkmcnt(0)
	v_add_f32_e32 v80, v80, v81
	ds_bpermute_b32 v81, v208, v80
	s_and_saveexec_b64 s[0:1], s[36:37]
	s_cbranch_execz .LBB0_2930
	s_waitcnt lgkmcnt(0)
	v_add_f32_e32 v80, v80, v81
	v_mul_f32_e32 v80, 0x49800000, v80
	v_trunc_f32_e32 v80, v80
	v_mul_f32_e32 v81, 0x2f800000, v80
	v_floor_f32_e32 v81, v81
	v_fmac_f32_e32 v80, 0xcf800000, v81
	v_cvt_u32_f32_e32 v80, v80
	v_cvt_u32_f32_e32 v81, v81
	global_atomic_add_x2 v[114:115], v[80:81], off offset:256
.LBB0_2930:
	s_or_b64 exec, exec, s[0:1]
	v_or_b32_e32 v80, 48, v142
	s_waitcnt lgkmcnt(0)
	v_ashrrev_i32_e32 v81, 31, v80
	v_lshlrev_b64 v[80:81], 11, v[80:81]
	v_lshl_add_u64 v[80:81], s[4:5], 0, v[80:81]
	v_lshl_add_u64 v[84:85], v[140:141], 1, v[80:81]
	s_waitcnt vmcnt(13)
	v_mov_b64_e32 v[80:81], v[198:199]
	v_mov_b64_e32 v[82:83], v[200:201]
	global_load_dwordx4 v[198:201], v[216:217], off
	v_lshlrev_b32_e32 v86, 16, v80
	v_and_b32_e32 v87, 0xffff0000, v80
	v_lshlrev_b32_e32 v80, 16, v81
	v_and_b32_e32 v81, 0xffff0000, v81
	v_lshlrev_b32_e32 v88, 16, v82
	v_and_b32_e32 v89, 0xffff0000, v82
	v_lshlrev_b32_e32 v82, 16, v83
	v_and_b32_e32 v83, 0xffff0000, v83
	v_pk_add_f32 v[78:79], v[78:79], v[80:81]
	v_pk_add_f32 v[76:77], v[76:77], v[86:87]
	v_pk_add_f32 v[80:81], v[74:75], v[82:83]
	v_pk_add_f32 v[82:83], v[72:73], v[88:89]
	v_cvt_pk_bf16_f32 v72, v76, v77
	v_cvt_pk_bf16_f32 v73, v78, v79
	v_cvt_pk_bf16_f32 v74, v82, v83
	v_cvt_pk_bf16_f32 v75, v80, v81
	global_store_dwordx4 v[84:85], v[72:75], off
	s_nop 1
	v_mul_f32_e32 v72, v77, v77
	v_mul_f32_e32 v73, v79, v79
	v_fmac_f32_e32 v72, v76, v76
	v_fmac_f32_e32 v73, v78, v78
	v_add_f32_e32 v72, v72, v73
	v_mul_f32_e32 v73, v83, v83
	v_fmac_f32_e32 v73, v82, v82
	v_add_f32_e32 v72, v73, v72
	v_mul_f32_e32 v73, v81, v81
	v_fmac_f32_e32 v73, v80, v80
	v_add_f32_e32 v80, v73, v72
	s_waitcnt vmcnt(14)
	v_mov_b64_e32 v[72:73], v[202:203]
	v_mov_b64_e32 v[74:75], v[204:205]
	global_load_dwordx4 v[202:205], v[216:217], off offset:256
	v_lshlrev_b32_e32 v76, 16, v72
	v_and_b32_e32 v77, 0xffff0000, v72
	v_lshlrev_b32_e32 v72, 16, v73
	v_and_b32_e32 v73, 0xffff0000, v73
	v_lshlrev_b32_e32 v78, 16, v74
	v_and_b32_e32 v79, 0xffff0000, v74
	v_lshlrev_b32_e32 v74, 16, v75
	v_and_b32_e32 v75, 0xffff0000, v75
	v_pk_add_f32 v[70:71], v[70:71], v[72:73]
	v_pk_add_f32 v[68:69], v[68:69], v[76:77]
	v_pk_add_f32 v[72:73], v[66:67], v[74:75]
	v_pk_add_f32 v[74:75], v[64:65], v[78:79]
	v_cvt_pk_bf16_f32 v64, v68, v69
	v_cvt_pk_bf16_f32 v65, v70, v71
	v_cvt_pk_bf16_f32 v66, v74, v75
	v_cvt_pk_bf16_f32 v67, v72, v73
	global_store_dwordx4 v[84:85], v[64:67], off offset:256
	s_nop 1
	v_mul_f32_e32 v64, v69, v69
	v_mul_f32_e32 v65, v71, v71
	v_fmac_f32_e32 v64, v68, v68
	v_fmac_f32_e32 v65, v70, v70
	v_add_f32_e32 v64, v64, v65
	v_mul_f32_e32 v65, v75, v75
	v_fmac_f32_e32 v65, v74, v74
	v_add_f32_e32 v64, v65, v64
	v_mul_f32_e32 v65, v73, v73
	v_fmac_f32_e32 v65, v72, v72
	v_add_f32_e32 v64, v65, v64
	v_add_f32_e32 v64, v80, v64
	ds_bpermute_b32 v65, v207, v64
	s_waitcnt lgkmcnt(0)
	v_add_f32_e32 v64, v64, v65
	ds_bpermute_b32 v65, v208, v64
	s_and_saveexec_b64 s[0:1], s[36:37]
	s_cbranch_execz .LBB0_2932
	s_waitcnt lgkmcnt(0)
	v_add_f32_e32 v64, v64, v65
	v_mul_f32_e32 v64, 0x49800000, v64
	v_trunc_f32_e32 v64, v64
	v_mul_f32_e32 v65, 0x2f800000, v64
	v_floor_f32_e32 v65, v65
	v_fmac_f32_e32 v64, 0xcf800000, v65
	v_cvt_u32_f32_e32 v64, v64
	v_cvt_u32_f32_e32 v65, v65
	global_atomic_add_x2 v[114:115], v[64:65], off offset:384
; DI unsigned pk2(float lo, float hi) { f32x2 v = {lo, hi}; bf16x2_t b = __builtin_convertvector(v, bf16x2_t); return __builtin_bit_cast(unsigned, b); }
; DI void acc_add(acc_t* p, float v, float scale) { atomicAdd(p, (acc_t)(v * scale)); }
;     DI void operator()(const f32x4 (&acc)[2][2][4][2], const Unit& u, int wr, int wc, int fr, int fq) const {
;         const int colb = u.pn * BM + wc * 32 + 8 * fq;
;         EPI_ROWS_BEGIN
;             float ss = 0.f;
; #pragma unroll
;             for (int bj = 0; bj < 2; ++bj) { const int col = colb + bj * HALF; bf16_t* xp = XB + (size_t)row * DM + col;
;                 float xv[8]; unpack8(*(const u32x4*)xp, xv);
;                 const f32x4 x0 = (f32x4){xv[0], xv[1], xv[2], xv[3]} + acc[ai][bj][m][0], x1 = (f32x4){xv[4], xv[5], xv[6], xv[7]} + acc[ai][bj][m][1];
;                 if (Y != nullptr) { float* yp = Y + (size_t)row * DM + col; *(f32x4*)yp = x0; *(f32x4*)(yp + 4) = x1; }
;                 u32x4 w; w.x = pk2(x0[0], x0[1]); w.y = pk2(x0[2], x0[3]); w.z = pk2(x1[0], x1[1]); w.w = pk2(x1[2], x1[3]); *(u32x4*)xp = w;
;                 ss += (x0[0] * x0[0] + x0[1] * x0[1]) + (x0[2] * x0[2] + x0[3] * x0[3]) + (x1[0] * x1[0] + x1[1] * x1[1]) + (x1[2] * x1[2] + x1[3] * x1[3]); }
;             ss += __shfl_xor(ss, 16); ss += __shfl_xor(ss, 32);
;             if (ssq_next != nullptr && fq == 0) acc_add(ssq_next + row, ss, SSQ_SCALE);
;         EPI_ROWS_END
.LBB0_2932:
	s_or_b64 exec, exec, s[0:1]
	v_add_u32_e32 v64, 0x80, v142
	s_waitcnt lgkmcnt(0)
	v_ashrrev_i32_e32 v65, 31, v64
	v_lshlrev_b64 v[64:65], 11, v[64:65]
	v_lshl_add_u64 v[64:65], s[4:5], 0, v[64:65]
	v_lshl_add_u64 v[68:69], v[140:141], 1, v[64:65]
	s_waitcnt vmcnt(15)
	v_mov_b64_e32 v[64:65], v[174:175]
	v_mov_b64_e32 v[66:67], v[176:177]
	v_lshlrev_b32_e32 v70, 16, v64
	v_and_b32_e32 v71, 0xffff0000, v64
	v_lshlrev_b32_e32 v64, 16, v65
	v_and_b32_e32 v65, 0xffff0000, v65
	v_lshlrev_b32_e32 v72, 16, v66
	v_and_b32_e32 v73, 0xffff0000, v66
	v_lshlrev_b32_e32 v66, 16, v67
	v_and_b32_e32 v67, 0xffff0000, v67
	v_pk_add_f32 v[62:63], v[62:63], v[64:65]
	v_pk_add_f32 v[60:61], v[60:61], v[70:71]
	v_pk_add_f32 v[64:65], v[58:59], v[66:67]
	v_pk_add_f32 v[66:67], v[56:57], v[72:73]
	v_cvt_pk_bf16_f32 v56, v60, v61
	v_cvt_pk_bf16_f32 v57, v62, v63
	v_cvt_pk_bf16_f32 v58, v66, v67
	v_cvt_pk_bf16_f32 v59, v64, v65
	global_store_dwordx4 v[68:69], v[56:59], off
	s_nop 1
	v_mul_f32_e32 v56, v61, v61
	v_mul_f32_e32 v57, v63, v63
	v_fmac_f32_e32 v56, v60, v60
	v_fmac_f32_e32 v57, v62, v62
	v_add_f32_e32 v56, v56, v57
	v_mul_f32_e32 v57, v67, v67
	v_fmac_f32_e32 v57, v66, v66
	v_add_f32_e32 v56, v57, v56
	v_mul_f32_e32 v57, v65, v65
	v_fmac_f32_e32 v57, v64, v64
	v_add_f32_e32 v64, v57, v56
	s_waitcnt vmcnt(14)
	v_mov_b64_e32 v[56:57], v[178:179]
	v_mov_b64_e32 v[58:59], v[180:181]
	v_lshlrev_b32_e32 v60, 16, v56
	v_and_b32_e32 v61, 0xffff0000, v56
	v_lshlrev_b32_e32 v56, 16, v57
	v_and_b32_e32 v57, 0xffff0000, v57
	v_lshlrev_b32_e32 v62, 16, v58
	v_and_b32_e32 v63, 0xffff0000, v58
	v_lshlrev_b32_e32 v58, 16, v59
	v_and_b32_e32 v59, 0xffff0000, v59
	v_pk_add_f32 v[54:55], v[54:55], v[56:57]
	v_pk_add_f32 v[52:53], v[52:53], v[60:61]
	v_pk_add_f32 v[56:57], v[50:51], v[58:59]
	v_pk_add_f32 v[58:59], v[48:49], v[62:63]
	v_cvt_pk_bf16_f32 v48, v52, v53
	v_cvt_pk_bf16_f32 v49, v54, v55
	v_cvt_pk_bf16_f32 v50, v58, v59
	v_cvt_pk_bf16_f32 v51, v56, v57
	global_store_dwordx4 v[68:69], v[48:51], off offset:256
	s_nop 1
	v_mul_f32_e32 v48, v53, v53
	v_mul_f32_e32 v49, v55, v55
	v_fmac_f32_e32 v48, v52, v52
	v_fmac_f32_e32 v49, v54, v54
	v_add_f32_e32 v48, v48, v49
	v_mul_f32_e32 v49, v59, v59
	v_fmac_f32_e32 v49, v58, v58
	v_add_f32_e32 v48, v49, v48
	v_mul_f32_e32 v49, v57, v57
	v_fmac_f32_e32 v49, v56, v56
	v_add_f32_e32 v48, v49, v48
	v_add_f32_e32 v48, v64, v48
	ds_bpermute_b32 v49, v207, v48
	s_waitcnt lgkmcnt(0)
	v_add_f32_e32 v48, v48, v49
	ds_bpermute_b32 v49, v208, v48
	s_and_saveexec_b64 s[0:1], s[36:37]
	s_cbranch_execz .LBB0_2934
	s_waitcnt lgkmcnt(0)
	v_add_f32_e32 v48, v48, v49
	v_mul_f32_e32 v48, 0x49800000, v48
	v_trunc_f32_e32 v48, v48
	v_mul_f32_e32 v49, 0x2f800000, v48
	v_floor_f32_e32 v49, v49
	v_fmac_f32_e32 v48, 0xcf800000, v49
	v_cvt_u32_f32_e32 v48, v48
	v_cvt_u32_f32_e32 v49, v49
	global_atomic_add_x2 v[114:115], v[48:49], off offset:1024
.LBB0_2934:
	s_or_b64 exec, exec, s[0:1]
	v_add_u32_e32 v48, 0x90, v142
	s_waitcnt lgkmcnt(0)
	v_ashrrev_i32_e32 v49, 31, v48
	v_lshlrev_b64 v[48:49], 11, v[48:49]
	v_lshl_add_u64 v[48:49], s[4:5], 0, v[48:49]
	v_lshl_add_u64 v[52:53], v[140:141], 1, v[48:49]
	s_waitcnt vmcnt(13)
	v_mov_b64_e32 v[48:49], v[182:183]
	v_mov_b64_e32 v[50:51], v[184:185]
	v_lshlrev_b32_e32 v54, 16, v48
	v_and_b32_e32 v55, 0xffff0000, v48
	v_lshlrev_b32_e32 v48, 16, v49
	v_and_b32_e32 v49, 0xffff0000, v49
	v_lshlrev_b32_e32 v56, 16, v50
	v_and_b32_e32 v57, 0xffff0000, v50
	v_lshlrev_b32_e32 v50, 16, v51
	v_and_b32_e32 v51, 0xffff0000, v51
	v_pk_add_f32 v[46:47], v[46:47], v[48:49]
	v_pk_add_f32 v[44:45], v[44:45], v[54:55]
	v_pk_add_f32 v[48:49], v[42:43], v[50:51]
	v_pk_add_f32 v[50:51], v[40:41], v[56:57]
	v_cvt_pk_bf16_f32 v40, v44, v45
	v_cvt_pk_bf16_f32 v41, v46, v47
	v_cvt_pk_bf16_f32 v42, v50, v51
	v_cvt_pk_bf16_f32 v43, v48, v49
	global_store_dwordx4 v[52:53], v[40:43], off
	s_nop 1
	v_mul_f32_e32 v40, v45, v45
	v_mul_f32_e32 v41, v47, v47
	v_fmac_f32_e32 v40, v44, v44
	v_fmac_f32_e32 v41, v46, v46
	v_add_f32_e32 v40, v40, v41
	v_mul_f32_e32 v41, v51, v51
	v_fmac_f32_e32 v41, v50, v50
	v_add_f32_e32 v40, v41, v40
	v_mul_f32_e32 v41, v49, v49
	v_fmac_f32_e32 v41, v48, v48
	v_add_f32_e32 v48, v41, v40
	s_waitcnt vmcnt(12)
	v_mov_b64_e32 v[40:41], v[186:187]
	v_mov_b64_e32 v[42:43], v[188:189]
	v_lshlrev_b32_e32 v44, 16, v40
	v_and_b32_e32 v45, 0xffff0000, v40
	v_lshlrev_b32_e32 v40, 16, v41
	v_and_b32_e32 v41, 0xffff0000, v41
	v_lshlrev_b32_e32 v46, 16, v42
	v_and_b32_e32 v47, 0xffff0000, v42
	v_lshlrev_b32_e32 v42, 16, v43
	v_and_b32_e32 v43, 0xffff0000, v43
	v_pk_add_f32 v[38:39], v[38:39], v[40:41]
	v_pk_add_f32 v[36:37], v[36:37], v[44:45]
	v_pk_add_f32 v[40:41], v[34:35], v[42:43]
	v_pk_add_f32 v[42:43], v[32:33], v[46:47]
	v_cvt_pk_bf16_f32 v32, v36, v37
	v_cvt_pk_bf16_f32 v33, v38, v39
	v_cvt_pk_bf16_f32 v34, v42, v43
	v_cvt_pk_bf16_f32 v35, v40, v41
	global_store_dwordx4 v[52:53], v[32:35], off offset:256
	s_nop 1
	v_mul_f32_e32 v32, v37, v37
	v_mul_f32_e32 v33, v39, v39
	v_fmac_f32_e32 v32, v36, v36
	v_fmac_f32_e32 v33, v38, v38
	v_add_f32_e32 v32, v32, v33
	v_mul_f32_e32 v33, v43, v43
	v_fmac_f32_e32 v33, v42, v42
	v_add_f32_e32 v32, v33, v32
	v_mul_f32_e32 v33, v41, v41
	v_fmac_f32_e32 v33, v40, v40
	v_add_f32_e32 v32, v33, v32
	v_add_f32_e32 v32, v48, v32
	ds_bpermute_b32 v33, v207, v32
	s_waitcnt lgkmcnt(0)
	v_add_f32_e32 v32, v32, v33
	ds_bpermute_b32 v33, v208, v32
	s_and_saveexec_b64 s[0:1], s[36:37]
	s_cbranch_execz .LBB0_2936
	s_waitcnt lgkmcnt(0)
	v_add_f32_e32 v32, v32, v33
	v_mul_f32_e32 v32, 0x49800000, v32
	v_trunc_f32_e32 v32, v32
	v_mul_f32_e32 v33, 0x2f800000, v32
	v_floor_f32_e32 v33, v33
	v_fmac_f32_e32 v32, 0xcf800000, v33
	v_cvt_u32_f32_e32 v32, v32
	v_cvt_u32_f32_e32 v33, v33
	global_atomic_add_x2 v[114:115], v[32:33], off offset:1152
; DI unsigned pk2(float lo, float hi) { f32x2 v = {lo, hi}; bf16x2_t b = __builtin_convertvector(v, bf16x2_t); return __builtin_bit_cast(unsigned, b); }
; DI void acc_add(acc_t* p, float v, float scale) { atomicAdd(p, (acc_t)(v * scale)); }
;     DI void operator()(const f32x4 (&acc)[2][2][4][2], const Unit& u, int wr, int wc, int fr, int fq) const {
;         const int colb = u.pn * BM + wc * 32 + 8 * fq;
;         EPI_ROWS_BEGIN
;             float ss = 0.f;
; #pragma unroll
;             for (int bj = 0; bj < 2; ++bj) { const int col = colb + bj * HALF; bf16_t* xp = XB + (size_t)row * DM + col;
;                 float xv[8]; unpack8(*(const u32x4*)xp, xv);
;                 const f32x4 x0 = (f32x4){xv[0], xv[1], xv[2], xv[3]} + acc[ai][bj][m][0], x1 = (f32x4){xv[4], xv[5], xv[6], xv[7]} + acc[ai][bj][m][1];
;                 if (Y != nullptr) { float* yp = Y + (size_t)row * DM + col; *(f32x4*)yp = x0; *(f32x4*)(yp + 4) = x1; }
;                 u32x4 w; w.x = pk2(x0[0], x0[1]); w.y = pk2(x0[2], x0[3]); w.z = pk2(x1[0], x1[1]); w.w = pk2(x1[2], x1[3]); *(u32x4*)xp = w;
;                 ss += (x0[0] * x0[0] + x0[1] * x0[1]) + (x0[2] * x0[2] + x0[3] * x0[3]) + (x1[0] * x1[0] + x1[1] * x1[1]) + (x1[2] * x1[2] + x1[3] * x1[3]); }
;             ss += __shfl_xor(ss, 16); ss += __shfl_xor(ss, 32);
;             if (ssq_next != nullptr && fq == 0) acc_add(ssq_next + row, ss, SSQ_SCALE);
;         EPI_ROWS_END
.LBB0_2936:
	s_or_b64 exec, exec, s[0:1]
	v_add_u32_e32 v32, 0xa0, v142
	s_waitcnt lgkmcnt(0)
	v_ashrrev_i32_e32 v33, 31, v32
	v_lshlrev_b64 v[32:33], 11, v[32:33]
	v_lshl_add_u64 v[32:33], s[4:5], 0, v[32:33]
	v_lshl_add_u64 v[36:37], v[140:141], 1, v[32:33]
	s_waitcnt vmcnt(11)
	v_mov_b64_e32 v[32:33], v[190:191]
	v_mov_b64_e32 v[34:35], v[192:193]
	v_lshlrev_b32_e32 v38, 16, v32
	v_and_b32_e32 v39, 0xffff0000, v32
	v_lshlrev_b32_e32 v32, 16, v33
	v_and_b32_e32 v33, 0xffff0000, v33
	v_lshlrev_b32_e32 v40, 16, v34
	v_and_b32_e32 v41, 0xffff0000, v34
	v_lshlrev_b32_e32 v34, 16, v35
	v_and_b32_e32 v35, 0xffff0000, v35
	v_pk_add_f32 v[30:31], v[30:31], v[32:33]
	v_pk_add_f32 v[28:29], v[28:29], v[38:39]
	v_pk_add_f32 v[32:33], v[26:27], v[34:35]
	v_pk_add_f32 v[34:35], v[24:25], v[40:41]
	v_cvt_pk_bf16_f32 v24, v28, v29
	v_cvt_pk_bf16_f32 v25, v30, v31
	v_cvt_pk_bf16_f32 v26, v34, v35
	v_cvt_pk_bf16_f32 v27, v32, v33
	global_store_dwordx4 v[36:37], v[24:27], off
	s_nop 1
	v_mul_f32_e32 v24, v29, v29
	v_mul_f32_e32 v25, v31, v31
	v_fmac_f32_e32 v24, v28, v28
	v_fmac_f32_e32 v25, v30, v30
	v_add_f32_e32 v24, v24, v25
	v_mul_f32_e32 v25, v35, v35
	v_fmac_f32_e32 v25, v34, v34
	v_add_f32_e32 v24, v25, v24
	v_mul_f32_e32 v25, v33, v33
	v_fmac_f32_e32 v25, v32, v32
	v_add_f32_e32 v32, v25, v24
	s_waitcnt vmcnt(10)
	v_mov_b64_e32 v[24:25], v[194:195]
	v_mov_b64_e32 v[26:27], v[196:197]
	v_lshlrev_b32_e32 v28, 16, v24
	v_and_b32_e32 v29, 0xffff0000, v24
	v_lshlrev_b32_e32 v24, 16, v25
	v_and_b32_e32 v25, 0xffff0000, v25
	v_lshlrev_b32_e32 v30, 16, v26
	v_and_b32_e32 v31, 0xffff0000, v26
	v_lshlrev_b32_e32 v26, 16, v27
	v_and_b32_e32 v27, 0xffff0000, v27
	v_pk_add_f32 v[22:23], v[22:23], v[24:25]
	v_pk_add_f32 v[20:21], v[20:21], v[28:29]
	v_pk_add_f32 v[24:25], v[18:19], v[26:27]
	v_pk_add_f32 v[26:27], v[16:17], v[30:31]
	v_cvt_pk_bf16_f32 v16, v20, v21
	v_cvt_pk_bf16_f32 v17, v22, v23
	v_cvt_pk_bf16_f32 v18, v26, v27
	v_cvt_pk_bf16_f32 v19, v24, v25
	global_store_dwordx4 v[36:37], v[16:19], off offset:256
	s_nop 1
	v_mul_f32_e32 v16, v21, v21
	v_mul_f32_e32 v17, v23, v23
	v_fmac_f32_e32 v16, v20, v20
	v_fmac_f32_e32 v17, v22, v22
	v_add_f32_e32 v16, v16, v17
	v_mul_f32_e32 v17, v27, v27
	v_fmac_f32_e32 v17, v26, v26
	v_add_f32_e32 v16, v17, v16
	v_mul_f32_e32 v17, v25, v25
	v_fmac_f32_e32 v17, v24, v24
	v_add_f32_e32 v16, v17, v16
	v_add_f32_e32 v16, v32, v16
	ds_bpermute_b32 v17, v207, v16
	s_waitcnt lgkmcnt(0)
	v_add_f32_e32 v16, v16, v17
	ds_bpermute_b32 v17, v208, v16
	s_and_saveexec_b64 s[0:1], s[36:37]
	s_cbranch_execz .LBB0_2938
	s_waitcnt lgkmcnt(0)
	v_add_f32_e32 v16, v16, v17
	v_mul_f32_e32 v16, 0x49800000, v16
	v_trunc_f32_e32 v16, v16
	v_mul_f32_e32 v17, 0x2f800000, v16
	v_floor_f32_e32 v17, v17
	v_fmac_f32_e32 v16, 0xcf800000, v17
	v_cvt_u32_f32_e32 v16, v16
	v_cvt_u32_f32_e32 v17, v17
	global_atomic_add_x2 v[114:115], v[16:17], off offset:1280
.LBB0_2938:
	s_or_b64 exec, exec, s[0:1]
	v_add_u32_e32 v16, 0xb0, v142
	s_waitcnt lgkmcnt(0)
	v_ashrrev_i32_e32 v17, 31, v16
	v_lshlrev_b64 v[16:17], 11, v[16:17]
	v_lshl_add_u64 v[16:17], s[4:5], 0, v[16:17]
	v_lshl_add_u64 v[20:21], v[140:141], 1, v[16:17]
	s_waitcnt vmcnt(9)
	v_mov_b64_e32 v[16:17], v[198:199]
	v_mov_b64_e32 v[18:19], v[200:201]
	v_lshlrev_b32_e32 v22, 16, v16
	v_and_b32_e32 v23, 0xffff0000, v16
	v_lshlrev_b32_e32 v16, 16, v17
	v_and_b32_e32 v17, 0xffff0000, v17
	v_lshlrev_b32_e32 v24, 16, v18
	v_and_b32_e32 v25, 0xffff0000, v18
	v_lshlrev_b32_e32 v18, 16, v19
	v_and_b32_e32 v19, 0xffff0000, v19
	v_pk_add_f32 v[14:15], v[14:15], v[16:17]
	v_pk_add_f32 v[12:13], v[12:13], v[22:23]
	v_pk_add_f32 v[16:17], v[10:11], v[18:19]
	v_pk_add_f32 v[18:19], v[8:9], v[24:25]
	v_cvt_pk_bf16_f32 v8, v12, v13
	v_cvt_pk_bf16_f32 v9, v14, v15
	v_cvt_pk_bf16_f32 v10, v18, v19
	v_cvt_pk_bf16_f32 v11, v16, v17
	global_store_dwordx4 v[20:21], v[8:11], off
	s_nop 1
	v_mul_f32_e32 v8, v13, v13
	v_mul_f32_e32 v9, v15, v15
	v_fmac_f32_e32 v8, v12, v12
	v_fmac_f32_e32 v9, v14, v14
	v_add_f32_e32 v8, v8, v9
	v_mul_f32_e32 v9, v19, v19
	v_fmac_f32_e32 v9, v18, v18
	v_add_f32_e32 v8, v9, v8
	v_mul_f32_e32 v9, v17, v17
	v_fmac_f32_e32 v9, v16, v16
	v_add_f32_e32 v16, v9, v8
	s_waitcnt vmcnt(8)
	v_mov_b64_e32 v[8:9], v[202:203]
	v_mov_b64_e32 v[10:11], v[204:205]
	v_lshlrev_b32_e32 v12, 16, v8
	v_and_b32_e32 v13, 0xffff0000, v8
	v_lshlrev_b32_e32 v8, 16, v9
	v_and_b32_e32 v9, 0xffff0000, v9
	v_lshlrev_b32_e32 v14, 16, v10
	v_and_b32_e32 v15, 0xffff0000, v10
	v_lshlrev_b32_e32 v10, 16, v11
	v_and_b32_e32 v11, 0xffff0000, v11
	v_pk_add_f32 v[6:7], v[6:7], v[8:9]
	v_pk_add_f32 v[4:5], v[4:5], v[12:13]
	v_pk_add_f32 v[8:9], v[2:3], v[10:11]
	v_pk_add_f32 v[10:11], v[0:1], v[14:15]
	v_cvt_pk_bf16_f32 v0, v4, v5
	v_cvt_pk_bf16_f32 v1, v6, v7
	v_cvt_pk_bf16_f32 v2, v10, v11
	v_cvt_pk_bf16_f32 v3, v8, v9
	global_store_dwordx4 v[20:21], v[0:3], off offset:256
	s_nop 1
	v_mul_f32_e32 v0, v5, v5
	v_mul_f32_e32 v1, v7, v7
	v_fmac_f32_e32 v0, v4, v4
	v_fmac_f32_e32 v1, v6, v6
	v_add_f32_e32 v0, v0, v1
	v_mul_f32_e32 v1, v11, v11
	v_fmac_f32_e32 v1, v10, v10
	v_add_f32_e32 v0, v1, v0
	v_mul_f32_e32 v1, v9, v9
	v_fmac_f32_e32 v1, v8, v8
	v_add_f32_e32 v0, v1, v0
	v_add_f32_e32 v0, v16, v0
	ds_bpermute_b32 v1, v207, v0
	s_waitcnt lgkmcnt(0)
	v_add_f32_e32 v0, v0, v1
	ds_bpermute_b32 v1, v208, v0
	s_and_saveexec_b64 s[0:1], s[36:37]
	s_cbranch_execz .LBB0_2940
	s_waitcnt lgkmcnt(0)
	v_add_f32_e32 v0, v0, v1
	v_mul_f32_e32 v0, 0x49800000, v0
	v_trunc_f32_e32 v0, v0
	v_mul_f32_e32 v1, 0x2f800000, v0
	v_floor_f32_e32 v1, v1
	v_fmac_f32_e32 v0, 0xcf800000, v1
	v_cvt_u32_f32_e32 v0, v0
	v_cvt_u32_f32_e32 v1, v1
	global_atomic_add_x2 v[114:115], v[0:1], off offset:1408

; DI float silu_f(float x) { return x * __builtin_amdgcn_rcpf(1.f + __builtin_amdgcn_exp2f(-LOG2E * x)); }
; DI float rstd_of(float ssq, float inv_n) { return 1.0f / sqrtf(ssq * inv_n + EPS); }
; DI float acc_get_i(const acc_t* base, unsigned idx, float inv_scale) { return (float)(*(const acc_t*)((const char*)base + idx * 8u)) * inv_scale; }
;     DI void operator()(const f32x4 (&acc)[2][2][4][2], const Unit& u, int wr, int wc, int fr, int fq) const {
;     ...
;         const int src1 = (fq << 4) | ((fr + 15) & 15), src2 = (fq << 4) | ((fr + 14) & 15);
; #pragma unroll
;         for (int n = 0; n < 2; ++n) {
;             const int c4 = c8 + 4 * n;
;             const f32x4 w0 = *(const f32x4*)(cw + c4), w1 = *(const f32x4*)(cw + DFF + c4), w2 = *(const f32x4*)(cw + 2 * DFF + c4), cbv = *(const f32x4*)(cb + c4);
; #pragma unroll
;             for (int ai = 0; ai < 2; ++ai) {
;                 f32x4 pg = {0.f, 0.f, 0.f, 0.f};
; #pragma unroll
;                 for (int m = 0; m < 4; ++m) { const int row = u.pm * BM + ai * HALF + wr * 64 + m * 16 + fr;
;                     const float rs = rstd_of(acc_get_i(ssq, (unsigned)row, 1.0f / SSQ_SCALE), 1.0f / DM);
;                     const f32x4 g = acc[ai][0][m][n] * rs, up = acc[ai][1][m][n] * rs;
;                     f32x4 a;
; #pragma unroll
;                     for (int j = 0; j < 4; ++j) { const float s1 = __shfl(fr == 15 ? pg[j] : g[j], src1), s2 = __shfl(fr >= 14 ? pg[j] : g[j], src2);
;                         a[j] = silu_f(cbv[j] + w0[j] * s2 + w1[j] * s1 + w2[j] * g[j]) * up[j]; }
.LBB0_3093:
	s_lshl_b32 s15, s0, 8
	s_add_i32 s15, s15, s80
	v_or_b32_e32 v194, s15, v209
	v_lshlrev_b32_e32 v96, 3, v194
	v_lshlrev_b64 v[142:143], 2, v[176:177]
	v_lshl_add_u64 v[178:179], s[54:55], 0, v[142:143]
	v_lshl_add_u64 v[134:135], s[62:63], 0, v[142:143]
	v_lshl_add_u64 v[138:139], s[64:65], 0, v[142:143]
	v_lshl_add_u64 v[180:181], s[56:57], 0, v[142:143]
	global_load_dwordx4 v[130:133], v[178:179], off
	global_load_dwordx4 v[142:145], v[180:181], off
	v_mul_lo_u32 v218, v194, s90
	global_load_dwordx4 v[134:137], v[134:135], off
	global_load_dwordx2 v[236:237], v96, s[48:49]
	global_load_dwordx2 v[238:239], v96, s[48:49] offset:128
	global_load_dwordx2 v[240:241], v96, s[48:49] offset:256
	global_load_dwordx2 v[242:243], v96, s[48:49] offset:384
	global_load_dwordx2 v[246:247], v96, s[48:49] offset:1024
	s_waitcnt vmcnt(0)
	v_ffbh_u32_e32 v250, v237
	v_min_u32_e32 v250, 32, v250
	v_lshlrev_b64 v[236:237], v250, v[236:237]
	v_min_u32_e32 v236, 1, v236
	v_or_b32_e32 v236, v237, v236
	v_cvt_f32_u32_e32 v236, v236
	v_sub_u32_e32 v237, 32, v250
	v_ldexp_f32 v236, v236, v237
	v_mul_f32_e32 v236, 0x35800000, v236
	v_fmamk_f32 v236, v236, 0x3a800000, v222
	v_rsq_f32_e32 v237, v236
	s_nop 0
	v_mul_f32_e32 v250, v236, v237
	v_fma_f32 v250, -v250, v237, 1.0
	v_mul_f32_e32 v250, 0.5, v250
	v_fmac_f32_e32 v237, v250, v237
	v_ffbh_u32_e32 v250, v239
	v_min_u32_e32 v250, 32, v250
	v_lshlrev_b64 v[238:239], v250, v[238:239]
	v_min_u32_e32 v238, 1, v238
	v_or_b32_e32 v238, v239, v238
	v_cvt_f32_u32_e32 v238, v238
	v_sub_u32_e32 v239, 32, v250
	v_ldexp_f32 v238, v238, v239
	v_mul_f32_e32 v238, 0x35800000, v238
	v_fmamk_f32 v238, v238, 0x3a800000, v222
	v_rsq_f32_e32 v239, v238
	s_nop 0
	v_mul_f32_e32 v250, v238, v239
	v_fma_f32 v250, -v250, v239, 1.0
	v_mul_f32_e32 v250, 0.5, v250
	v_fmac_f32_e32 v239, v250, v239
	v_ffbh_u32_e32 v250, v241
	v_min_u32_e32 v250, 32, v250
	v_lshlrev_b64 v[240:241], v250, v[240:241]
	v_min_u32_e32 v240, 1, v240
	v_or_b32_e32 v240, v241, v240
	v_cvt_f32_u32_e32 v240, v240
	v_sub_u32_e32 v241, 32, v250
	v_ldexp_f32 v240, v240, v241
	v_mul_f32_e32 v240, 0x35800000, v240
	v_fmamk_f32 v240, v240, 0x3a800000, v222
	v_rsq_f32_e32 v241, v240
	s_nop 0
	v_mul_f32_e32 v250, v240, v241
	v_fma_f32 v250, -v250, v241, 1.0
	v_mul_f32_e32 v250, 0.5, v250
	v_fmac_f32_e32 v241, v250, v241
	v_ffbh_u32_e32 v250, v243
	v_min_u32_e32 v250, 32, v250
	v_lshlrev_b64 v[242:243], v250, v[242:243]
	v_min_u32_e32 v242, 1, v242
	v_or_b32_e32 v242, v243, v242
	v_cvt_f32_u32_e32 v242, v242
	v_sub_u32_e32 v243, 32, v250
	v_ldexp_f32 v242, v242, v243
	v_mul_f32_e32 v242, 0x35800000, v242
	v_fmamk_f32 v242, v242, 0x3a800000, v222
	v_rsq_f32_e32 v243, v242
	s_nop 0
	v_mul_f32_e32 v250, v242, v243
	v_fma_f32 v250, -v250, v243, 1.0
	v_mul_f32_e32 v250, 0.5, v250
	v_fmac_f32_e32 v243, v250, v243
	v_ffbh_u32_e32 v250, v247
	v_min_u32_e32 v250, 32, v250
	v_lshlrev_b64 v[246:247], v250, v[246:247]
	v_min_u32_e32 v246, 1, v246
	v_or_b32_e32 v246, v247, v246
	v_cvt_f32_u32_e32 v246, v246
	v_sub_u32_e32 v247, 32, v250
	v_ldexp_f32 v246, v246, v247
	v_mul_f32_e32 v246, 0x35800000, v246
	v_fmamk_f32 v246, v246, 0x3a800000, v222
	v_rsq_f32_e32 v247, v246
	s_nop 0
	v_mul_f32_e32 v250, v246, v247
	v_fma_f32 v250, -v250, v247, 1.0
	v_mul_f32_e32 v250, 0.5, v250
	v_fmac_f32_e32 v247, v250, v247
	v_mov_b32_e32 v236, v237
	v_mov_b32_e32 v237, v239
	v_mov_b32_e32 v238, v241
	v_mov_b32_e32 v239, v243
	v_mov_b32_e32 v240, v247
	global_load_dwordx2 v[242:243], v96, s[48:49] offset:1152
	global_load_dwordx2 v[246:247], v96, s[48:49] offset:1280
	global_load_dwordx2 v[250:251], v96, s[48:49] offset:1408
	s_waitcnt vmcnt(0)
	v_ffbh_u32_e32 v241, v243
	v_min_u32_e32 v241, 32, v241
	v_lshlrev_b64 v[242:243], v241, v[242:243]
	v_min_u32_e32 v242, 1, v242
	v_or_b32_e32 v242, v243, v242
	v_cvt_f32_u32_e32 v242, v242
	v_sub_u32_e32 v243, 32, v241
	v_ldexp_f32 v242, v242, v243
	v_mul_f32_e32 v242, 0x35800000, v242
	v_fmamk_f32 v242, v242, 0x3a800000, v222
	v_rsq_f32_e32 v243, v242
	s_nop 0
	v_mul_f32_e32 v241, v242, v243
	v_fma_f32 v241, -v241, v243, 1.0
	v_mul_f32_e32 v241, 0.5, v241
	v_fmac_f32_e32 v243, v241, v243
	v_ffbh_u32_e32 v241, v247
	v_min_u32_e32 v241, 32, v241
	v_lshlrev_b64 v[246:247], v241, v[246:247]
	v_min_u32_e32 v246, 1, v246
	v_or_b32_e32 v246, v247, v246
	v_cvt_f32_u32_e32 v246, v246
	v_sub_u32_e32 v247, 32, v241
	v_ldexp_f32 v246, v246, v247
	v_mul_f32_e32 v246, 0x35800000, v246
	v_fmamk_f32 v246, v246, 0x3a800000, v222
	v_rsq_f32_e32 v247, v246
	s_nop 0
	v_mul_f32_e32 v241, v246, v247
	v_fma_f32 v241, -v241, v247, 1.0
	v_mul_f32_e32 v241, 0.5, v241
	v_fmac_f32_e32 v247, v241, v247
	v_ffbh_u32_e32 v241, v251
	v_min_u32_e32 v241, 32, v241
	v_lshlrev_b64 v[250:251], v241, v[250:251]
	v_min_u32_e32 v250, 1, v250
	v_or_b32_e32 v250, v251, v250
	v_cvt_f32_u32_e32 v250, v250
	v_sub_u32_e32 v251, 32, v241
	v_ldexp_f32 v250, v250, v251
	v_mul_f32_e32 v250, 0x35800000, v250
	v_fmamk_f32 v250, v250, 0x3a800000, v222
	v_rsq_f32_e32 v251, v250
	s_nop 0
	v_mul_f32_e32 v241, v250, v251
	v_fma_f32 v241, -v241, v251, 1.0
	v_mul_f32_e32 v241, 0.5, v241
	v_fmac_f32_e32 v251, v241, v251
	v_mov_b32_e32 v241, v243
	v_mov_b32_e32 v242, v247
	v_mov_b32_e32 v243, v251
	s_waitcnt vmcnt(0)
	global_load_dwordx4 v[138:141], v[138:139], off
	v_mov_b32_e32 v148, v236
	v_pk_mul_f32 v[186:187], v[126:127], v[148:149] op_sel_hi:[1,0]
	v_pk_mul_f32 v[184:185], v[128:129], v[148:149] op_sel_hi:[1,0]
	v_cndmask_b32_e64 v150, v186, 0, s[36:37]
	ds_bpermute_b32 v188, v213, v150
	v_cndmask_b32_e64 v150, v186, 0, s[38:39]
	ds_bpermute_b32 v192, v214, v150
	v_cndmask_b32_e64 v150, v187, 0, s[36:37]
	ds_bpermute_b32 v189, v213, v150
	v_cndmask_b32_e64 v150, v187, 0, s[38:39]
	ds_bpermute_b32 v193, v214, v150
	v_cndmask_b32_e64 v150, v184, 0, s[36:37]
	ds_bpermute_b32 v182, v213, v150
	v_cndmask_b32_e64 v150, v184, 0, s[38:39]
	ds_bpermute_b32 v190, v214, v150
	v_cndmask_b32_e64 v150, v185, 0, s[36:37]
	ds_bpermute_b32 v183, v213, v150
	v_cndmask_b32_e64 v150, v185, 0, s[38:39]
	ds_bpermute_b32 v191, v214, v150
	v_pk_mul_f32 v[146:147], v[120:121], v[148:149] op_sel_hi:[1,0]
	v_pk_mul_f32 v[148:149], v[118:119], v[148:149] op_sel_hi:[1,0]
	s_and_saveexec_b64 s[0:1], s[40:41]
	s_xor_b64 s[0:1], exec, s[0:1]
	s_cbranch_execz .LBB0_3095
; DI unsigned pk2(float lo, float hi) { f32x2 v = {lo, hi}; bf16x2_t b = __builtin_convertvector(v, bf16x2_t); return __builtin_bit_cast(unsigned, b); }
; DI float silu_f(float x) { return x * __builtin_amdgcn_rcpf(1.f + __builtin_amdgcn_exp2f(-LOG2E * x)); }
; template <class T> DI T* boff(T* base, unsigned byte_off) { return (T*)((char*)base + byte_off); }
;     DI void operator()(const f32x4 (&acc)[2][2][4][2], const Unit& u, int wr, int wc, int fr, int fq) const {
;     ...
;                     for (int j = 0; j < 4; ++j) { const float s1 = __shfl(fr == 15 ? pg[j] : g[j], src1), s2 = __shfl(fr >= 14 ? pg[j] : g[j], src2);
;                         a[j] = silu_f(cbv[j] + w0[j] * s2 + w1[j] * s1 + w2[j] * g[j]) * up[j]; }
;                     u32x2 gw; gw.x = pk2(g[0], g[1]); gw.y = pk2(g[2], g[3]);
;                     if (m == 0 && fr < 2) {
;                         *boff((u32x2*)GS, (unsigned)(((row >> 6) * 4 + 2 + fr) * DFF + c4) * 2u) = gw;
;                         u32x2 uw; uw.x = pk2(up[0], up[1]); uw.y = pk2(up[2], up[3]); *boff((u32x2*)US, (unsigned)(((row >> 6) * 2 + fr) * DFF + c4) * 2u) = uw;
;                     } else { u32x2 w; w.x = pk2(a[0], a[1]); w.y = pk2(a[2], a[3]); *boff((u32x2*)A2, (unsigned)(row * DFF + c4) * 2u) = w; }
	s_waitcnt lgkmcnt(4)
	v_pk_fma_f32 v[150:151], v[130:131], v[192:193], v[142:143]
	s_nop 0
	v_pk_fma_f32 v[150:151], v[134:135], v[188:189], v[150:151]
	s_waitcnt lgkmcnt(0)
	v_pk_fma_f32 v[188:189], v[132:133], v[190:191], v[144:145]
	s_waitcnt vmcnt(0)
	v_pk_fma_f32 v[150:151], v[138:139], v[186:187], v[150:151]
	v_pk_fma_f32 v[182:183], v[136:137], v[182:183], v[188:189]
	v_mul_f32_e32 v152, 0xbfb8aa3b, v150
	v_mul_f32_e32 v153, 0xbfb8aa3b, v151
	v_pk_fma_f32 v[182:183], v[140:141], v[184:185], v[182:183]
	v_exp_f32_e32 v152, v152
	v_exp_f32_e32 v153, v153
	v_mul_f32_e32 v188, 0xbfb8aa3b, v182
	v_mul_f32_e32 v189, 0xbfb8aa3b, v183
	v_exp_f32_e32 v188, v188
	v_exp_f32_e32 v189, v189
	v_add_f32_e32 v152, 1.0, v152
	v_add_f32_e32 v153, 1.0, v153
	v_rcp_f32_e32 v152, v152
	v_rcp_f32_e32 v153, v153
	v_add_f32_e32 v188, 1.0, v188
	v_add_f32_e32 v189, 1.0, v189
	v_rcp_f32_e32 v188, v188
	v_rcp_f32_e32 v189, v189
	v_pk_mul_f32 v[150:151], v[150:151], v[152:153]
	s_nop 0
	v_pk_mul_f32 v[148:149], v[148:149], v[150:151]
	v_pk_mul_f32 v[150:151], v[182:183], v[188:189]
	v_cvt_pk_bf16_f32 v148, v148, v149
	v_pk_mul_f32 v[146:147], v[146:147], v[150:151]
	s_nop 0
	v_cvt_pk_bf16_f32 v149, v146, v147
	v_add_lshl_u32 v146, v218, v176, 1
	global_store_dwordx2 v146, v[148:149], s[46:47]

; DI unsigned pk2(float lo, float hi) { f32x2 v = {lo, hi}; bf16x2_t b = __builtin_convertvector(v, bf16x2_t); return __builtin_bit_cast(unsigned, b); }
; DI float silu_f(float x) { return x * __builtin_amdgcn_rcpf(1.f + __builtin_amdgcn_exp2f(-LOG2E * x)); }
; DI float rstd_of(float ssq, float inv_n) { return 1.0f / sqrtf(ssq * inv_n + EPS); }
; DI float acc_get_i(const acc_t* base, unsigned idx, float inv_scale) { return (float)(*(const acc_t*)((const char*)base + idx * 8u)) * inv_scale; }
; template <class T> DI T* boff(T* base, unsigned byte_off) { return (T*)((char*)base + byte_off); }
;     DI void operator()(const f32x4 (&acc)[2][2][4][2], const Unit& u, int wr, int wc, int fr, int fq) const {
;     ...
;                 for (int m = 0; m < 4; ++m) { const int row = u.pm * BM + ai * HALF + wr * 64 + m * 16 + fr;
;                     const float rs = rstd_of(acc_get_i(ssq, (unsigned)row, 1.0f / SSQ_SCALE), 1.0f / DM);
;                     const f32x4 g = acc[ai][0][m][n] * rs, up = acc[ai][1][m][n] * rs;
;                     f32x4 a;
; #pragma unroll
;                     for (int j = 0; j < 4; ++j) { const float s1 = __shfl(fr == 15 ? pg[j] : g[j], src1), s2 = __shfl(fr >= 14 ? pg[j] : g[j], src2);
;                         a[j] = silu_f(cbv[j] + w0[j] * s2 + w1[j] * s1 + w2[j] * g[j]) * up[j]; }
;                     u32x2 gw; gw.x = pk2(g[0], g[1]); gw.y = pk2(g[2], g[3]);
;                     if (m == 0 && fr < 2) {
;                         *boff((u32x2*)GS, (unsigned)(((row >> 6) * 4 + 2 + fr) * DFF + c4) * 2u) = gw;
;                         u32x2 uw; uw.x = pk2(up[0], up[1]); uw.y = pk2(up[2], up[3]); *boff((u32x2*)US, (unsigned)(((row >> 6) * 2 + fr) * DFF + c4) * 2u) = uw;
;                     } else { u32x2 w; w.x = pk2(a[0], a[1]); w.y = pk2(a[2], a[3]); *boff((u32x2*)A2, (unsigned)(row * DFF + c4) * 2u) = w; }
;                     if (m == 3 && fr >= 14) {
;                         *boff((u32x2*)GS, (unsigned)(((row >> 6) * 4 + (fr - 14)) * DFF + c4) * 2u) = gw;
;                         if ((row & (SEQ - 1)) >= SEQ - 2) *boff((f32x4*)fcp, (unsigned)(((row >> 11) * 2 + ((row & (SEQ - 1)) - (SEQ - 2))) * DFF + c4) * 4u) = g;
;                     }
;                     pg = g;
;                     asm volatile("" ::: "memory");
.LBB0_3097:
	s_or_b64 exec, exec, s[0:1]
	v_or_b32_e32 v192, 16, v194
	v_add_u32_e32 v146, s2, v212
	v_lshlrev_b32_e32 v182, 3, v192
	v_mul_lo_u32 v217, v146, s90
	s_ashr_i32 s0, s15, 10
	s_and_b32 s14, s0, 0x3ffffffe
	s_add_i32 s14, s14, 0x3ffff802
	v_mov_b32_e32 v150, v237
	v_pk_mul_f32 v[148:149], v[110:111], v[150:151] op_sel_hi:[1,0]
	v_pk_mul_f32 v[146:147], v[112:113], v[150:151] op_sel_hi:[1,0]
	v_cndmask_b32_e64 v151, v148, v186, s[36:37]
	ds_bpermute_b32 v152, v213, v151
	v_cndmask_b32_e64 v151, v148, v186, s[38:39]
	ds_bpermute_b32 v186, v214, v151
	v_cndmask_b32_e64 v151, v149, v187, s[36:37]
	ds_bpermute_b32 v153, v213, v151
	v_cndmask_b32_e64 v151, v149, v187, s[38:39]
	ds_bpermute_b32 v187, v214, v151
	v_cndmask_b32_e64 v151, v146, v184, s[36:37]
	ds_bpermute_b32 v188, v213, v151
	v_cndmask_b32_e64 v151, v146, v184, s[38:39]
	ds_bpermute_b32 v184, v214, v151
	s_waitcnt lgkmcnt(2)
	v_pk_fma_f32 v[186:187], v[130:131], v[186:187], v[142:143]
	v_cndmask_b32_e64 v151, v147, v185, s[36:37]
	v_pk_fma_f32 v[152:153], v[134:135], v[152:153], v[186:187]
	ds_bpermute_b32 v189, v213, v151
	v_pk_fma_f32 v[152:153], v[138:139], v[148:149], v[152:153]
	v_cndmask_b32_e64 v151, v147, v185, s[38:39]
	v_mul_f32_e32 v186, 0xbfb8aa3b, v152
	v_mul_f32_e32 v187, 0xbfb8aa3b, v153
	v_exp_f32_e32 v186, v186
	v_exp_f32_e32 v187, v187
	ds_bpermute_b32 v185, v214, v151
	v_pk_mul_f32 v[190:191], v[104:105], v[150:151] op_sel_hi:[1,0]
	v_add_f32_e32 v186, 1.0, v186
	v_add_f32_e32 v187, 1.0, v187
	v_rcp_f32_e32 v186, v186
	v_rcp_f32_e32 v187, v187
	v_pk_mul_f32 v[150:151], v[102:103], v[150:151] op_sel_hi:[1,0]
	v_pk_mul_f32 v[152:153], v[152:153], v[186:187]
	s_nop 0
	v_pk_mul_f32 v[150:151], v[150:151], v[152:153]
	s_waitcnt lgkmcnt(0)
	v_pk_fma_f32 v[152:153], v[132:133], v[184:185], v[144:145]
	v_mul_lo_u32 v187, v192, s90
	v_pk_fma_f32 v[152:153], v[136:137], v[188:189], v[152:153]
	v_cvt_pk_bf16_f32 v150, v150, v151
	v_pk_fma_f32 v[152:153], v[140:141], v[146:147], v[152:153]
	v_add_u32_e32 v220, 0xb000, v187
	v_mul_f32_e32 v184, 0xbfb8aa3b, v152
	v_mul_f32_e32 v185, 0xbfb8aa3b, v153
	v_exp_f32_e32 v184, v184
	v_exp_f32_e32 v185, v185
	v_add_u32_e32 v230, 0x16000, v187
	v_add_f32_e32 v184, 1.0, v184
	v_add_f32_e32 v185, 1.0, v185
	v_rcp_f32_e32 v184, v184
	v_rcp_f32_e32 v185, v185
	s_nop 0
	v_pk_mul_f32 v[152:153], v[152:153], v[184:185]
	s_nop 0
	v_pk_mul_f32 v[152:153], v[190:191], v[152:153]
	v_lshl_or_b32 v184, v194, 3, v229
	v_cvt_pk_bf16_f32 v151, v152, v153
	v_add_lshl_u32 v152, v187, v176, 1
	global_store_dwordx2 v152, v[150:151], s[46:47]
	v_mov_b32_e32 v150, v238
	v_pk_mul_f32 v[190:191], v[92:93], v[150:151] op_sel_hi:[1,0]
	v_pk_mul_f32 v[188:189], v[94:95], v[150:151] op_sel_hi:[1,0]
	v_cndmask_b32_e64 v151, v190, v148, s[36:37]
	ds_bpermute_b32 v152, v213, v151
	v_cndmask_b32_e64 v148, v190, v148, s[38:39]
	v_cndmask_b32_e64 v151, v191, v149, s[36:37]
	v_cndmask_b32_e64 v149, v191, v149, s[38:39]
	ds_bpermute_b32 v148, v214, v148
	ds_bpermute_b32 v149, v214, v149
	ds_bpermute_b32 v153, v213, v151
	v_cndmask_b32_e64 v151, v188, v146, s[36:37]
	ds_bpermute_b32 v192, v213, v151
	v_cndmask_b32_e64 v146, v188, v146, s[38:39]
	s_waitcnt lgkmcnt(2)
	v_pk_fma_f32 v[148:149], v[130:131], v[148:149], v[142:143]
	v_cndmask_b32_e64 v151, v189, v147, s[36:37]
	s_waitcnt lgkmcnt(1)
	v_pk_fma_f32 v[148:149], v[134:135], v[152:153], v[148:149]
	v_cndmask_b32_e64 v147, v189, v147, s[38:39]
	v_pk_fma_f32 v[148:149], v[138:139], v[190:191], v[148:149]
	ds_bpermute_b32 v146, v214, v146
	v_mul_f32_e32 v152, 0xbfb8aa3b, v148
	v_mul_f32_e32 v153, 0xbfb8aa3b, v149
	v_exp_f32_e32 v152, v152
	v_exp_f32_e32 v153, v153
	ds_bpermute_b32 v147, v214, v147
	ds_bpermute_b32 v193, v213, v151
	v_add_f32_e32 v152, 1.0, v152
	v_add_f32_e32 v153, 1.0, v153
	v_rcp_f32_e32 v152, v152
	v_rcp_f32_e32 v153, v153
	s_waitcnt lgkmcnt(1)
	v_pk_fma_f32 v[146:147], v[132:133], v[146:147], v[144:145]
	v_pk_mul_f32 v[196:197], v[86:87], v[150:151] op_sel_hi:[1,0]
	s_waitcnt lgkmcnt(0)
	v_pk_fma_f32 v[146:147], v[136:137], v[192:193], v[146:147]
	v_pk_mul_f32 v[150:151], v[84:85], v[150:151] op_sel_hi:[1,0]
	v_pk_mul_f32 v[148:149], v[148:149], v[152:153]
	v_pk_fma_f32 v[146:147], v[140:141], v[188:189], v[146:147]
	v_pk_mul_f32 v[148:149], v[150:151], v[148:149]
	v_mul_f32_e32 v150, 0xbfb8aa3b, v146
	v_mul_f32_e32 v151, 0xbfb8aa3b, v147
	v_exp_f32_e32 v150, v150
	v_exp_f32_e32 v151, v151
	v_cvt_pk_bf16_f32 v148, v148, v149
	v_or_b32_e32 v185, 48, v194
	v_add_f32_e32 v150, 1.0, v150
	v_add_f32_e32 v151, 1.0, v151
	v_rcp_f32_e32 v150, v150
	v_rcp_f32_e32 v151, v151
	v_lshlrev_b32_e32 v186, 3, v185
	v_pk_mul_f32 v[146:147], v[146:147], v[150:151]
	s_nop 0
	v_pk_mul_f32 v[146:147], v[196:197], v[146:147]
	s_nop 0
	v_cvt_pk_bf16_f32 v149, v146, v147
	v_add_lshl_u32 v146, v220, v176, 1
	global_store_dwordx2 v146, v[148:149], s[46:47]
	v_mov_b32_e32 v150, v239
	v_pk_mul_f32 v[146:147], v[76:77], v[150:151] op_sel_hi:[1,0]
	v_pk_mul_f32 v[148:149], v[78:79], v[150:151] op_sel_hi:[1,0]
	v_cndmask_b32_e64 v151, v146, v190, s[36:37]
	ds_bpermute_b32 v152, v213, v151
	v_cndmask_b32_e64 v151, v146, v190, s[38:39]
	ds_bpermute_b32 v190, v214, v151
	v_cndmask_b32_e64 v151, v147, v191, s[36:37]
	ds_bpermute_b32 v153, v213, v151
	v_cndmask_b32_e64 v151, v147, v191, s[38:39]
	ds_bpermute_b32 v191, v214, v151
	v_cndmask_b32_e64 v151, v148, v188, s[36:37]
	ds_bpermute_b32 v192, v213, v151
	v_cndmask_b32_e64 v151, v148, v188, s[38:39]
	ds_bpermute_b32 v188, v214, v151
	s_waitcnt lgkmcnt(2)
; DI unsigned pk2(float lo, float hi) { f32x2 v = {lo, hi}; bf16x2_t b = __builtin_convertvector(v, bf16x2_t); return __builtin_bit_cast(unsigned, b); }
; DI float silu_f(float x) { return x * __builtin_amdgcn_rcpf(1.f + __builtin_amdgcn_exp2f(-LOG2E * x)); }
; DI float rstd_of(float ssq, float inv_n) { return 1.0f / sqrtf(ssq * inv_n + EPS); }
; DI float acc_get_i(const acc_t* base, unsigned idx, float inv_scale) { return (float)(*(const acc_t*)((const char*)base + idx * 8u)) * inv_scale; }
; template <class T> DI T* boff(T* base, unsigned byte_off) { return (T*)((char*)base + byte_off); }
;     DI void operator()(const f32x4 (&acc)[2][2][4][2], const Unit& u, int wr, int wc, int fr, int fq) const {
;     ...
;                 for (int m = 0; m < 4; ++m) { const int row = u.pm * BM + ai * HALF + wr * 64 + m * 16 + fr;
;                     const float rs = rstd_of(acc_get_i(ssq, (unsigned)row, 1.0f / SSQ_SCALE), 1.0f / DM);
;                     const f32x4 g = acc[ai][0][m][n] * rs, up = acc[ai][1][m][n] * rs;
;                     f32x4 a;
; #pragma unroll
;                     for (int j = 0; j < 4; ++j) { const float s1 = __shfl(fr == 15 ? pg[j] : g[j], src1), s2 = __shfl(fr >= 14 ? pg[j] : g[j], src2);
;                         a[j] = silu_f(cbv[j] + w0[j] * s2 + w1[j] * s1 + w2[j] * g[j]) * up[j]; }
;                     u32x2 gw; gw.x = pk2(g[0], g[1]); gw.y = pk2(g[2], g[3]);
;                     if (m == 0 && fr < 2) {
;                         *boff((u32x2*)GS, (unsigned)(((row >> 6) * 4 + 2 + fr) * DFF + c4) * 2u) = gw;
;                         u32x2 uw; uw.x = pk2(up[0], up[1]); uw.y = pk2(up[2], up[3]); *boff((u32x2*)US, (unsigned)(((row >> 6) * 2 + fr) * DFF + c4) * 2u) = uw;
;                     } else { u32x2 w; w.x = pk2(a[0], a[1]); w.y = pk2(a[2], a[3]); *boff((u32x2*)A2, (unsigned)(row * DFF + c4) * 2u) = w; }
;                     if (m == 3 && fr >= 14) {
;                         *boff((u32x2*)GS, (unsigned)(((row >> 6) * 4 + (fr - 14)) * DFF + c4) * 2u) = gw;
;                         if ((row & (SEQ - 1)) >= SEQ - 2) *boff((f32x4*)fcp, (unsigned)(((row >> 11) * 2 + ((row & (SEQ - 1)) - (SEQ - 2))) * DFF + c4) * 4u) = g;
;                     }
;                     pg = g;
;                     asm volatile("" ::: "memory");
	v_pk_fma_f32 v[190:191], v[130:131], v[190:191], v[142:143]
	v_cndmask_b32_e64 v151, v149, v189, s[36:37]
	v_pk_fma_f32 v[152:153], v[134:135], v[152:153], v[190:191]
	ds_bpermute_b32 v193, v213, v151
	v_pk_fma_f32 v[152:153], v[138:139], v[146:147], v[152:153]
	v_cndmask_b32_e64 v151, v149, v189, s[38:39]
	v_mul_f32_e32 v190, 0xbfb8aa3b, v152
	v_mul_f32_e32 v191, 0xbfb8aa3b, v153
	v_exp_f32_e32 v190, v190
	v_exp_f32_e32 v191, v191
	ds_bpermute_b32 v189, v214, v151
	v_pk_mul_f32 v[194:195], v[70:71], v[150:151] op_sel_hi:[1,0]
	v_add_f32_e32 v190, 1.0, v190
	v_add_f32_e32 v191, 1.0, v191
	v_rcp_f32_e32 v190, v190
	v_rcp_f32_e32 v191, v191
	v_pk_mul_f32 v[150:151], v[68:69], v[150:151] op_sel_hi:[1,0]
	v_pk_mul_f32 v[152:153], v[152:153], v[190:191]
	s_nop 0
	v_pk_mul_f32 v[150:151], v[150:151], v[152:153]
	s_waitcnt lgkmcnt(0)
	v_pk_fma_f32 v[152:153], v[132:133], v[188:189], v[144:145]
	s_nop 0
	v_pk_fma_f32 v[152:153], v[136:137], v[192:193], v[152:153]
	s_nop 0
	v_pk_fma_f32 v[152:153], v[140:141], v[148:149], v[152:153]
	s_nop 0
	v_mul_f32_e32 v188, 0xbfb8aa3b, v152
	v_mul_f32_e32 v189, 0xbfb8aa3b, v153
	v_exp_f32_e32 v188, v188
	v_exp_f32_e32 v189, v189
	v_add_f32_e32 v188, 1.0, v188
	v_add_f32_e32 v189, 1.0, v189
	v_rcp_f32_e32 v188, v188
	v_rcp_f32_e32 v189, v189
	s_nop 0
	v_pk_mul_f32 v[152:153], v[152:153], v[188:189]
	s_nop 0
	v_pk_mul_f32 v[152:153], v[194:195], v[152:153]
	v_cvt_pk_bf16_f32 v188, v150, v151
	v_cvt_pk_bf16_f32 v189, v152, v153
	v_add_lshl_u32 v150, v230, v176, 1
	global_store_dwordx2 v150, v[188:189], s[46:47]
	v_and_b32_e32 v189, 0x7ff, v185
	s_and_saveexec_b64 s[0:1], s[38:39]
	s_cbranch_execz .LBB0_3100
	s_movk_i32 s2, 0x7fd
	v_add_lshl_u32 v152, v217, v176, 1
	v_cvt_pk_bf16_f32 v150, v146, v147
	v_cvt_pk_bf16_f32 v151, v148, v149
	v_cmp_lt_u32_e32 vcc, s2, v189
	global_store_dwordx2 v152, v[150:151], s[50:51]
	s_and_b64 exec, exec, vcc
	s_cbranch_execz .LBB0_3100
	v_add_u32_e32 v150, s14, v189
	v_mul_lo_u32 v150, v150, s90
	v_add_lshl_u32 v150, v150, v176, 2
	global_store_dwordx4 v150, v[146:149], s[58:59]
.LBB0_3100:
	s_or_b64 exec, exec, s[0:1]
	s_addk_i32 s15, 0x80
	v_or_b32_e32 v185, s15, v209
	v_lshlrev_b32_e32 v188, 3, v185
	v_mul_lo_u32 v231, v185, s90
	v_mov_b32_e32 v148, v240
	v_pk_mul_f32 v[194:195], v[60:61], v[148:149] op_sel_hi:[1,0]
	v_pk_mul_f32 v[192:193], v[62:63], v[148:149] op_sel_hi:[1,0]
	v_cndmask_b32_e64 v150, v194, 0, s[36:37]
	ds_bpermute_b32 v190, v213, v150
	v_cndmask_b32_e64 v150, v194, 0, s[38:39]
	ds_bpermute_b32 v198, v214, v150
	v_cndmask_b32_e64 v150, v195, 0, s[36:37]
	ds_bpermute_b32 v191, v213, v150
	v_cndmask_b32_e64 v150, v195, 0, s[38:39]
	ds_bpermute_b32 v199, v214, v150
	v_cndmask_b32_e64 v150, v192, 0, s[36:37]
	ds_bpermute_b32 v196, v213, v150
	v_cndmask_b32_e64 v150, v192, 0, s[38:39]
	ds_bpermute_b32 v200, v214, v150
	v_cndmask_b32_e64 v150, v193, 0, s[36:37]
	ds_bpermute_b32 v197, v213, v150
	v_cndmask_b32_e64 v150, v193, 0, s[38:39]
	ds_bpermute_b32 v201, v214, v150
	v_pk_mul_f32 v[146:147], v[54:55], v[148:149] op_sel_hi:[1,0]
	v_pk_mul_f32 v[148:149], v[52:53], v[148:149] op_sel_hi:[1,0]
	s_and_saveexec_b64 s[0:1], s[40:41]
	s_xor_b64 s[0:1], exec, s[0:1]
	s_cbranch_execz .LBB0_3102
	s_waitcnt lgkmcnt(4)
	v_pk_fma_f32 v[150:151], v[130:131], v[198:199], v[142:143]
	s_nop 0
	v_pk_fma_f32 v[150:151], v[134:135], v[190:191], v[150:151]
	s_waitcnt lgkmcnt(0)
	v_pk_fma_f32 v[190:191], v[132:133], v[200:201], v[144:145]
	v_pk_fma_f32 v[150:151], v[138:139], v[194:195], v[150:151]
	v_pk_fma_f32 v[190:191], v[136:137], v[196:197], v[190:191]
	v_mul_f32_e32 v152, 0xbfb8aa3b, v150
	v_mul_f32_e32 v153, 0xbfb8aa3b, v151
	v_pk_fma_f32 v[190:191], v[140:141], v[192:193], v[190:191]
	v_exp_f32_e32 v152, v152
	v_exp_f32_e32 v153, v153
	v_mul_f32_e32 v196, 0xbfb8aa3b, v190
	v_mul_f32_e32 v197, 0xbfb8aa3b, v191
	v_exp_f32_e32 v196, v196
	v_exp_f32_e32 v197, v197
	v_add_f32_e32 v152, 1.0, v152
	v_add_f32_e32 v153, 1.0, v153
	v_rcp_f32_e32 v152, v152
	v_rcp_f32_e32 v153, v153
	v_add_f32_e32 v196, 1.0, v196
	v_add_f32_e32 v197, 1.0, v197
	v_rcp_f32_e32 v196, v196
	v_rcp_f32_e32 v197, v197
	v_pk_mul_f32 v[150:151], v[150:151], v[152:153]
	s_nop 0
	v_pk_mul_f32 v[148:149], v[148:149], v[150:151]
	v_pk_mul_f32 v[150:151], v[190:191], v[196:197]
	v_cvt_pk_bf16_f32 v148, v148, v149
	v_pk_mul_f32 v[146:147], v[146:147], v[150:151]
	s_nop 0
	v_cvt_pk_bf16_f32 v149, v146, v147
	v_add_lshl_u32 v146, v231, v176, 1
	global_store_dwordx2 v146, v[148:149], s[46:47]

; DI unsigned pk2(float lo, float hi) { f32x2 v = {lo, hi}; bf16x2_t b = __builtin_convertvector(v, bf16x2_t); return __builtin_bit_cast(unsigned, b); }
; DI float silu_f(float x) { return x * __builtin_amdgcn_rcpf(1.f + __builtin_amdgcn_exp2f(-LOG2E * x)); }
; DI float rstd_of(float ssq, float inv_n) { return 1.0f / sqrtf(ssq * inv_n + EPS); }
; DI float acc_get_i(const acc_t* base, unsigned idx, float inv_scale) { return (float)(*(const acc_t*)((const char*)base + idx * 8u)) * inv_scale; }
; template <class T> DI T* boff(T* base, unsigned byte_off) { return (T*)((char*)base + byte_off); }
;     DI void operator()(const f32x4 (&acc)[2][2][4][2], const Unit& u, int wr, int wc, int fr, int fq) const {
;     ...
;                 for (int m = 0; m < 4; ++m) { const int row = u.pm * BM + ai * HALF + wr * 64 + m * 16 + fr;
;                     const float rs = rstd_of(acc_get_i(ssq, (unsigned)row, 1.0f / SSQ_SCALE), 1.0f / DM);
;                     const f32x4 g = acc[ai][0][m][n] * rs, up = acc[ai][1][m][n] * rs;
;                     f32x4 a;
; #pragma unroll
;                     for (int j = 0; j < 4; ++j) { const float s1 = __shfl(fr == 15 ? pg[j] : g[j], src1), s2 = __shfl(fr >= 14 ? pg[j] : g[j], src2);
;                         a[j] = silu_f(cbv[j] + w0[j] * s2 + w1[j] * s1 + w2[j] * g[j]) * up[j]; }
;                     u32x2 gw; gw.x = pk2(g[0], g[1]); gw.y = pk2(g[2], g[3]);
;                     if (m == 0 && fr < 2) {
;                         *boff((u32x2*)GS, (unsigned)(((row >> 6) * 4 + 2 + fr) * DFF + c4) * 2u) = gw;
;                         u32x2 uw; uw.x = pk2(up[0], up[1]); uw.y = pk2(up[2], up[3]); *boff((u32x2*)US, (unsigned)(((row >> 6) * 2 + fr) * DFF + c4) * 2u) = uw;
;                     } else { u32x2 w; w.x = pk2(a[0], a[1]); w.y = pk2(a[2], a[3]); *boff((u32x2*)A2, (unsigned)(row * DFF + c4) * 2u) = w; }
;                     if (m == 3 && fr >= 14) {
;                         *boff((u32x2*)GS, (unsigned)(((row >> 6) * 4 + (fr - 14)) * DFF + c4) * 2u) = gw;
;                         if ((row & (SEQ - 1)) >= SEQ - 2) *boff((f32x4*)fcp, (unsigned)(((row >> 11) * 2 + ((row & (SEQ - 1)) - (SEQ - 2))) * DFF + c4) * 4u) = g;
;                     }
;                     pg = g;
;                     asm volatile("" ::: "memory");
.LBB0_3104:
	s_or_b64 exec, exec, s[0:1]
	s_waitcnt lgkmcnt(2)
	v_or_b32_e32 v200, 16, v185
	v_add_u32_e32 v146, s2, v212
	v_lshlrev_b32_e32 v190, 3, v200
	v_mul_lo_u32 v221, v146, s90
	s_ashr_i32 s0, s15, 10
	s_and_b32 s15, s0, 0x3ffffffe
	s_add_i32 s15, s15, 0x3ffff802
	v_mov_b32_e32 v150, v241
	v_pk_mul_f32 v[148:149], v[44:45], v[150:151] op_sel_hi:[1,0]
	v_pk_mul_f32 v[146:147], v[46:47], v[150:151] op_sel_hi:[1,0]
	v_cndmask_b32_e64 v151, v148, v194, s[36:37]
	ds_bpermute_b32 v152, v213, v151
	v_cndmask_b32_e64 v151, v148, v194, s[38:39]
	ds_bpermute_b32 v194, v214, v151
	v_cndmask_b32_e64 v151, v149, v195, s[36:37]
	ds_bpermute_b32 v153, v213, v151
	v_cndmask_b32_e64 v151, v149, v195, s[38:39]
	ds_bpermute_b32 v195, v214, v151
	v_cndmask_b32_e64 v151, v146, v192, s[36:37]
	ds_bpermute_b32 v196, v213, v151
	v_cndmask_b32_e64 v151, v146, v192, s[38:39]
	ds_bpermute_b32 v192, v214, v151
	s_waitcnt lgkmcnt(2)
	v_pk_fma_f32 v[194:195], v[130:131], v[194:195], v[142:143]
	v_cndmask_b32_e64 v151, v147, v193, s[36:37]
	v_pk_fma_f32 v[152:153], v[134:135], v[152:153], v[194:195]
	ds_bpermute_b32 v197, v213, v151
	v_pk_fma_f32 v[152:153], v[138:139], v[148:149], v[152:153]
	v_cndmask_b32_e64 v151, v147, v193, s[38:39]
	v_mul_f32_e32 v194, 0xbfb8aa3b, v152
	v_mul_f32_e32 v195, 0xbfb8aa3b, v153
	v_exp_f32_e32 v194, v194
	v_exp_f32_e32 v195, v195
	ds_bpermute_b32 v193, v214, v151
	v_pk_mul_f32 v[198:199], v[38:39], v[150:151] op_sel_hi:[1,0]
	v_add_f32_e32 v194, 1.0, v194
	v_add_f32_e32 v195, 1.0, v195
	v_rcp_f32_e32 v194, v194
	v_rcp_f32_e32 v195, v195
	v_pk_mul_f32 v[150:151], v[36:37], v[150:151] op_sel_hi:[1,0]
	v_pk_mul_f32 v[152:153], v[152:153], v[194:195]
	s_nop 0
	v_pk_mul_f32 v[150:151], v[150:151], v[152:153]
	s_waitcnt lgkmcnt(0)
	v_pk_fma_f32 v[152:153], v[132:133], v[192:193], v[144:145]
	v_mul_lo_u32 v195, v200, s90
	v_pk_fma_f32 v[152:153], v[136:137], v[196:197], v[152:153]
	v_cvt_pk_bf16_f32 v150, v150, v151
	v_pk_fma_f32 v[152:153], v[140:141], v[146:147], v[152:153]
	v_add_u32_e32 v233, 0xb000, v195
	v_mul_f32_e32 v192, 0xbfb8aa3b, v152
	v_mul_f32_e32 v193, 0xbfb8aa3b, v153
	v_exp_f32_e32 v192, v192
	v_exp_f32_e32 v193, v193
	v_add_u32_e32 v234, 0x16000, v195
	v_add_f32_e32 v192, 1.0, v192
	v_add_f32_e32 v193, 1.0, v193
	v_rcp_f32_e32 v192, v192
	v_rcp_f32_e32 v193, v193
	s_nop 0
	v_pk_mul_f32 v[152:153], v[152:153], v[192:193]
	s_nop 0
	v_pk_mul_f32 v[152:153], v[198:199], v[152:153]
	v_lshl_or_b32 v192, v185, 3, v229
	v_cvt_pk_bf16_f32 v151, v152, v153
	v_add_lshl_u32 v152, v195, v176, 1
	global_store_dwordx2 v152, v[150:151], s[46:47]
	v_or_b32_e32 v185, 48, v185
	v_and_b32_e32 v235, 0x7ff, v185
	v_mov_b32_e32 v150, v242
	v_pk_mul_f32 v[198:199], v[28:29], v[150:151] op_sel_hi:[1,0]
	v_pk_mul_f32 v[196:197], v[30:31], v[150:151] op_sel_hi:[1,0]
	v_cndmask_b32_e64 v151, v198, v148, s[36:37]
	ds_bpermute_b32 v152, v213, v151
	v_cndmask_b32_e64 v148, v198, v148, s[38:39]
	v_cndmask_b32_e64 v151, v199, v149, s[36:37]
	v_cndmask_b32_e64 v149, v199, v149, s[38:39]
	ds_bpermute_b32 v148, v214, v148
	ds_bpermute_b32 v149, v214, v149
	ds_bpermute_b32 v153, v213, v151
	v_cndmask_b32_e64 v151, v196, v146, s[36:37]
	ds_bpermute_b32 v200, v213, v151
	v_cndmask_b32_e64 v146, v196, v146, s[38:39]
	s_waitcnt lgkmcnt(2)
	v_pk_fma_f32 v[148:149], v[130:131], v[148:149], v[142:143]
	v_cndmask_b32_e64 v151, v197, v147, s[36:37]
	s_waitcnt lgkmcnt(1)
	v_pk_fma_f32 v[148:149], v[134:135], v[152:153], v[148:149]
	v_cndmask_b32_e64 v147, v197, v147, s[38:39]
	v_pk_fma_f32 v[148:149], v[138:139], v[198:199], v[148:149]
	ds_bpermute_b32 v146, v214, v146
	v_mul_f32_e32 v152, 0xbfb8aa3b, v148
	v_mul_f32_e32 v153, 0xbfb8aa3b, v149
	v_exp_f32_e32 v152, v152
	v_exp_f32_e32 v153, v153
	ds_bpermute_b32 v147, v214, v147
	ds_bpermute_b32 v201, v213, v151
	v_add_f32_e32 v152, 1.0, v152
	v_add_f32_e32 v153, 1.0, v153
	v_rcp_f32_e32 v152, v152
	v_rcp_f32_e32 v153, v153
	s_waitcnt lgkmcnt(1)
	v_pk_fma_f32 v[146:147], v[132:133], v[146:147], v[144:145]
	v_pk_mul_f32 v[202:203], v[22:23], v[150:151] op_sel_hi:[1,0]
	s_waitcnt lgkmcnt(0)
	v_pk_fma_f32 v[146:147], v[136:137], v[200:201], v[146:147]
	v_pk_mul_f32 v[150:151], v[20:21], v[150:151] op_sel_hi:[1,0]
	v_pk_mul_f32 v[148:149], v[148:149], v[152:153]
	v_pk_fma_f32 v[146:147], v[140:141], v[196:197], v[146:147]
	v_pk_mul_f32 v[148:149], v[150:151], v[148:149]
	v_mul_f32_e32 v150, 0xbfb8aa3b, v146
	v_mul_f32_e32 v151, 0xbfb8aa3b, v147
	v_exp_f32_e32 v150, v150
	v_exp_f32_e32 v151, v151
	v_cvt_pk_bf16_f32 v148, v148, v149
	v_lshlrev_b32_e32 v194, 3, v185
	v_add_f32_e32 v150, 1.0, v150
	v_add_f32_e32 v151, 1.0, v151
	v_rcp_f32_e32 v150, v150
	v_rcp_f32_e32 v151, v151
	s_nop 0
	v_pk_mul_f32 v[146:147], v[146:147], v[150:151]
	s_nop 0
	v_pk_mul_f32 v[146:147], v[202:203], v[146:147]
	s_nop 0
	v_cvt_pk_bf16_f32 v149, v146, v147
	v_add_lshl_u32 v146, v233, v176, 1
	global_store_dwordx2 v146, v[148:149], s[46:47]
	v_mov_b32_e32 v150, v243
	v_pk_mul_f32 v[146:147], v[12:13], v[150:151] op_sel_hi:[1,0]
	v_pk_mul_f32 v[148:149], v[14:15], v[150:151] op_sel_hi:[1,0]
	v_cndmask_b32_e64 v151, v146, v198, s[36:37]
	ds_bpermute_b32 v152, v213, v151
	v_cndmask_b32_e64 v151, v146, v198, s[38:39]
	ds_bpermute_b32 v198, v214, v151
	v_cndmask_b32_e64 v151, v147, v199, s[36:37]
	ds_bpermute_b32 v153, v213, v151
	v_cndmask_b32_e64 v151, v147, v199, s[38:39]
	ds_bpermute_b32 v199, v214, v151
	v_cndmask_b32_e64 v151, v148, v196, s[36:37]
	ds_bpermute_b32 v200, v213, v151
	v_cndmask_b32_e64 v151, v148, v196, s[38:39]
	ds_bpermute_b32 v196, v214, v151
	s_waitcnt lgkmcnt(2)
; DI unsigned pk2(float lo, float hi) { f32x2 v = {lo, hi}; bf16x2_t b = __builtin_convertvector(v, bf16x2_t); return __builtin_bit_cast(unsigned, b); }
; DI float silu_f(float x) { return x * __builtin_amdgcn_rcpf(1.f + __builtin_amdgcn_exp2f(-LOG2E * x)); }
;     DI void operator()(const f32x4 (&acc)[2][2][4][2], const Unit& u, int wr, int wc, int fr, int fq) const {
;     ...
;         for (int n = 0; n < 2; ++n) {
;             const int c4 = c8 + 4 * n;
;             const f32x4 w0 = *(const f32x4*)(cw + c4), w1 = *(const f32x4*)(cw + DFF + c4), w2 = *(const f32x4*)(cw + 2 * DFF + c4), cbv = *(const f32x4*)(cb + c4);
; #pragma unroll
;             for (int ai = 0; ai < 2; ++ai) {
;                 f32x4 pg = {0.f, 0.f, 0.f, 0.f};
; #pragma unroll
;                 for (int m = 0; m < 4; ++m) { const int row = u.pm * BM + ai * HALF + wr * 64 + m * 16 + fr;
;                     const float rs = rstd_of(acc_get_i(ssq, (unsigned)row, 1.0f / SSQ_SCALE), 1.0f / DM);
;                     const f32x4 g = acc[ai][0][m][n] * rs, up = acc[ai][1][m][n] * rs;
;                     f32x4 a;
; #pragma unroll
;                     for (int j = 0; j < 4; ++j) { const float s1 = __shfl(fr == 15 ? pg[j] : g[j], src1), s2 = __shfl(fr >= 14 ? pg[j] : g[j], src2);
;                         a[j] = silu_f(cbv[j] + w0[j] * s2 + w1[j] * s1 + w2[j] * g[j]) * up[j]; }
;                     u32x2 gw; gw.x = pk2(g[0], g[1]); gw.y = pk2(g[2], g[3]);
;                     if (m == 0 && fr < 2) {
;                         *boff((u32x2*)GS, (unsigned)(((row >> 6) * 4 + 2 + fr) * DFF + c4) * 2u) = gw;
;                         u32x2 uw; uw.x = pk2(up[0], up[1]); uw.y = pk2(up[2], up[3]); *boff((u32x2*)US, (unsigned)(((row >> 6) * 2 + fr) * DFF + c4) * 2u) = uw;
;                     } else { u32x2 w; w.x = pk2(a[0], a[1]); w.y = pk2(a[2], a[3]); *boff((u32x2*)A2, (unsigned)(row * DFF + c4) * 2u) = w; }
;                     if (m == 3 && fr >= 14) {
;                         *boff((u32x2*)GS, (unsigned)(((row >> 6) * 4 + (fr - 14)) * DFF + c4) * 2u) = gw;
;                         if ((row & (SEQ - 1)) >= SEQ - 2) *boff((f32x4*)fcp, (unsigned)(((row >> 11) * 2 + ((row & (SEQ - 1)) - (SEQ - 2))) * DFF + c4) * 4u) = g;
;                     }
;                     pg = g;
;                     asm volatile("" ::: "memory");
	v_pk_fma_f32 v[130:131], v[130:131], v[198:199], v[142:143]
	v_cndmask_b32_e64 v151, v149, v197, s[36:37]
	v_pk_fma_f32 v[130:131], v[134:135], v[152:153], v[130:131]
	ds_bpermute_b32 v201, v213, v151
	v_pk_fma_f32 v[130:131], v[138:139], v[146:147], v[130:131]
	v_cndmask_b32_e64 v151, v149, v197, s[38:39]
	v_mul_f32_e32 v134, 0xbfb8aa3b, v130
	v_mul_f32_e32 v135, 0xbfb8aa3b, v131
	v_exp_f32_e32 v134, v134
	v_exp_f32_e32 v135, v135
	ds_bpermute_b32 v197, v214, v151
	v_pk_mul_f32 v[202:203], v[6:7], v[150:151] op_sel_hi:[1,0]
	v_add_f32_e32 v134, 1.0, v134
	v_add_f32_e32 v135, 1.0, v135
	v_rcp_f32_e32 v134, v134
	v_rcp_f32_e32 v135, v135
	s_waitcnt lgkmcnt(0)
	v_pk_fma_f32 v[132:133], v[132:133], v[196:197], v[144:145]
	v_pk_mul_f32 v[150:151], v[4:5], v[150:151] op_sel_hi:[1,0]
	v_pk_fma_f32 v[132:133], v[136:137], v[200:201], v[132:133]
	v_pk_mul_f32 v[130:131], v[130:131], v[134:135]
	v_pk_fma_f32 v[132:133], v[140:141], v[148:149], v[132:133]
	v_pk_mul_f32 v[130:131], v[150:151], v[130:131]
	v_mul_f32_e32 v134, 0xbfb8aa3b, v132
	v_mul_f32_e32 v135, 0xbfb8aa3b, v133
	v_exp_f32_e32 v134, v134
	v_exp_f32_e32 v135, v135
	v_cvt_pk_bf16_f32 v130, v130, v131
	v_add_f32_e32 v134, 1.0, v134
	v_add_f32_e32 v135, 1.0, v135
	v_rcp_f32_e32 v134, v134
	v_rcp_f32_e32 v135, v135
	s_nop 0
	v_pk_mul_f32 v[132:133], v[132:133], v[134:135]
	s_nop 0
	v_pk_mul_f32 v[132:133], v[202:203], v[132:133]
	s_nop 0
	v_cvt_pk_bf16_f32 v131, v132, v133
	v_add_lshl_u32 v132, v234, v176, 1
	global_store_dwordx2 v132, v[130:131], s[46:47]
	s_and_saveexec_b64 s[0:1], s[38:39]
	s_cbranch_execz .LBB0_3107
	s_movk_i32 s2, 0x7fd
	v_add_lshl_u32 v132, v221, v176, 1
	v_cvt_pk_bf16_f32 v130, v146, v147
	v_cvt_pk_bf16_f32 v131, v148, v149
	v_cmp_lt_u32_e32 vcc, s2, v235
	global_store_dwordx2 v132, v[130:131], s[50:51]
	s_and_b64 exec, exec, vcc
	s_cbranch_execz .LBB0_3107
	v_add_u32_e32 v130, s15, v235
	v_mul_lo_u32 v130, v130, s90
	v_add_lshl_u32 v130, v130, v176, 2
	global_store_dwordx4 v130, v[146:149], s[58:59]
.LBB0_3107:
	s_or_b64 exec, exec, s[0:1]
	v_or_b32_e32 v196, 4, v176
	v_ashrrev_i32_e32 v197, 31, v196
	v_lshlrev_b64 v[134:135], 2, v[196:197]
	v_lshl_add_u64 v[146:147], s[48:49], 0, v[96:97]
	v_lshl_add_u64 v[136:137], s[62:63], 0, v[134:135]
	v_lshl_add_u64 v[134:135], s[64:65], 0, v[134:135]
	global_load_dwordx4 v[130:133], v[178:179], off offset:16
	global_load_dwordx4 v[138:141], v[136:137], off
	s_nop 0
	global_load_dwordx4 v[134:137], v[134:135], off
	s_nop 0
	global_load_dwordx4 v[142:145], v[180:181], off offset:16
	s_nop 0
	s_waitcnt vmcnt(0)
	v_mov_b32_e32 v96, v236
	v_pk_mul_f32 v[148:149], v[122:123], v[96:97] op_sel_hi:[1,0]
	v_pk_mul_f32 v[146:147], v[124:125], v[96:97] op_sel_hi:[1,0]
	v_pk_mul_f32 v[178:179], v[116:117], v[96:97] op_sel_hi:[1,0]
	v_pk_mul_f32 v[180:181], v[114:115], v[96:97] op_sel_hi:[1,0]
	v_cndmask_b32_e64 v96, v148, 0, s[36:37]
	ds_bpermute_b32 v200, v213, v96
	v_cndmask_b32_e64 v96, v148, 0, s[38:39]
	ds_bpermute_b32 v204, v214, v96
	v_cndmask_b32_e64 v96, v149, 0, s[36:37]
	ds_bpermute_b32 v201, v213, v96
	v_cndmask_b32_e64 v96, v149, 0, s[38:39]
	ds_bpermute_b32 v205, v214, v96
	v_cndmask_b32_e64 v96, v146, 0, s[36:37]
	ds_bpermute_b32 v198, v213, v96
	v_cndmask_b32_e64 v96, v146, 0, s[38:39]
	ds_bpermute_b32 v202, v214, v96
	v_cndmask_b32_e64 v96, v147, 0, s[36:37]
	ds_bpermute_b32 v199, v213, v96
	v_cndmask_b32_e64 v96, v147, 0, s[38:39]
	ds_bpermute_b32 v203, v214, v96
	s_and_saveexec_b64 s[0:1], s[40:41]
	s_xor_b64 s[0:1], exec, s[0:1]
	s_cbranch_execz .LBB0_3109
	s_waitcnt lgkmcnt(4)
	v_pk_fma_f32 v[150:151], v[130:131], v[204:205], v[142:143]
	s_nop 0
	v_pk_fma_f32 v[150:151], v[138:139], v[200:201], v[150:151]
	s_waitcnt lgkmcnt(0)
	v_pk_fma_f32 v[200:201], v[132:133], v[202:203], v[144:145]
	v_pk_fma_f32 v[150:151], v[134:135], v[148:149], v[150:151]
	v_pk_fma_f32 v[198:199], v[140:141], v[198:199], v[200:201]
	v_mul_f32_e32 v96, 0xbfb8aa3b, v150
	v_exp_f32_e32 v96, v96
	v_mul_f32_e32 v152, 0xbfb8aa3b, v151
	v_exp_f32_e32 v152, v152
	v_pk_fma_f32 v[198:199], v[136:137], v[146:147], v[198:199]
	v_add_f32_e32 v96, 1.0, v96
	v_mul_f32_e32 v183, 0xbfb8aa3b, v199
	v_add_f32_e32 v153, 1.0, v152
	v_rcp_f32_e32 v152, v96
	v_mul_f32_e32 v96, 0xbfb8aa3b, v198
	v_exp_f32_e32 v96, v96
	v_exp_f32_e32 v183, v183
	v_rcp_f32_e32 v153, v153
	v_add_f32_e32 v96, 1.0, v96
	v_rcp_f32_e32 v200, v96
	v_add_f32_e32 v96, 1.0, v183
	v_rcp_f32_e32 v201, v96
	v_pk_mul_f32 v[150:151], v[150:151], v[152:153]
	v_add_lshl_u32 v96, v218, v196, 1
	v_pk_mul_f32 v[150:151], v[180:181], v[150:151]
	v_pk_mul_f32 v[152:153], v[198:199], v[200:201]
	v_cvt_pk_bf16_f32 v150, v150, v151
	v_pk_mul_f32 v[152:153], v[178:179], v[152:153]
	s_nop 0
	v_cvt_pk_bf16_f32 v151, v152, v153
	global_store_dwordx2 v96, v[150:151], s[46:47]

; DI unsigned pk2(float lo, float hi) { f32x2 v = {lo, hi}; bf16x2_t b = __builtin_convertvector(v, bf16x2_t); return __builtin_bit_cast(unsigned, b); }
; DI float silu_f(float x) { return x * __builtin_amdgcn_rcpf(1.f + __builtin_amdgcn_exp2f(-LOG2E * x)); }
; DI float rstd_of(float ssq, float inv_n) { return 1.0f / sqrtf(ssq * inv_n + EPS); }
; DI float acc_get_i(const acc_t* base, unsigned idx, float inv_scale) { return (float)(*(const acc_t*)((const char*)base + idx * 8u)) * inv_scale; }
; template <class T> DI T* boff(T* base, unsigned byte_off) { return (T*)((char*)base + byte_off); }
;     DI void operator()(const f32x4 (&acc)[2][2][4][2], const Unit& u, int wr, int wc, int fr, int fq) const {
;     ...
;                 for (int m = 0; m < 4; ++m) { const int row = u.pm * BM + ai * HALF + wr * 64 + m * 16 + fr;
;                     const float rs = rstd_of(acc_get_i(ssq, (unsigned)row, 1.0f / SSQ_SCALE), 1.0f / DM);
;                     const f32x4 g = acc[ai][0][m][n] * rs, up = acc[ai][1][m][n] * rs;
;                     f32x4 a;
; #pragma unroll
;                     for (int j = 0; j < 4; ++j) { const float s1 = __shfl(fr == 15 ? pg[j] : g[j], src1), s2 = __shfl(fr >= 14 ? pg[j] : g[j], src2);
;                         a[j] = silu_f(cbv[j] + w0[j] * s2 + w1[j] * s1 + w2[j] * g[j]) * up[j]; }
;                     u32x2 gw; gw.x = pk2(g[0], g[1]); gw.y = pk2(g[2], g[3]);
;                     if (m == 0 && fr < 2) {
;                         *boff((u32x2*)GS, (unsigned)(((row >> 6) * 4 + 2 + fr) * DFF + c4) * 2u) = gw;
;                         u32x2 uw; uw.x = pk2(up[0], up[1]); uw.y = pk2(up[2], up[3]); *boff((u32x2*)US, (unsigned)(((row >> 6) * 2 + fr) * DFF + c4) * 2u) = uw;
;                     } else { u32x2 w; w.x = pk2(a[0], a[1]); w.y = pk2(a[2], a[3]); *boff((u32x2*)A2, (unsigned)(row * DFF + c4) * 2u) = w; }
;                     if (m == 3 && fr >= 14) {
;                         *boff((u32x2*)GS, (unsigned)(((row >> 6) * 4 + (fr - 14)) * DFF + c4) * 2u) = gw;
;                         if ((row & (SEQ - 1)) >= SEQ - 2) *boff((f32x4*)fcp, (unsigned)(((row >> 11) * 2 + ((row & (SEQ - 1)) - (SEQ - 2))) * DFF + c4) * 4u) = g;
;                     }
;                     pg = g;
;                     asm volatile("" ::: "memory");
.LBB0_3111:
	s_or_b64 exec, exec, s[0:1]
	v_mov_b32_e32 v183, v97
	v_lshl_add_u64 v[150:151], s[48:49], 0, v[182:183]
	v_add_lshl_u32 v187, v187, v196, 1
	v_mov_b32_e32 v185, v97
	v_lshl_add_u64 v[184:185], s[48:49], 0, v[184:185]
	v_mov_b32_e32 v150, v237
	v_pk_mul_f32 v[152:153], v[108:109], v[150:151] op_sel_hi:[1,0]
	v_pk_mul_f32 v[178:179], v[106:107], v[150:151] op_sel_hi:[1,0]
	v_cndmask_b32_e64 v181, v152, v146, s[38:39]
	v_cndmask_b32_e64 v151, v178, v148, s[36:37]
	v_cndmask_b32_e64 v148, v178, v148, s[38:39]
	v_cndmask_b32_e64 v180, v179, v149, s[36:37]
	v_cndmask_b32_e64 v149, v179, v149, s[38:39]
	v_cndmask_b32_e64 v193, v153, v147, s[38:39]
	v_cndmask_b32_e64 v182, v152, v146, s[36:37]
	v_cndmask_b32_e64 v183, v153, v147, s[36:37]
	ds_bpermute_b32 v148, v214, v148
	ds_bpermute_b32 v147, v213, v180
	ds_bpermute_b32 v149, v214, v149
	ds_bpermute_b32 v180, v214, v181
	ds_bpermute_b32 v181, v214, v193
	ds_bpermute_b32 v146, v213, v151
	ds_bpermute_b32 v182, v213, v182
	ds_bpermute_b32 v183, v213, v183
	s_waitcnt lgkmcnt(5)
	v_pk_fma_f32 v[148:149], v[130:131], v[148:149], v[142:143]
	s_waitcnt lgkmcnt(3)
	v_pk_fma_f32 v[180:181], v[132:133], v[180:181], v[144:145]
	s_waitcnt lgkmcnt(2)
	v_pk_fma_f32 v[146:147], v[138:139], v[146:147], v[148:149]
	s_waitcnt lgkmcnt(0)
	v_pk_fma_f32 v[148:149], v[140:141], v[182:183], v[180:181]
	v_pk_fma_f32 v[146:147], v[134:135], v[178:179], v[146:147]
	v_pk_fma_f32 v[148:149], v[136:137], v[152:153], v[148:149]
	v_mul_f32_e32 v151, 0xbfb8aa3b, v146
	v_mul_f32_e32 v180, 0xbfb8aa3b, v147
	v_mul_f32_e32 v181, 0xbfb8aa3b, v148
	v_mul_f32_e32 v182, 0xbfb8aa3b, v149
	v_exp_f32_e32 v151, v151
	v_exp_f32_e32 v180, v180
	v_exp_f32_e32 v181, v181
	v_exp_f32_e32 v182, v182
	v_add_f32_e32 v151, 1.0, v151
	v_add_f32_e32 v183, 1.0, v180
	v_add_f32_e32 v193, 1.0, v181
	v_add_f32_e32 v197, 1.0, v182
	v_rcp_f32_e32 v180, v151
	v_rcp_f32_e32 v181, v183
	v_rcp_f32_e32 v182, v193
	v_rcp_f32_e32 v183, v197
	v_pk_mul_f32 v[198:199], v[100:101], v[150:151] op_sel_hi:[1,0]
	v_pk_mul_f32 v[150:151], v[98:99], v[150:151] op_sel_hi:[1,0]
	v_pk_mul_f32 v[146:147], v[146:147], v[180:181]
	v_pk_mul_f32 v[148:149], v[148:149], v[182:183]
	v_pk_mul_f32 v[146:147], v[150:151], v[146:147]
	v_pk_mul_f32 v[148:149], v[198:199], v[148:149]
	v_cvt_pk_bf16_f32 v146, v146, v147
	v_cvt_pk_bf16_f32 v147, v148, v149
	global_store_dwordx2 v187, v[146:147], s[46:47]
	v_mov_b32_e32 v187, v97
	v_add_lshl_u32 v193, v220, v196, 1
	v_mov_b32_e32 v146, v238
	v_pk_mul_f32 v[150:151], v[90:91], v[146:147] op_sel_hi:[1,0]
	v_pk_mul_f32 v[180:181], v[88:89], v[146:147] op_sel_hi:[1,0]
	v_cndmask_b32_e64 v183, v150, v152, s[38:39]
	v_cndmask_b32_e64 v147, v180, v178, s[36:37]
	v_cndmask_b32_e64 v149, v180, v178, s[38:39]
	v_cndmask_b32_e64 v178, v181, v179, s[36:37]
	v_cndmask_b32_e64 v179, v181, v179, s[38:39]
	v_cndmask_b32_e64 v185, v151, v153, s[38:39]
	v_cndmask_b32_e64 v182, v150, v152, s[36:37]
	v_cndmask_b32_e64 v184, v151, v153, s[36:37]
	ds_bpermute_b32 v152, v214, v149
	ds_bpermute_b32 v149, v213, v178
	ds_bpermute_b32 v153, v214, v179
	ds_bpermute_b32 v178, v214, v183
	ds_bpermute_b32 v179, v214, v185
	ds_bpermute_b32 v148, v213, v147
	ds_bpermute_b32 v182, v213, v182
	ds_bpermute_b32 v183, v213, v184
	s_waitcnt lgkmcnt(5)
	v_pk_fma_f32 v[152:153], v[130:131], v[152:153], v[142:143]
	s_waitcnt lgkmcnt(3)
	v_pk_fma_f32 v[178:179], v[132:133], v[178:179], v[144:145]
	s_waitcnt lgkmcnt(2)
	v_pk_fma_f32 v[148:149], v[138:139], v[148:149], v[152:153]
	v_lshl_add_u64 v[184:185], s[48:49], 0, v[186:187]
	s_waitcnt lgkmcnt(0)
	v_pk_fma_f32 v[152:153], v[140:141], v[182:183], v[178:179]
	v_pk_fma_f32 v[148:149], v[134:135], v[180:181], v[148:149]
	v_pk_fma_f32 v[152:153], v[136:137], v[150:151], v[152:153]
	v_mul_f32_e32 v147, 0xbfb8aa3b, v148
	v_mul_f32_e32 v178, 0xbfb8aa3b, v149
	v_mul_f32_e32 v179, 0xbfb8aa3b, v152
	v_mul_f32_e32 v182, 0xbfb8aa3b, v153
	v_exp_f32_e32 v147, v147
	v_exp_f32_e32 v178, v178
	v_exp_f32_e32 v179, v179
	v_exp_f32_e32 v182, v182
	v_add_f32_e32 v147, 1.0, v147
	v_add_f32_e32 v183, 1.0, v178
	v_add_f32_e32 v186, 1.0, v179
	v_add_f32_e32 v187, 1.0, v182
	v_rcp_f32_e32 v178, v147
	v_rcp_f32_e32 v179, v183
	v_rcp_f32_e32 v182, v186
	v_rcp_f32_e32 v183, v187
	v_pk_mul_f32 v[186:187], v[82:83], v[146:147] op_sel_hi:[1,0]
	v_pk_mul_f32 v[146:147], v[80:81], v[146:147] op_sel_hi:[1,0]
	v_pk_mul_f32 v[148:149], v[148:149], v[178:179]
	v_pk_mul_f32 v[152:153], v[152:153], v[182:183]
	v_pk_mul_f32 v[146:147], v[146:147], v[148:149]
	v_pk_mul_f32 v[148:149], v[186:187], v[152:153]
	v_cvt_pk_bf16_f32 v146, v146, v147
	v_cvt_pk_bf16_f32 v147, v148, v149
	global_store_dwordx2 v193, v[146:147], s[46:47]
	v_mov_b32_e32 v152, v239
	v_pk_mul_f32 v[148:149], v[74:75], v[152:153] op_sel_hi:[1,0]
	v_pk_mul_f32 v[146:147], v[72:73], v[152:153] op_sel_hi:[1,0]
	v_cndmask_b32_e64 v184, v149, v151, s[38:39]
	v_cndmask_b32_e64 v153, v146, v180, s[36:37]
	v_cndmask_b32_e64 v178, v146, v180, s[38:39]
	v_cndmask_b32_e64 v179, v147, v181, s[36:37]
	v_cndmask_b32_e64 v180, v147, v181, s[38:39]
	v_cndmask_b32_e64 v181, v148, v150, s[38:39]
	v_cndmask_b32_e64 v182, v148, v150, s[36:37]
	v_cndmask_b32_e64 v183, v149, v151, s[36:37]
	ds_bpermute_b32 v178, v214, v178
	ds_bpermute_b32 v151, v213, v179
	ds_bpermute_b32 v179, v214, v180
	ds_bpermute_b32 v180, v214, v181
	ds_bpermute_b32 v181, v214, v184
	ds_bpermute_b32 v150, v213, v153
	ds_bpermute_b32 v182, v213, v182
	ds_bpermute_b32 v183, v213, v183
	s_waitcnt lgkmcnt(5)
	v_pk_fma_f32 v[178:179], v[130:131], v[178:179], v[142:143]
	s_waitcnt lgkmcnt(3)
	v_pk_fma_f32 v[180:181], v[132:133], v[180:181], v[144:145]
	s_waitcnt lgkmcnt(2)
	v_pk_fma_f32 v[150:151], v[138:139], v[150:151], v[178:179]
	s_waitcnt lgkmcnt(0)
	v_pk_fma_f32 v[178:179], v[140:141], v[182:183], v[180:181]
	v_pk_fma_f32 v[150:151], v[134:135], v[146:147], v[150:151]
	v_pk_fma_f32 v[178:179], v[136:137], v[148:149], v[178:179]
	v_mul_f32_e32 v153, 0xbfb8aa3b, v150
	v_mul_f32_e32 v180, 0xbfb8aa3b, v151
	v_mul_f32_e32 v181, 0xbfb8aa3b, v178
	v_mul_f32_e32 v182, 0xbfb8aa3b, v179
	v_exp_f32_e32 v153, v153
	v_exp_f32_e32 v180, v180
	v_exp_f32_e32 v181, v181
	v_exp_f32_e32 v182, v182
	v_add_f32_e32 v153, 1.0, v153
	v_add_f32_e32 v183, 1.0, v180
	v_add_f32_e32 v184, 1.0, v181
	v_add_f32_e32 v185, 1.0, v182
	v_rcp_f32_e32 v180, v153
	v_rcp_f32_e32 v181, v183
	v_rcp_f32_e32 v182, v184
	v_rcp_f32_e32 v183, v185
	v_pk_mul_f32 v[184:185], v[66:67], v[152:153] op_sel_hi:[1,0]
	v_pk_mul_f32 v[152:153], v[64:65], v[152:153] op_sel_hi:[1,0]
	v_pk_mul_f32 v[150:151], v[150:151], v[180:181]
	v_pk_mul_f32 v[178:179], v[178:179], v[182:183]
	v_pk_mul_f32 v[150:151], v[152:153], v[150:151]
	v_pk_mul_f32 v[152:153], v[184:185], v[178:179]
	v_cvt_pk_bf16_f32 v150, v150, v151
	v_cvt_pk_bf16_f32 v151, v152, v153
	v_add_lshl_u32 v152, v230, v196, 1
	global_store_dwordx2 v152, v[150:151], s[46:47]
	s_and_saveexec_b64 s[0:1], s[38:39]
	s_cbranch_execz .LBB0_3114
; DI unsigned pk2(float lo, float hi) { f32x2 v = {lo, hi}; bf16x2_t b = __builtin_convertvector(v, bf16x2_t); return __builtin_bit_cast(unsigned, b); }
; DI float silu_f(float x) { return x * __builtin_amdgcn_rcpf(1.f + __builtin_amdgcn_exp2f(-LOG2E * x)); }
; DI float rstd_of(float ssq, float inv_n) { return 1.0f / sqrtf(ssq * inv_n + EPS); }
; DI float acc_get_i(const acc_t* base, unsigned idx, float inv_scale) { return (float)(*(const acc_t*)((const char*)base + idx * 8u)) * inv_scale; }
; template <class T> DI T* boff(T* base, unsigned byte_off) { return (T*)((char*)base + byte_off); }
;     DI void operator()(const f32x4 (&acc)[2][2][4][2], const Unit& u, int wr, int wc, int fr, int fq) const {
;     ...
;                 for (int m = 0; m < 4; ++m) { const int row = u.pm * BM + ai * HALF + wr * 64 + m * 16 + fr;
;                     const float rs = rstd_of(acc_get_i(ssq, (unsigned)row, 1.0f / SSQ_SCALE), 1.0f / DM);
;                     const f32x4 g = acc[ai][0][m][n] * rs, up = acc[ai][1][m][n] * rs;
;                     f32x4 a;
; #pragma unroll
;                     for (int j = 0; j < 4; ++j) { const float s1 = __shfl(fr == 15 ? pg[j] : g[j], src1), s2 = __shfl(fr >= 14 ? pg[j] : g[j], src2);
;                         a[j] = silu_f(cbv[j] + w0[j] * s2 + w1[j] * s1 + w2[j] * g[j]) * up[j]; }
;                     u32x2 gw; gw.x = pk2(g[0], g[1]); gw.y = pk2(g[2], g[3]);
;                     if (m == 0 && fr < 2) {
;                         *boff((u32x2*)GS, (unsigned)(((row >> 6) * 4 + 2 + fr) * DFF + c4) * 2u) = gw;
;                         u32x2 uw; uw.x = pk2(up[0], up[1]); uw.y = pk2(up[2], up[3]); *boff((u32x2*)US, (unsigned)(((row >> 6) * 2 + fr) * DFF + c4) * 2u) = uw;
;                     } else { u32x2 w; w.x = pk2(a[0], a[1]); w.y = pk2(a[2], a[3]); *boff((u32x2*)A2, (unsigned)(row * DFF + c4) * 2u) = w; }
;                     if (m == 3 && fr >= 14) {
;                         *boff((u32x2*)GS, (unsigned)(((row >> 6) * 4 + (fr - 14)) * DFF + c4) * 2u) = gw;
;                         if ((row & (SEQ - 1)) >= SEQ - 2) *boff((f32x4*)fcp, (unsigned)(((row >> 11) * 2 + ((row & (SEQ - 1)) - (SEQ - 2))) * DFF + c4) * 4u) = g;
;                     }
;                     pg = g;
;                     asm volatile("" ::: "memory");
	s_movk_i32 s2, 0x7fd
	v_add_lshl_u32 v152, v217, v196, 1
	v_cvt_pk_bf16_f32 v150, v146, v147
	v_cvt_pk_bf16_f32 v151, v148, v149
	v_cmp_lt_u32_e32 vcc, s2, v189
	global_store_dwordx2 v152, v[150:151], s[50:51]
	s_and_b64 exec, exec, vcc
	s_cbranch_execz .LBB0_3114
	v_add_u32_e32 v150, s14, v189
	v_mul_lo_u32 v150, v150, s90
	v_add_lshl_u32 v150, v150, v196, 2
	global_store_dwordx4 v150, v[146:149], s[58:59]
.LBB0_3114:
	s_or_b64 exec, exec, s[0:1]
	v_mov_b32_e32 v189, v97
	v_lshl_add_u64 v[146:147], s[48:49], 0, v[188:189]
	v_mov_b32_e32 v150, v240
	v_pk_mul_f32 v[148:149], v[56:57], v[150:151] op_sel_hi:[1,0]
	v_pk_mul_f32 v[146:147], v[58:59], v[150:151] op_sel_hi:[1,0]
	v_pk_mul_f32 v[178:179], v[50:51], v[150:151] op_sel_hi:[1,0]
	v_pk_mul_f32 v[180:181], v[48:49], v[150:151] op_sel_hi:[1,0]
	v_cndmask_b32_e64 v150, v148, 0, s[36:37]
	ds_bpermute_b32 v182, v213, v150
	v_cndmask_b32_e64 v150, v148, 0, s[38:39]
	ds_bpermute_b32 v186, v214, v150
	v_cndmask_b32_e64 v150, v149, 0, s[36:37]
	ds_bpermute_b32 v183, v213, v150
	v_cndmask_b32_e64 v150, v149, 0, s[38:39]
	ds_bpermute_b32 v187, v214, v150
	v_cndmask_b32_e64 v150, v146, 0, s[36:37]
	ds_bpermute_b32 v184, v213, v150
	v_cndmask_b32_e64 v150, v146, 0, s[38:39]
	ds_bpermute_b32 v188, v214, v150
	v_cndmask_b32_e64 v150, v147, 0, s[36:37]
	ds_bpermute_b32 v185, v213, v150
	v_cndmask_b32_e64 v150, v147, 0, s[38:39]
	ds_bpermute_b32 v189, v214, v150
	s_and_saveexec_b64 s[0:1], s[40:41]
	s_xor_b64 s[0:1], exec, s[0:1]
	s_cbranch_execz .LBB0_3116
	s_waitcnt lgkmcnt(4)
	v_pk_fma_f32 v[150:151], v[130:131], v[186:187], v[142:143]
	s_nop 0
	v_pk_fma_f32 v[150:151], v[138:139], v[182:183], v[150:151]
	s_waitcnt lgkmcnt(0)
	v_pk_fma_f32 v[182:183], v[132:133], v[188:189], v[144:145]
	v_pk_fma_f32 v[150:151], v[134:135], v[148:149], v[150:151]
	v_pk_fma_f32 v[182:183], v[140:141], v[184:185], v[182:183]
	v_mul_f32_e32 v96, 0xbfb8aa3b, v150
	v_exp_f32_e32 v96, v96
	v_mul_f32_e32 v152, 0xbfb8aa3b, v151
	v_exp_f32_e32 v152, v152
	v_pk_fma_f32 v[182:183], v[136:137], v[146:147], v[182:183]
	v_add_f32_e32 v96, 1.0, v96
	v_mul_f32_e32 v184, 0xbfb8aa3b, v183
	v_add_f32_e32 v153, 1.0, v152
	v_rcp_f32_e32 v152, v96
	v_mul_f32_e32 v96, 0xbfb8aa3b, v182
	v_exp_f32_e32 v96, v96
	v_exp_f32_e32 v185, v184
	v_rcp_f32_e32 v153, v153
	v_add_f32_e32 v96, 1.0, v96
	v_rcp_f32_e32 v184, v96
	v_add_f32_e32 v96, 1.0, v185
	v_rcp_f32_e32 v185, v96
	v_pk_mul_f32 v[150:151], v[150:151], v[152:153]
	v_add_lshl_u32 v96, v231, v196, 1
	v_pk_mul_f32 v[150:151], v[180:181], v[150:151]
	v_pk_mul_f32 v[152:153], v[182:183], v[184:185]
	v_cvt_pk_bf16_f32 v150, v150, v151
	v_pk_mul_f32 v[152:153], v[178:179], v[152:153]
	s_nop 0
	v_cvt_pk_bf16_f32 v151, v152, v153
	global_store_dwordx2 v96, v[150:151], s[46:47]

; DI unsigned pk2(float lo, float hi) { f32x2 v = {lo, hi}; bf16x2_t b = __builtin_convertvector(v, bf16x2_t); return __builtin_bit_cast(unsigned, b); }
; DI float silu_f(float x) { return x * __builtin_amdgcn_rcpf(1.f + __builtin_amdgcn_exp2f(-LOG2E * x)); }
; DI float rstd_of(float ssq, float inv_n) { return 1.0f / sqrtf(ssq * inv_n + EPS); }
; DI float acc_get_i(const acc_t* base, unsigned idx, float inv_scale) { return (float)(*(const acc_t*)((const char*)base + idx * 8u)) * inv_scale; }
; template <class T> DI T* boff(T* base, unsigned byte_off) { return (T*)((char*)base + byte_off); }
;     DI void operator()(const f32x4 (&acc)[2][2][4][2], const Unit& u, int wr, int wc, int fr, int fq) const {
;     ...
;                 for (int m = 0; m < 4; ++m) { const int row = u.pm * BM + ai * HALF + wr * 64 + m * 16 + fr;
;                     const float rs = rstd_of(acc_get_i(ssq, (unsigned)row, 1.0f / SSQ_SCALE), 1.0f / DM);
;                     const f32x4 g = acc[ai][0][m][n] * rs, up = acc[ai][1][m][n] * rs;
;                     f32x4 a;
; #pragma unroll
;                     for (int j = 0; j < 4; ++j) { const float s1 = __shfl(fr == 15 ? pg[j] : g[j], src1), s2 = __shfl(fr >= 14 ? pg[j] : g[j], src2);
;                         a[j] = silu_f(cbv[j] + w0[j] * s2 + w1[j] * s1 + w2[j] * g[j]) * up[j]; }
;                     u32x2 gw; gw.x = pk2(g[0], g[1]); gw.y = pk2(g[2], g[3]);
;                     if (m == 0 && fr < 2) {
;                         *boff((u32x2*)GS, (unsigned)(((row >> 6) * 4 + 2 + fr) * DFF + c4) * 2u) = gw;
;                         u32x2 uw; uw.x = pk2(up[0], up[1]); uw.y = pk2(up[2], up[3]); *boff((u32x2*)US, (unsigned)(((row >> 6) * 2 + fr) * DFF + c4) * 2u) = uw;
;                     } else { u32x2 w; w.x = pk2(a[0], a[1]); w.y = pk2(a[2], a[3]); *boff((u32x2*)A2, (unsigned)(row * DFF + c4) * 2u) = w; }
;                     if (m == 3 && fr >= 14) {
;                         *boff((u32x2*)GS, (unsigned)(((row >> 6) * 4 + (fr - 14)) * DFF + c4) * 2u) = gw;
;                         if ((row & (SEQ - 1)) >= SEQ - 2) *boff((f32x4*)fcp, (unsigned)(((row >> 11) * 2 + ((row & (SEQ - 1)) - (SEQ - 2))) * DFF + c4) * 4u) = g;
;                     }
;                     pg = g;
;                     asm volatile("" ::: "memory");
.LBB0_3118:
	s_or_b64 exec, exec, s[0:1]
	v_mov_b32_e32 v191, v97
	v_lshl_add_u64 v[150:151], s[48:49], 0, v[190:191]
	s_waitcnt lgkmcnt(2)
	v_add_lshl_u32 v188, v195, v196, 1
	v_mov_b32_e32 v193, v97
	v_mov_b32_e32 v195, v97
	v_mov_b32_e32 v96, v241
	v_pk_mul_f32 v[150:151], v[42:43], v[96:97] op_sel_hi:[1,0]
	v_pk_mul_f32 v[152:153], v[40:41], v[96:97] op_sel_hi:[1,0]
	v_cndmask_b32_e64 v181, v150, v146, s[38:39]
	v_cndmask_b32_e64 v178, v152, v148, s[36:37]
	v_cndmask_b32_e64 v148, v152, v148, s[38:39]
	v_cndmask_b32_e64 v179, v153, v149, s[36:37]
	v_cndmask_b32_e64 v149, v153, v149, s[38:39]
	v_cndmask_b32_e64 v183, v151, v147, s[38:39]
	v_cndmask_b32_e64 v180, v150, v146, s[36:37]
	v_cndmask_b32_e64 v182, v151, v147, s[36:37]
	ds_bpermute_b32 v146, v213, v178
	ds_bpermute_b32 v148, v214, v148
	ds_bpermute_b32 v147, v213, v179
	ds_bpermute_b32 v149, v214, v149
	ds_bpermute_b32 v178, v214, v181
	ds_bpermute_b32 v179, v214, v183
	ds_bpermute_b32 v180, v213, v180
	ds_bpermute_b32 v181, v213, v182
	s_waitcnt lgkmcnt(4)
	v_pk_fma_f32 v[148:149], v[130:131], v[148:149], v[142:143]
	v_pk_mul_f32 v[184:185], v[34:35], v[96:97] op_sel_hi:[1,0]
	s_waitcnt lgkmcnt(2)
	v_pk_fma_f32 v[178:179], v[132:133], v[178:179], v[144:145]
	v_pk_fma_f32 v[146:147], v[138:139], v[146:147], v[148:149]
	s_waitcnt lgkmcnt(0)
	v_pk_fma_f32 v[148:149], v[140:141], v[180:181], v[178:179]
	v_pk_fma_f32 v[146:147], v[134:135], v[152:153], v[146:147]
	v_pk_fma_f32 v[148:149], v[136:137], v[150:151], v[148:149]
	v_mul_f32_e32 v178, 0xbfb8aa3b, v146
	v_mul_f32_e32 v179, 0xbfb8aa3b, v147
	v_mul_f32_e32 v180, 0xbfb8aa3b, v148
	v_mul_f32_e32 v181, 0xbfb8aa3b, v149
	v_exp_f32_e32 v178, v178
	v_exp_f32_e32 v179, v179
	v_exp_f32_e32 v180, v180
	v_exp_f32_e32 v181, v181
	v_add_f32_e32 v178, 1.0, v178
	v_add_f32_e32 v179, 1.0, v179
	v_add_f32_e32 v180, 1.0, v180
	v_add_f32_e32 v181, 1.0, v181
	v_rcp_f32_e32 v178, v178
	v_rcp_f32_e32 v179, v179
	v_rcp_f32_e32 v180, v180
	v_rcp_f32_e32 v181, v181
	v_pk_mul_f32 v[186:187], v[32:33], v[96:97] op_sel_hi:[1,0]
	v_pk_mul_f32 v[146:147], v[146:147], v[178:179]
	v_lshl_add_u64 v[182:183], s[48:49], 0, v[192:193]
	v_pk_mul_f32 v[148:149], v[148:149], v[180:181]
	v_pk_mul_f32 v[146:147], v[186:187], v[146:147]
	v_pk_mul_f32 v[148:149], v[184:185], v[148:149]
	v_cvt_pk_bf16_f32 v146, v146, v147
	v_cvt_pk_bf16_f32 v147, v148, v149
	global_store_dwordx2 v188, v[146:147], s[46:47]
	v_add_lshl_u32 v188, v233, v196, 1
	v_mov_b32_e32 v96, v242
	v_pk_mul_f32 v[178:179], v[26:27], v[96:97] op_sel_hi:[1,0]
	v_pk_mul_f32 v[180:181], v[24:25], v[96:97] op_sel_hi:[1,0]
	v_cndmask_b32_e64 v182, v179, v151, s[36:37]
	v_cndmask_b32_e64 v146, v180, v152, s[36:37]
	v_cndmask_b32_e64 v147, v180, v152, s[38:39]
	v_cndmask_b32_e64 v149, v181, v153, s[36:37]
	v_cndmask_b32_e64 v152, v181, v153, s[38:39]
	v_cndmask_b32_e64 v153, v178, v150, s[36:37]
	v_cndmask_b32_e64 v150, v178, v150, s[38:39]
	v_cndmask_b32_e64 v151, v179, v151, s[38:39]
	ds_bpermute_b32 v148, v214, v147
	ds_bpermute_b32 v147, v213, v149
	ds_bpermute_b32 v149, v214, v152
	ds_bpermute_b32 v150, v214, v150
	ds_bpermute_b32 v151, v214, v151
	ds_bpermute_b32 v146, v213, v146
	ds_bpermute_b32 v152, v213, v153
	ds_bpermute_b32 v153, v213, v182
	s_waitcnt lgkmcnt(5)
	v_pk_fma_f32 v[148:149], v[130:131], v[148:149], v[142:143]
	s_waitcnt lgkmcnt(3)
	v_pk_fma_f32 v[150:151], v[132:133], v[150:151], v[144:145]
	s_waitcnt lgkmcnt(2)
	v_pk_fma_f32 v[146:147], v[138:139], v[146:147], v[148:149]
	v_pk_mul_f32 v[184:185], v[18:19], v[96:97] op_sel_hi:[1,0]
	s_waitcnt lgkmcnt(0)
	v_pk_fma_f32 v[148:149], v[140:141], v[152:153], v[150:151]
	v_pk_fma_f32 v[146:147], v[134:135], v[180:181], v[146:147]
	v_pk_fma_f32 v[148:149], v[136:137], v[178:179], v[148:149]
	v_mul_f32_e32 v150, 0xbfb8aa3b, v146
	v_mul_f32_e32 v151, 0xbfb8aa3b, v147
	v_mul_f32_e32 v152, 0xbfb8aa3b, v148
	v_mul_f32_e32 v153, 0xbfb8aa3b, v149
	v_exp_f32_e32 v150, v150
	v_exp_f32_e32 v151, v151
	v_exp_f32_e32 v152, v152
	v_exp_f32_e32 v153, v153
	v_add_f32_e32 v150, 1.0, v150
	v_add_f32_e32 v151, 1.0, v151
	v_add_f32_e32 v152, 1.0, v152
	v_add_f32_e32 v153, 1.0, v153
	v_rcp_f32_e32 v150, v150
	v_rcp_f32_e32 v151, v151
	v_rcp_f32_e32 v152, v152
	v_rcp_f32_e32 v153, v153
	v_pk_mul_f32 v[186:187], v[16:17], v[96:97] op_sel_hi:[1,0]
	v_pk_mul_f32 v[146:147], v[146:147], v[150:151]
	v_lshl_add_u64 v[182:183], s[48:49], 0, v[194:195]
	v_pk_mul_f32 v[148:149], v[148:149], v[152:153]
	v_pk_mul_f32 v[146:147], v[186:187], v[146:147]
	v_pk_mul_f32 v[148:149], v[184:185], v[148:149]
	v_cvt_pk_bf16_f32 v146, v146, v147
	v_cvt_pk_bf16_f32 v147, v148, v149
	global_store_dwordx2 v188, v[146:147], s[46:47]
	v_mov_b32_e32 v96, v243
	v_pk_mul_f32 v[148:149], v[10:11], v[96:97] op_sel_hi:[1,0]
	v_pk_mul_f32 v[146:147], v[8:9], v[96:97] op_sel_hi:[1,0]
	v_cndmask_b32_e64 v182, v149, v179, s[36:37]
	v_cndmask_b32_e64 v150, v146, v180, s[36:37]
	v_cndmask_b32_e64 v151, v146, v180, s[38:39]
	v_cndmask_b32_e64 v153, v147, v181, s[36:37]
	v_cndmask_b32_e64 v180, v147, v181, s[38:39]
	v_cndmask_b32_e64 v181, v148, v178, s[36:37]
	v_cndmask_b32_e64 v178, v148, v178, s[38:39]
	v_cndmask_b32_e64 v179, v149, v179, s[38:39]
	ds_bpermute_b32 v152, v214, v151
	ds_bpermute_b32 v151, v213, v153
	ds_bpermute_b32 v153, v214, v180
	ds_bpermute_b32 v178, v214, v178
	ds_bpermute_b32 v179, v214, v179
	ds_bpermute_b32 v150, v213, v150
	ds_bpermute_b32 v180, v213, v181
	ds_bpermute_b32 v181, v213, v182
	s_waitcnt lgkmcnt(5)
	v_pk_fma_f32 v[130:131], v[130:131], v[152:153], v[142:143]
	s_waitcnt lgkmcnt(3)
	v_pk_fma_f32 v[132:133], v[132:133], v[178:179], v[144:145]
	s_waitcnt lgkmcnt(2)
	v_pk_fma_f32 v[130:131], v[138:139], v[150:151], v[130:131]
	v_pk_mul_f32 v[138:139], v[2:3], v[96:97] op_sel_hi:[1,0]
	s_waitcnt lgkmcnt(0)
	v_pk_fma_f32 v[132:133], v[140:141], v[180:181], v[132:133]
	v_pk_fma_f32 v[130:131], v[134:135], v[146:147], v[130:131]
	v_pk_fma_f32 v[132:133], v[136:137], v[148:149], v[132:133]
	v_mul_f32_e32 v134, 0xbfb8aa3b, v130
	v_mul_f32_e32 v135, 0xbfb8aa3b, v131
	v_mul_f32_e32 v136, 0xbfb8aa3b, v132
	v_mul_f32_e32 v137, 0xbfb8aa3b, v133
	v_exp_f32_e32 v134, v134
	v_exp_f32_e32 v135, v135
	v_exp_f32_e32 v136, v136
	v_exp_f32_e32 v137, v137
	v_add_f32_e32 v134, 1.0, v134
	v_add_f32_e32 v135, 1.0, v135
	v_add_f32_e32 v136, 1.0, v136
	v_add_f32_e32 v137, 1.0, v137
	v_rcp_f32_e32 v134, v134
	v_rcp_f32_e32 v135, v135
	v_rcp_f32_e32 v136, v136
	v_rcp_f32_e32 v137, v137
	v_pk_mul_f32 v[140:141], v[0:1], v[96:97] op_sel_hi:[1,0]
	v_pk_mul_f32 v[130:131], v[130:131], v[134:135]
	v_add_lshl_u32 v96, v234, v196, 1
	v_pk_mul_f32 v[132:133], v[132:133], v[136:137]
	v_pk_mul_f32 v[130:131], v[140:141], v[130:131]
	v_pk_mul_f32 v[132:133], v[138:139], v[132:133]
	v_cvt_pk_bf16_f32 v130, v130, v131
	v_cvt_pk_bf16_f32 v131, v132, v133
	global_store_dwordx2 v96, v[130:131], s[46:47]
	s_and_saveexec_b64 s[0:1], s[38:39]
	s_cbranch_execz .LBB0_3121
; template <class T> DI T* boff(T* base, unsigned byte_off) { return (T*)((char*)base + byte_off); }
;     DI void operator()(const f32x4 (&acc)[2][2][4][2], const Unit& u, int wr, int wc, int fr, int fq) const {
;     ...
;                     if (m == 3 && fr >= 14) {
;                         *boff((u32x2*)GS, (unsigned)(((row >> 6) * 4 + (fr - 14)) * DFF + c4) * 2u) = gw;
;                         if ((row & (SEQ - 1)) >= SEQ - 2) *boff((f32x4*)fcp, (unsigned)(((row >> 11) * 2 + ((row & (SEQ - 1)) - (SEQ - 2))) * DFF + c4) * 4u) = g;
;                     }
	s_movk_i32 s2, 0x7fd
	v_add_lshl_u32 v96, v221, v196, 1
	v_cvt_pk_bf16_f32 v130, v146, v147
	v_cvt_pk_bf16_f32 v131, v148, v149
	v_cmp_lt_u32_e32 vcc, s2, v235
	global_store_dwordx2 v96, v[130:131], s[50:51]
	s_and_b64 exec, exec, vcc
	s_cbranch_execz .LBB0_3121
	v_add_u32_e32 v96, s15, v235
	v_mul_lo_u32 v96, v96, s90
	v_add_lshl_u32 v96, v96, v196, 2
	global_store_dwordx4 v96, v[146:149], s[58:59]
